# convert_weights loops: gain loads without serial waits (multiply deferred to next iteration), vmcnt(2) keeps previous stores in flight, flat->global
# speedup vs baseline: 1.0140x; 1.0126x over previous
.LBB0_18:
	s_andn2_b64 vcc, exec, s[2:3]
	s_cbranch_vccnz .LBB0_219
	v_writelane_b32 v255, s96, 44
	s_mov_b32 s0, s70
	v_readlane_b32 s36, v255, 27
	v_readlane_b32 s42, v255, 33
	v_readlane_b32 s43, v255, 34
	s_mov_b64 s[20:21], s[74:75]
	s_mov_b64 s[2:3], s[42:43]
	v_readlane_b32 s40, v255, 31
	v_readlane_b32 s41, v255, 32
	s_add_u32 s24, s2, 0x1600000
	s_addc_u32 s25, s3, 0
	s_mov_b64 s[8:9], s[40:41]
	s_add_u32 s26, s8, 0x1000
	s_addc_u32 s27, s9, 0
	s_abs_i32 s61, s0
	v_cvt_f32_u32_e32 v0, s61
	s_sub_i32 s6, 0, s61
	v_readlane_b32 s2, v255, 43
	s_add_i32 s62, s0, s2
	v_rcp_iflag_f32_e32 v0, v0
	s_abs_i32 s3, s62
	s_ashr_i32 s2, s62, 31
	v_mov_b32_e32 v24, v191
	v_mul_f32_e32 v0, 0x4f7ffffe, v0
	v_cvt_u32_f32_e32 v0, v0
	v_mov_b32_e32 v15, 0
	v_lshlrev_b32_e32 v20, 2, v24
	v_readfirstlane_b32 s63, v0
	s_mul_i32 s6, s6, s63
	s_mul_hi_u32 s6, s63, s6
	s_add_i32 s63, s63, s6
	s_mul_hi_u32 s6, s3, s63
	s_mul_i32 s6, s6, s61
	s_sub_i32 s3, s3, s6
	s_sub_i32 s6, s3, s61
	s_cmp_ge_u32 s3, s61
	s_cselect_b32 s3, s6, s3
	s_sub_i32 s6, s3, s61
	s_cmp_ge_u32 s3, s61
	s_cselect_b32 s3, s6, s3
	s_xor_b32 s3, s3, s2
	s_sub_i32 s34, s3, s2
	s_cmpk_gt_i32 s34, 0x57f
	v_ashrrev_i32_e32 v18, 4, v24
	v_and_b32_e32 v19, 28, v20
	v_mov_b32_e32 v14, v15
	v_mov_b32_e32 v13, v15
	v_mov_b32_e32 v12, v15
	v_mov_b32_e32 v11, v15
	v_mov_b32_e32 v10, v15
	v_mov_b32_e32 v9, v15
	v_mov_b32_e32 v8, v15
	v_mov_b32_e32 v7, v15
	v_mov_b32_e32 v6, v15
	v_mov_b32_e32 v5, v15
	v_mov_b32_e32 v4, v15
	v_mov_b32_e32 v3, v15
	v_mov_b32_e32 v2, v15
	v_mov_b32_e32 v1, v15
	v_mov_b32_e32 v0, v15
	s_mov_b32 s96, 0x7f800000
	v_readlane_b32 s37, v255, 28
	v_readlane_b32 s38, v255, 29
	v_readlane_b32 s39, v255, 30
	v_readlane_b32 s44, v255, 35
	v_readlane_b32 s45, v255, 36
	v_readlane_b32 s46, v255, 37
	v_readlane_b32 s47, v255, 38
	v_readlane_b32 s48, v255, 39
	v_readlane_b32 s49, v255, 40
	v_readlane_b32 s50, v255, 41
	v_readlane_b32 s51, v255, 42
	s_cbranch_scc1 .LBB0_28
	s_ashr_i32 s2, s34, 31
	s_lshr_b32 s2, s2, 28
	s_add_i32 s2, s34, s2
	s_and_b32 s3, s2, 0x3fffff0
	s_lshl_b32 s2, s2, 2
	s_andn2_b32 s2, s2, 63
	v_and_or_b32 v0, v20, 32, s2
	v_ashrrev_i32_e32 v0, 1, v0
	s_movk_i32 s2, 0xaf0
	v_or_b32_e32 v1, v0, v19
	v_add3_u32 v0, v19, v0, s2
	v_cmp_gt_u32_e32 vcc, 16, v19
	s_sub_i32 s3, s34, s3
	v_lshl_add_u32 v12, s3, 6, v18
	v_cndmask_b32_e32 v0, v0, v1, vcc
	v_ashrrev_i32_e32 v1, 31, v0
	v_lshl_add_u64 v[14:15], v[0:1], 2, s[24:25]
	v_mad_i64_i32 v[0:1], s[2:3], v12, s85, v[14:15]
	global_load_dwordx4 v[0:3], v[0:1], off
	s_cmp_lg_u64 s[8:9], 0
	s_cselect_b64 s[2:3], -1, 0
	s_cmp_eq_u64 s[8:9], 0
	v_ashrrev_i32_e32 v13, 31, v12
	s_cbranch_scc1 .LBB0_22
	v_lshl_add_u64 v[4:5], v[12:13], 2, s[26:27]
	global_load_dword v40, v[4:5], off
.LBB0_22:
	v_add_u32_e32 v8, 16, v12
	v_mad_i64_i32 v[4:5], s[6:7], v8, s85, v[14:15]
	global_load_dwordx4 v[4:7], v[4:5], off
	v_cndmask_b32_e64 v9, 0, 1, s[2:3]
	v_cmp_ne_u32_e64 s[6:7], 1, v9
	s_andn2_b64 vcc, exec, s[2:3]
	s_cbranch_vccnz .LBB0_24
	v_ashrrev_i32_e32 v9, 31, v8
	v_lshl_add_u64 v[8:9], v[8:9], 2, s[26:27]
	global_load_dword v42, v[8:9], off
.LBB0_24:
	v_add_u32_e32 v16, 32, v12
	v_mad_i64_i32 v[8:9], s[2:3], v16, s85, v[14:15]
	global_load_dwordx4 v[8:11], v[8:9], off
	s_and_b64 vcc, exec, s[6:7]
	s_cbranch_vccnz .LBB0_26
	v_ashrrev_i32_e32 v17, 31, v16
	v_lshl_add_u64 v[16:17], v[16:17], 2, s[26:27]
	global_load_dword v44, v[16:17], off
.LBB0_26:
	v_add_u32_e32 v16, 48, v12
	v_mad_i64_i32 v[12:13], s[2:3], v16, s85, v[14:15]
	global_load_dwordx4 v[12:15], v[12:13], off
	s_and_b64 vcc, exec, s[6:7]
	s_cbranch_vccnz .LBB0_28
	v_ashrrev_i32_e32 v17, 31, v16
	v_lshl_add_u64 v[16:17], v[16:17], 2, s[26:27]
	global_load_dword v46, v[16:17], off
.LBB0_28:
	s_add_i32 s2, s0, 0x57f
	s_sub_i32 s6, 0xfffffa81, s0
	s_ashr_i32 s3, s2, 31
	s_max_i32 s2, s2, s6
	s_mul_hi_u32 s6, s2, s63
	s_mul_i32 s7, s6, s61
	s_ashr_i32 s66, s0, 31
	s_sub_i32 s2, s2, s7
	s_xor_b32 s3, s3, s66
	s_add_i32 s7, s6, 1
	s_sub_i32 s22, s2, s61
	s_cmp_ge_u32 s2, s61
	s_cselect_b32 s6, s7, s6
	s_cselect_b32 s2, s22, s2
	s_add_i32 s7, s6, 1
	s_cmp_ge_u32 s2, s61
	s_cselect_b32 s2, s7, s6
	s_xor_b32 s2, s2, s3
	s_sub_i32 s64, s2, s3
	s_cmp_gt_i32 s64, 0
	s_cselect_b64 s[22:23], -1, 0
	s_cmp_lt_i32 s64, 1
	s_cbranch_scc1 .LBB0_45
	v_and_b32_e32 v20, 60, v20
	v_lshlrev_b32_e32 v16, 4, v24
	s_movk_i32 s2, 0x104
	v_and_b32_e32 v16, 48, v16
	v_mul_lo_u32 v17, v18, s2
	v_lshlrev_b32_e32 v23, 2, v20
	s_cmp_lg_u64 s[8:9], 0
	v_ashrrev_i32_e32 v22, 2, v24
	v_add3_u32 v23, s60, v17, v23
	v_mul_u32_u24_e32 v17, 0x104, v16
	v_and_b32_e32 v24, -4, v24
	v_cmp_gt_u32_e64 s[6:7], 16, v19
	v_add_u32_e32 v21, 0xaf0, v19
	s_cselect_b64 s[28:29], -1, 0
	v_add3_u32 v24, s60, v17, v24
	v_lshlrev_b32_e32 v144, 1, v16
	s_mov_b32 s2, s64
	s_mov_b32 s98, 0
	s_branch .LBB0_31

.LBB0_31:
	s_cmpk_lt_i32 s34, 0x580
	s_cselect_b64 s[30:31], -1, 0
	s_cmpk_gt_i32 s34, 0x57f
	s_waitcnt lgkmcnt(0)
	s_barrier
	s_cbranch_scc1 .LBB0_33
	v_add_u32_e32 v16, 0x1040, v23
	s_cmp_eq_u32 s98, 0
	s_cbranch_scc1 .Lcvw0_f
	s_waitcnt vmcnt(2)
	s_branch .Lcvw0_d

.Lcvw0_d:
	s_mov_b32 s98, 1
	v_pk_mul_f32 v[2:3], v[2:3], v[40:41] op_sel_hi:[1,0]
	v_pk_mul_f32 v[0:1], v[0:1], v[40:41] op_sel_hi:[1,0]
	v_pk_mul_f32 v[6:7], v[6:7], v[42:43] op_sel_hi:[1,0]
	v_pk_mul_f32 v[4:5], v[4:5], v[42:43] op_sel_hi:[1,0]
	v_pk_mul_f32 v[10:11], v[10:11], v[44:45] op_sel_hi:[1,0]
	v_pk_mul_f32 v[8:9], v[8:9], v[44:45] op_sel_hi:[1,0]
	v_pk_mul_f32 v[14:15], v[14:15], v[46:47] op_sel_hi:[1,0]
	v_pk_mul_f32 v[12:13], v[12:13], v[46:47] op_sel_hi:[1,0]
	ds_write2_b32 v23, v0, v1 offset1:1
	ds_write2_b32 v23, v2, v3 offset0:2 offset1:3
	ds_write2_b32 v16, v4, v5 offset1:1
	v_add_u32_e32 v16, 0x1048, v23
	ds_write2_b32 v16, v6, v7 offset1:1
	v_add_u32_e32 v16, 0x2080, v23
	ds_write2_b32 v16, v8, v9 offset1:1
	v_add_u32_e32 v16, 0x2088, v23
	ds_write2_b32 v16, v10, v11 offset1:1
	v_add_u32_e32 v16, 0x30c0, v23
	ds_write2_b32 v16, v12, v13 offset1:1
	v_add_u32_e32 v16, 0x30c8, v23
	ds_write2_b32 v16, v14, v15 offset1:1
.LBB0_33:
	s_add_i32 s3, s0, s34
	s_cmpk_gt_i32 s3, 0x57f
	s_cbranch_scc1 .LBB0_42
	s_ashr_i32 s8, s3, 31
	s_lshr_b32 s8, s8, 28
	s_add_i32 s8, s3, s8
	s_and_b32 s9, s8, 0x3fffff0
	s_lshl_b32 s8, s8, 2
	s_andn2_b32 s8, s8, 63
	s_waitcnt vmcnt(2)
	v_or_b32_e32 v0, s8, v20
	v_ashrrev_i32_e32 v0, 1, v0
	v_and_b32_e32 v0, -16, v0
	v_or_b32_e32 v1, v0, v19
	v_add_u32_e32 v0, v21, v0
	v_cndmask_b32_e64 v0, v0, v1, s[6:7]
	s_sub_i32 s9, s3, s9
	v_ashrrev_i32_e32 v1, 31, v0
	v_lshl_add_u32 v12, s9, 6, v18
	v_lshl_add_u64 v[14:15], v[0:1], 2, s[24:25]
	v_mad_i64_i32 v[0:1], s[8:9], v12, s85, v[14:15]
	global_load_dwordx4 v[0:3], v[0:1], off
	v_cndmask_b32_e64 v4, 0, 1, s[28:29]
	v_ashrrev_i32_e32 v13, 31, v12
	v_cmp_ne_u32_e64 s[8:9], 1, v4
	s_andn2_b64 vcc, exec, s[28:29]
	s_cbranch_vccnz .LBB0_36
	v_lshl_add_u64 v[4:5], v[12:13], 2, s[26:27]
	global_load_dword v40, v[4:5], off
.LBB0_36:
	v_add_u32_e32 v8, 16, v12
	v_mad_i64_i32 v[4:5], s[36:37], v8, s85, v[14:15]
	global_load_dwordx4 v[4:7], v[4:5], off
	s_and_b64 vcc, exec, s[8:9]
	s_cbranch_vccnz .LBB0_38
	v_ashrrev_i32_e32 v9, 31, v8
	v_lshl_add_u64 v[8:9], v[8:9], 2, s[26:27]
	global_load_dword v42, v[8:9], off
.LBB0_38:
	v_add_u32_e32 v16, 32, v12
	v_mad_i64_i32 v[8:9], s[36:37], v16, s85, v[14:15]
	global_load_dwordx4 v[8:11], v[8:9], off
	s_and_b64 vcc, exec, s[8:9]
	s_cbranch_vccnz .LBB0_40
	v_ashrrev_i32_e32 v17, 31, v16
	v_lshl_add_u64 v[16:17], v[16:17], 2, s[26:27]
	global_load_dword v44, v[16:17], off
.LBB0_40:
	v_add_u32_e32 v16, 48, v12
	v_mad_i64_i32 v[12:13], s[36:37], v16, s85, v[14:15]
	global_load_dwordx4 v[12:15], v[12:13], off
	s_and_b64 vcc, exec, s[8:9]
	s_cbranch_vccnz .LBB0_42
	v_ashrrev_i32_e32 v17, 31, v16
	v_lshl_add_u64 v[16:17], v[16:17], 2, s[26:27]
	global_load_dword v46, v[16:17], off
.LBB0_42:
	s_andn2_b64 vcc, exec, s[30:31]
	s_waitcnt lgkmcnt(0)
	s_barrier
	s_cbranch_vccnz .LBB0_30
	ds_read2_b32 v[16:17], v24 offset1:65
	s_waitcnt lgkmcnt(0)
	v_cvt_pk_bf16_f32 v26, v16, v17
	ds_read2_b32 v[16:17], v24 offset0:130 offset1:195
	v_add_u32_e32 v25, 0x400, v24
	s_waitcnt lgkmcnt(0)
	v_cvt_pk_bf16_f32 v27, v16, v17
	ds_read2_b32 v[16:17], v25 offset0:4 offset1:69
	s_ashr_i32 s8, s34, 31
	s_waitcnt lgkmcnt(0)
	v_cvt_pk_bf16_f32 v28, v16, v17
	ds_read2_b32 v[16:17], v25 offset0:134 offset1:199
	v_add_u32_e32 v25, 0x800, v24
	s_lshr_b32 s8, s8, 28
	s_waitcnt lgkmcnt(0)
	v_cvt_pk_bf16_f32 v29, v16, v17
	ds_read2_b32 v[16:17], v25 offset0:8 offset1:73
	s_add_i32 s8, s34, s8
	s_waitcnt lgkmcnt(0)
	v_cvt_pk_bf16_f32 v30, v16, v17
	ds_read2_b32 v[16:17], v25 offset0:138 offset1:203
	v_add_u32_e32 v25, 0xc00, v24
	s_and_b32 s9, s8, 0x3fffff0
	s_waitcnt lgkmcnt(0)
	v_cvt_pk_bf16_f32 v31, v16, v17
	ds_read2_b32 v[16:17], v25 offset0:12 offset1:77
	s_lshl_b32 s8, s8, 2
	s_waitcnt lgkmcnt(0)
	v_cvt_pk_bf16_f32 v32, v16, v17
	ds_read2_b32 v[16:17], v25 offset0:142 offset1:207
	s_andn2_b32 s8, s8, 63
	s_waitcnt lgkmcnt(0)
	v_cvt_pk_bf16_f32 v33, v16, v17
	v_add_u32_e32 v16, s8, v22
	s_sub_i32 s9, s34, s9
	v_ashrrev_i32_e32 v17, 31, v16
	v_lshlrev_b64 v[16:17], 11, v[16:17]
	s_lshl_b32 s8, s9, 6
	v_lshl_add_u64 v[16:17], s[20:21], 0, v[16:17]
	s_ashr_i32 s9, s8, 31
	v_lshl_add_u64 v[16:17], s[8:9], 1, v[16:17]
	v_lshl_add_u64 v[16:17], v[16:17], 0, v[144:145]
	global_store_dwordx4 v[16:17], v[26:29], off
	global_store_dwordx4 v[16:17], v[30:33], off offset:16
	s_branch .LBB0_30

.LBB0_45:
	v_readlane_b32 s36, v255, 27
	v_readlane_b32 s44, v255, 35
	v_readlane_b32 s45, v255, 36
	s_mov_b64 s[2:3], s[44:45]
	s_add_u32 s6, s2, 0xb00000
	s_mul_hi_u32 s2, s63, 0x580
	s_mul_i32 s2, s2, s61
	s_addc_u32 s7, s3, 0
	s_sub_i32 s2, 0x580, s2
	s_sub_i32 s3, s2, s61
	s_cmp_ge_u32 s2, s61
	s_cselect_b32 s2, s3, s2
	s_sub_i32 s3, s2, s61
	s_cmp_ge_u32 s2, s61
	s_cselect_b32 s2, s3, s2
	s_sub_i32 s2, s62, s2
	s_ashr_i32 s3, s2, 31
	s_abs_i32 s2, s2
	s_mul_hi_u32 s8, s2, s63
	s_mul_i32 s8, s8, s61
	s_sub_i32 s2, s2, s8
	s_sub_i32 s8, s2, s61
	s_cmp_ge_u32 s2, s61
	s_cselect_b32 s2, s8, s2
	s_sub_i32 s8, s2, s61
	s_cmp_ge_u32 s2, s61
	s_cselect_b32 s2, s8, s2
	v_mov_b32_e32 v20, v191
	s_xor_b32 s2, s2, s3
	s_sub_i32 s2, s2, s3
	s_waitcnt vmcnt(0) lgkmcnt(0)
	v_mov_b32_e32 v0, 0
	v_lshlrev_b32_e32 v1, 2, v20
	s_cmpk_gt_i32 s2, 0x2bf
	v_ashrrev_i32_e32 v16, 4, v20
	v_and_b32_e32 v17, 60, v1
	v_mov_b32_e32 v1, v0
	v_mov_b32_e32 v2, v0
	v_mov_b32_e32 v3, v0
	v_mov_b32_e32 v4, v0
	v_mov_b32_e32 v5, v0
	v_mov_b32_e32 v6, v0
	v_mov_b32_e32 v7, v0
	v_mov_b32_e32 v8, v0
	v_mov_b32_e32 v9, v0
	v_mov_b32_e32 v10, v0
	v_mov_b32_e32 v11, v0
	v_mov_b32_e32 v12, v0
	v_mov_b32_e32 v13, v0
	v_mov_b32_e32 v14, v0
	v_mov_b32_e32 v15, v0
	v_readlane_b32 s37, v255, 28
	v_readlane_b32 s38, v255, 29
	v_readlane_b32 s39, v255, 30
	v_readlane_b32 s40, v255, 31
	v_readlane_b32 s41, v255, 32
	v_readlane_b32 s42, v255, 33
	v_readlane_b32 s43, v255, 34
	v_readlane_b32 s46, v255, 37
	v_readlane_b32 s47, v255, 38
	v_readlane_b32 s48, v255, 39
	v_readlane_b32 s49, v255, 40
	v_readlane_b32 s50, v255, 41
	v_readlane_b32 s51, v255, 42
	s_cbranch_scc1 .LBB0_47
	s_mul_hi_i32 s3, s2, 0x2e8ba2e9
	s_lshr_b32 s8, s3, 31
	s_ashr_i32 s3, s3, 3
	s_add_i32 s3, s3, s8
	s_mul_i32 s8, s3, 44
	s_sub_i32 s8, s2, s8
	v_lshl_or_b32 v0, s3, 6, v17
	v_lshl_add_u32 v2, s8, 6, v16
	v_ashrrev_i32_e32 v1, 31, v0
	v_ashrrev_i32_e32 v3, 31, v2
	v_lshl_add_u64 v[0:1], v[0:1], 2, s[6:7]
	v_lshlrev_b64 v[2:3], 12, v[2:3]
	v_lshl_add_u64 v[8:9], v[0:1], 0, v[2:3]
	v_add_co_u32_e32 v4, vcc, s81, v8
	s_mov_b32 s3, 0x30000
	s_nop 0
	v_addc_co_u32_e32 v5, vcc, 0, v9, vcc
	v_add_co_u32_e32 v10, vcc, s78, v8
	global_load_dwordx4 v[0:3], v[8:9], off
	s_nop 0
	global_load_dwordx4 v[4:7], v[4:5], off
	v_addc_co_u32_e32 v11, vcc, 0, v9, vcc
	v_add_co_u32_e32 v12, vcc, s3, v8
	s_nop 1
	v_addc_co_u32_e32 v13, vcc, 0, v9, vcc
	global_load_dwordx4 v[8:11], v[10:11], off
	s_nop 0
	global_load_dwordx4 v[12:15], v[12:13], off
.LBB0_47:
	s_add_i32 s3, s0, 0x2bf
	s_sub_i32 s9, 0xfffffd41, s0
	s_ashr_i32 s8, s3, 31
	s_max_i32 s3, s3, s9
	s_mul_hi_u32 s9, s3, s63
	s_mul_i32 s24, s9, s61
	s_sub_i32 s3, s3, s24
	s_xor_b32 s8, s8, s66
	s_add_i32 s24, s9, 1
	s_sub_i32 s25, s3, s61
	s_cmp_ge_u32 s3, s61
	s_cselect_b32 s9, s24, s9
	s_cselect_b32 s3, s25, s3
	s_add_i32 s24, s9, 1
	s_cmp_ge_u32 s3, s61
	s_cselect_b32 s3, s24, s9
	s_xor_b32 s3, s3, s8
	s_sub_i32 s65, s3, s8
	s_cmp_gt_i32 s65, 0
	s_cselect_b64 s[24:25], -1, 0
	s_cmp_lt_i32 s65, 1
	s_cbranch_scc1 .LBB0_56
	v_lshlrev_b32_e32 v19, 4, v20
	s_movk_i32 s3, 0x104
	v_and_b32_e32 v22, 48, v19
	v_mul_lo_u32 v19, v16, s3
	v_lshlrev_b32_e32 v21, 2, v17
	s_add_u32 s8, s20, 0xb00000
	v_ashrrev_i32_e32 v18, 2, v20
	v_add3_u32 v19, s60, v19, v21
	v_mul_u32_u24_e32 v21, 0x104, v22
	v_and_b32_e32 v20, -4, v20
	s_addc_u32 s9, s21, 0
	v_add3_u32 v20, s60, v21, v20
	v_lshlrev_b32_e32 v144, 1, v22
	s_mov_b32 s3, s65
	s_mov_b32 s98, 0
	s_branch .LBB0_50

.LBB0_50:
	s_cmpk_lt_i32 s2, 0x2c0
	s_cselect_b64 s[26:27], -1, 0
	s_cmpk_gt_i32 s2, 0x2bf
	s_waitcnt lgkmcnt(0)
	s_barrier
	s_cbranch_scc1 .LBB0_52
	v_add_u32_e32 v21, 0x1040, v19
	s_cmp_eq_u32 s98, 0
	s_cbranch_scc1 .Lcvw1_f
	s_waitcnt vmcnt(2)
	s_branch .Lcvw1_d

.Lcvw1_d:
	s_mov_b32 s98, 1
	ds_write2_b32 v19, v0, v1 offset1:1
	ds_write2_b32 v19, v2, v3 offset0:2 offset1:3
	ds_write2_b32 v21, v4, v5 offset1:1
	v_add_u32_e32 v21, 0x1048, v19
	ds_write2_b32 v21, v6, v7 offset1:1
	v_add_u32_e32 v21, 0x2080, v19
	ds_write2_b32 v21, v8, v9 offset1:1
	v_add_u32_e32 v21, 0x2088, v19
	ds_write2_b32 v21, v10, v11 offset1:1
	v_add_u32_e32 v21, 0x30c0, v19
	ds_write2_b32 v21, v12, v13 offset1:1
	v_add_u32_e32 v21, 0x30c8, v19
	ds_write2_b32 v21, v14, v15 offset1:1
.LBB0_52:
	s_add_i32 s28, s0, s2
	s_cmpk_gt_i32 s28, 0x2bf
	s_cbranch_scc1 .LBB0_54
	s_mul_hi_i32 s29, s28, 0x2e8ba2e9
	s_lshr_b32 s30, s29, 31
	s_ashr_i32 s29, s29, 3
	s_add_i32 s29, s29, s30
	s_mul_i32 s30, s29, 44
	s_sub_i32 s30, s28, s30
	s_waitcnt vmcnt(2)
	v_lshl_or_b32 v0, s29, 6, v17
	v_lshl_add_u32 v2, s30, 6, v16
	v_ashrrev_i32_e32 v1, 31, v0
	v_ashrrev_i32_e32 v3, 31, v2
	v_lshl_add_u64 v[0:1], v[0:1], 2, s[6:7]
	v_lshlrev_b64 v[2:3], 12, v[2:3]
	v_lshl_add_u64 v[8:9], v[0:1], 0, v[2:3]
	v_add_co_u32_e32 v4, vcc, s81, v8
	s_mov_b32 s29, 0x30000
	s_nop 0
	v_addc_co_u32_e32 v5, vcc, 0, v9, vcc
	v_add_co_u32_e32 v10, vcc, s78, v8
	global_load_dwordx4 v[0:3], v[8:9], off
	s_nop 0
	global_load_dwordx4 v[4:7], v[4:5], off
	v_addc_co_u32_e32 v11, vcc, 0, v9, vcc
	v_add_co_u32_e32 v12, vcc, s29, v8
	s_nop 1
	v_addc_co_u32_e32 v13, vcc, 0, v9, vcc
	global_load_dwordx4 v[8:11], v[10:11], off
	s_nop 0
	global_load_dwordx4 v[12:15], v[12:13], off
.LBB0_54:
	s_andn2_b64 vcc, exec, s[26:27]
	s_waitcnt lgkmcnt(0)
	s_barrier
	s_cbranch_vccnz .LBB0_49
	ds_read2_b32 v[22:23], v20 offset1:65
	ds_read2_b32 v[24:25], v20 offset0:130 offset1:195
	v_add_u32_e32 v21, 0x400, v20
	s_mul_hi_i32 s26, s2, 0x2e8ba2e9
	s_waitcnt lgkmcnt(0)
	v_cvt_pk_bf16_f32 v22, v22, v23
	v_cvt_pk_bf16_f32 v23, v24, v25
	ds_read2_b32 v[24:25], v21 offset0:4 offset1:69
	ds_read2_b32 v[26:27], v21 offset0:134 offset1:199
	v_add_u32_e32 v21, 0x800, v20
	s_lshr_b32 s27, s26, 31
	s_ashr_i32 s26, s26, 3
	s_waitcnt lgkmcnt(0)
	v_cvt_pk_bf16_f32 v24, v24, v25
	v_cvt_pk_bf16_f32 v25, v26, v27
	ds_read2_b32 v[26:27], v21 offset0:8 offset1:73
	ds_read2_b32 v[28:29], v21 offset0:138 offset1:203
	v_add_u32_e32 v21, 0xc00, v20
	s_add_i32 s26, s26, s27
	s_waitcnt lgkmcnt(0)
	v_cvt_pk_bf16_f32 v26, v26, v27
	v_cvt_pk_bf16_f32 v27, v28, v29
	ds_read2_b32 v[28:29], v21 offset0:12 offset1:77
	ds_read2_b32 v[30:31], v21 offset0:142 offset1:207
	s_mul_i32 s27, s26, 44
	s_waitcnt lgkmcnt(0)
	v_cvt_pk_bf16_f32 v28, v28, v29
	v_cvt_pk_bf16_f32 v29, v30, v31
	v_lshl_add_u32 v21, s26, 6, v18
	v_mov_b64_e32 v[30:31], s[8:9]
	s_sub_i32 s2, s2, s27
	v_mad_i64_i32 v[30:31], s[26:27], v21, s33, v[30:31]
	s_lshl_b32 s26, s2, 6
	s_ashr_i32 s27, s26, 31
	v_lshl_add_u64 v[30:31], s[26:27], 1, v[30:31]
	v_lshl_add_u64 v[30:31], v[30:31], 0, v[144:145]
	global_store_dwordx4 v[30:31], v[22:25], off
	global_store_dwordx4 v[30:31], v[26:29], off offset:16
	s_branch .LBB0_49
.LBB0_56:
	v_readlane_b32 s36, v255, 27
	v_readlane_b32 s48, v255, 39
	v_readlane_b32 s49, v255, 40
	s_mov_b64 s[2:3], s[48:49]
	v_readlane_b32 s46, v255, 37
	v_readlane_b32 s47, v255, 38
	s_add_u32 s8, s2, 0x1700000
	s_addc_u32 s9, s3, 0
	s_mov_b64 s[30:31], s[46:47]
	s_mul_hi_u32 s2, s63, 0x840
	s_add_u32 s26, s30, 0x1000
	s_mul_i32 s2, s2, s61
	s_addc_u32 s27, s31, 0
	s_sub_i32 s2, 0x840, s2
	s_sub_i32 s3, s2, s61
	s_cmp_ge_u32 s2, s61
	s_cselect_b32 s2, s3, s2
	s_sub_i32 s3, s2, s61
	s_cmp_ge_u32 s2, s61
	s_cselect_b32 s2, s3, s2
	s_sub_i32 s2, s62, s2
	s_ashr_i32 s3, s2, 31
	s_abs_i32 s2, s2
	s_mul_hi_u32 s6, s2, s63
	s_mul_i32 s6, s6, s61
	s_sub_i32 s2, s2, s6
	s_sub_i32 s6, s2, s61
	s_cmp_ge_u32 s2, s61
	s_cselect_b32 s2, s6, s2
	s_sub_i32 s6, s2, s61
	s_cmp_ge_u32 s2, s61
	s_cselect_b32 s2, s6, s2
	s_xor_b32 s2, s2, s3
	v_mov_b32_e32 v22, v191
	s_sub_i32 s36, s2, s3
	s_waitcnt vmcnt(0) lgkmcnt(0)
	v_mov_b32_e32 v15, 0
	s_cmpk_gt_i32 s36, 0x5bf
	v_lshlrev_b32_e32 v19, 2, v22
	v_ashrrev_i32_e32 v18, 4, v22
	v_mov_b32_e32 v14, v15
	v_mov_b32_e32 v13, v15
	v_mov_b32_e32 v12, v15
	v_mov_b32_e32 v11, v15
	v_mov_b32_e32 v10, v15
	v_mov_b32_e32 v9, v15
	v_mov_b32_e32 v8, v15
	v_mov_b32_e32 v7, v15
	v_mov_b32_e32 v6, v15
	v_mov_b32_e32 v5, v15
	v_mov_b32_e32 v4, v15
	v_mov_b32_e32 v3, v15
	v_mov_b32_e32 v2, v15
	v_mov_b32_e32 v1, v15
	v_mov_b32_e32 v0, v15
	v_readlane_b32 s37, v255, 28
	v_readlane_b32 s38, v255, 29
	v_readlane_b32 s39, v255, 30
	v_readlane_b32 s40, v255, 31
	v_readlane_b32 s41, v255, 32
	v_readlane_b32 s42, v255, 33
	v_readlane_b32 s43, v255, 34
	v_readlane_b32 s44, v255, 35
	v_readlane_b32 s45, v255, 36
	v_readlane_b32 s50, v255, 41
	v_readlane_b32 s51, v255, 42
	s_cbranch_scc1 .LBB0_65
	s_ashr_i32 s2, s36, 31
	s_lshr_b32 s2, s2, 28
	s_add_i32 s2, s36, s2
	s_and_b32 s3, s2, 0x3fffff0
	s_lshl_b32 s2, s2, 2
	s_andn2_b32 s2, s2, 63
	v_and_or_b32 v0, v19, 60, s2
	s_sub_i32 s3, s36, s3
	v_ashrrev_i32_e32 v1, 31, v0
	v_lshl_add_u32 v12, s3, 6, v18
	v_lshl_add_u64 v[14:15], v[0:1], 2, s[8:9]
	s_movk_i32 s2, 0x5c00
	v_mad_i64_i32 v[0:1], s[2:3], v12, s2, v[14:15]
	global_load_dwordx4 v[0:3], v[0:1], off
	s_cmp_lg_u64 s[30:31], 0
	s_cselect_b64 s[2:3], -1, 0
	s_cmp_eq_u64 s[30:31], 0
	v_ashrrev_i32_e32 v13, 31, v12
	s_cbranch_scc1 .LBB0_59
	v_lshl_add_u64 v[4:5], v[12:13], 2, s[26:27]
	global_load_dword v40, v[4:5], off
.LBB0_59:
	v_add_u32_e32 v8, 16, v12
	s_movk_i32 s6, 0x5c00
	v_mad_i64_i32 v[4:5], s[6:7], v8, s6, v[14:15]
	global_load_dwordx4 v[4:7], v[4:5], off
	v_cndmask_b32_e64 v9, 0, 1, s[2:3]
	v_cmp_ne_u32_e64 s[6:7], 1, v9
	s_andn2_b64 vcc, exec, s[2:3]
	s_cbranch_vccnz .LBB0_61
	v_ashrrev_i32_e32 v9, 31, v8
	v_lshl_add_u64 v[8:9], v[8:9], 2, s[26:27]
	global_load_dword v42, v[8:9], off
.LBB0_61:
	v_add_u32_e32 v16, 32, v12
	s_movk_i32 s2, 0x5c00
	v_mad_i64_i32 v[8:9], s[2:3], v16, s2, v[14:15]
	global_load_dwordx4 v[8:11], v[8:9], off
	s_and_b64 vcc, exec, s[6:7]
	s_cbranch_vccnz .LBB0_63
	v_ashrrev_i32_e32 v17, 31, v16
	v_lshl_add_u64 v[16:17], v[16:17], 2, s[26:27]
	global_load_dword v44, v[16:17], off
.LBB0_63:
	v_add_u32_e32 v16, 48, v12
	s_movk_i32 s2, 0x5c00
	v_mad_i64_i32 v[12:13], s[2:3], v16, s2, v[14:15]
	global_load_dwordx4 v[12:15], v[12:13], off
	s_and_b64 vcc, exec, s[6:7]
	s_cbranch_vccnz .LBB0_65
	v_ashrrev_i32_e32 v17, 31, v16
	v_lshl_add_u64 v[16:17], v[16:17], 2, s[26:27]
	global_load_dword v46, v[16:17], off
.LBB0_65:
	s_add_i32 s2, s0, 0x5bf
	s_sub_i32 s6, 0xfffffa41, s0
	s_ashr_i32 s3, s2, 31
	s_max_i32 s2, s2, s6
	s_mul_hi_u32 s6, s2, s63
	s_mul_i32 s7, s6, s61
	s_sub_i32 s2, s2, s7
	s_xor_b32 s3, s3, s66
	s_add_i32 s7, s6, 1
	s_sub_i32 s28, s2, s61
	s_cmp_ge_u32 s2, s61
	s_cselect_b32 s6, s7, s6
	s_cselect_b32 s2, s28, s2
	s_add_i32 s7, s6, 1
	s_cmp_ge_u32 s2, s61
	s_cselect_b32 s2, s7, s6
	s_xor_b32 s2, s2, s3
	s_sub_i32 s2, s2, s3
	s_cmp_lt_i32 s2, 1
	s_cbranch_scc1 .LBB0_82
	s_add_u32 s28, s20, 0x1080000
	v_and_b32_e32 v19, 60, v19
	v_lshlrev_b32_e32 v16, 4, v22
	s_movk_i32 s3, 0x104
	s_addc_u32 s29, s21, 0
	v_and_b32_e32 v16, 48, v16
	v_mul_lo_u32 v17, v18, s3
	v_lshlrev_b32_e32 v21, 2, v19
	s_cmp_lg_u64 s[30:31], 0
	v_ashrrev_i32_e32 v20, 2, v22
	v_add3_u32 v21, s60, v17, v21
	v_mul_u32_u24_e32 v17, 0x104, v16
	v_and_b32_e32 v22, -4, v22
	s_cselect_b64 s[30:31], -1, 0
	v_add3_u32 v22, s60, v17, v22
	v_lshlrev_b32_e32 v144, 1, v16
	s_mov_b32 s98, 0
	s_branch .LBB0_68

.LBB0_68:
	s_cmpk_lt_i32 s36, 0x5c0
	s_cselect_b64 s[34:35], -1, 0
	s_cmpk_gt_i32 s36, 0x5bf
	s_waitcnt lgkmcnt(0)
	s_barrier
	s_cbranch_scc1 .LBB0_70
	v_add_u32_e32 v16, 0x1040, v21
	s_cmp_eq_u32 s98, 0
	s_cbranch_scc1 .Lcvw2_f
	s_waitcnt vmcnt(2)
	s_branch .Lcvw2_d

.Lcvw2_d:
	s_mov_b32 s98, 1
	v_pk_mul_f32 v[2:3], v[2:3], v[40:41] op_sel_hi:[1,0]
	v_pk_mul_f32 v[0:1], v[0:1], v[40:41] op_sel_hi:[1,0]
	v_pk_mul_f32 v[6:7], v[6:7], v[42:43] op_sel_hi:[1,0]
	v_pk_mul_f32 v[4:5], v[4:5], v[42:43] op_sel_hi:[1,0]
	v_pk_mul_f32 v[10:11], v[10:11], v[44:45] op_sel_hi:[1,0]
	v_pk_mul_f32 v[8:9], v[8:9], v[44:45] op_sel_hi:[1,0]
	v_pk_mul_f32 v[14:15], v[14:15], v[46:47] op_sel_hi:[1,0]
	v_pk_mul_f32 v[12:13], v[12:13], v[46:47] op_sel_hi:[1,0]
	ds_write2_b32 v21, v0, v1 offset1:1
	ds_write2_b32 v21, v2, v3 offset0:2 offset1:3
	ds_write2_b32 v16, v4, v5 offset1:1
	v_add_u32_e32 v16, 0x1048, v21
	ds_write2_b32 v16, v6, v7 offset1:1
	v_add_u32_e32 v16, 0x2080, v21
	ds_write2_b32 v16, v8, v9 offset1:1
	v_add_u32_e32 v16, 0x2088, v21
	ds_write2_b32 v16, v10, v11 offset1:1
	v_add_u32_e32 v16, 0x30c0, v21
	ds_write2_b32 v16, v12, v13 offset1:1
	v_add_u32_e32 v16, 0x30c8, v21
	ds_write2_b32 v16, v14, v15 offset1:1
.LBB0_70:
	s_add_i32 s3, s0, s36
	s_cmpk_gt_i32 s3, 0x5bf
	s_cbranch_scc1 .LBB0_80
	s_ashr_i32 s6, s3, 31
	s_lshr_b32 s6, s6, 28
	s_add_i32 s6, s3, s6
	s_and_b32 s7, s6, 0x3fffff0
	s_lshl_b32 s6, s6, 2
	s_andn2_b32 s6, s6, 63
	s_waitcnt vmcnt(2)
	v_or_b32_e32 v0, s6, v19
	s_sub_i32 s7, s3, s7
	v_ashrrev_i32_e32 v1, 31, v0
	v_lshl_add_u32 v12, s7, 6, v18
	v_lshl_add_u64 v[14:15], v[0:1], 2, s[8:9]
	s_movk_i32 s6, 0x5c00
	v_mad_i64_i32 v[0:1], s[6:7], v12, s6, v[14:15]
	global_load_dwordx4 v[0:3], v[0:1], off
	v_cndmask_b32_e64 v4, 0, 1, s[30:31]
	v_ashrrev_i32_e32 v13, 31, v12
	v_cmp_ne_u32_e64 s[6:7], 1, v4
	s_andn2_b64 vcc, exec, s[30:31]
	s_cbranch_vccnz .LBB0_73
	v_lshl_add_u64 v[4:5], v[12:13], 2, s[26:27]
	global_load_dword v40, v[4:5], off
.LBB0_73:
	v_add_u32_e32 v8, 16, v12
	s_movk_i32 s37, 0x5c00
	v_mad_i64_i32 v[4:5], s[68:69], v8, s37, v[14:15]
	global_load_dwordx4 v[4:7], v[4:5], off
	s_and_b64 vcc, exec, s[6:7]
	s_cbranch_vccnz .LBB0_75
	v_ashrrev_i32_e32 v9, 31, v8
	v_lshl_add_u64 v[8:9], v[8:9], 2, s[26:27]
	global_load_dword v42, v[8:9], off
.LBB0_75:
	v_add_u32_e32 v16, 32, v12
	v_mad_i64_i32 v[8:9], s[68:69], v16, s37, v[14:15]
	global_load_dwordx4 v[8:11], v[8:9], off
	s_and_b64 vcc, exec, s[6:7]
	s_cbranch_vccnz .LBB0_77
	v_ashrrev_i32_e32 v17, 31, v16
	v_lshl_add_u64 v[16:17], v[16:17], 2, s[26:27]
	global_load_dword v44, v[16:17], off
.LBB0_77:
	v_add_u32_e32 v16, 48, v12
	v_mad_i64_i32 v[12:13], s[68:69], v16, s37, v[14:15]
	global_load_dwordx4 v[12:15], v[12:13], off
	s_and_b64 vcc, exec, s[6:7]
	s_cbranch_vccnz .LBB0_79
	v_ashrrev_i32_e32 v17, 31, v16
	v_lshl_add_u64 v[16:17], v[16:17], 2, s[26:27]
	global_load_dword v46, v[16:17], off

.LBB0_80:
	s_andn2_b64 vcc, exec, s[34:35]
	s_waitcnt lgkmcnt(0)
	s_barrier
	s_cbranch_vccnz .LBB0_67
	ds_read2_b32 v[16:17], v22 offset1:65
	s_waitcnt lgkmcnt(0)
	v_cvt_pk_bf16_f32 v24, v16, v17
	ds_read2_b32 v[16:17], v22 offset0:130 offset1:195
	v_add_u32_e32 v23, 0x400, v22
	s_waitcnt lgkmcnt(0)
	v_cvt_pk_bf16_f32 v25, v16, v17
	ds_read2_b32 v[16:17], v23 offset0:4 offset1:69
	s_ashr_i32 s6, s36, 31
	s_waitcnt lgkmcnt(0)
	v_cvt_pk_bf16_f32 v26, v16, v17
	ds_read2_b32 v[16:17], v23 offset0:134 offset1:199
	v_add_u32_e32 v23, 0x800, v22
	s_lshr_b32 s6, s6, 28
	s_waitcnt lgkmcnt(0)
	v_cvt_pk_bf16_f32 v27, v16, v17
	ds_read2_b32 v[16:17], v23 offset0:8 offset1:73
	s_add_i32 s6, s36, s6
	s_waitcnt lgkmcnt(0)
	v_cvt_pk_bf16_f32 v28, v16, v17
	ds_read2_b32 v[16:17], v23 offset0:138 offset1:203
	v_add_u32_e32 v23, 0xc00, v22
	s_and_b32 s7, s6, 0x3fffff0
	s_waitcnt lgkmcnt(0)
	v_cvt_pk_bf16_f32 v29, v16, v17
	ds_read2_b32 v[16:17], v23 offset0:12 offset1:77
	s_lshl_b32 s6, s6, 2
	s_waitcnt lgkmcnt(0)
	v_cvt_pk_bf16_f32 v30, v16, v17
	ds_read2_b32 v[16:17], v23 offset0:142 offset1:207
	s_andn2_b32 s6, s6, 63
	s_waitcnt lgkmcnt(0)
	v_cvt_pk_bf16_f32 v31, v16, v17
	v_add_u32_e32 v16, s6, v20
	s_sub_i32 s7, s36, s7
	v_ashrrev_i32_e32 v17, 31, v16
	v_lshlrev_b64 v[16:17], 11, v[16:17]
	s_lshl_b32 s6, s7, 6
	v_lshl_add_u64 v[16:17], s[28:29], 0, v[16:17]
	s_ashr_i32 s7, s6, 31
	v_lshl_add_u64 v[16:17], s[6:7], 1, v[16:17]
	v_lshl_add_u64 v[16:17], v[16:17], 0, v[144:145]
	global_store_dwordx4 v[16:17], v[24:27], off
	global_store_dwordx4 v[16:17], v[28:31], off offset:16
	s_branch .LBB0_67
.LBB0_82:
	v_readlane_b32 s36, v254, 6
	v_readlane_b32 s40, v254, 10
	v_readlane_b32 s41, v254, 11
	s_mov_b64 s[2:3], s[40:41]
	s_add_u32 s6, s2, 0x200000
	s_mul_hi_u32 s2, s63, 0xe00
	s_mul_i32 s2, s2, s61
	s_addc_u32 s7, s3, 0
	s_sub_i32 s2, 0xe00, s2
	s_sub_i32 s3, s2, s61
	s_cmp_ge_u32 s2, s61
	s_cselect_b32 s2, s3, s2
	s_sub_i32 s3, s2, s61
	s_cmp_ge_u32 s2, s61
	s_cselect_b32 s2, s3, s2
	s_sub_i32 s2, s62, s2
	s_ashr_i32 s3, s2, 31
	s_abs_i32 s2, s2
	s_mul_hi_u32 s8, s2, s63
	s_mul_i32 s8, s8, s61
	s_sub_i32 s2, s2, s8
	s_sub_i32 s8, s2, s61
	s_cmp_ge_u32 s2, s61
	s_cselect_b32 s2, s8, s2
	s_sub_i32 s8, s2, s61
	s_cmp_ge_u32 s2, s61
	s_cselect_b32 s2, s8, s2
	s_xor_b32 s2, s2, s3
	v_mov_b32_e32 v20, v191
	s_sub_i32 s3, s2, s3
	s_waitcnt vmcnt(0) lgkmcnt(0)
	v_mov_b32_e32 v0, 0
	s_cmpk_gt_i32 s3, 0x7f
	v_lshlrev_b32_e32 v17, 2, v20
	v_ashrrev_i32_e32 v16, 4, v20
	v_mov_b32_e32 v1, v0
	v_mov_b32_e32 v2, v0
	v_mov_b32_e32 v3, v0
	v_mov_b32_e32 v4, v0
	v_mov_b32_e32 v5, v0
	v_mov_b32_e32 v6, v0
	v_mov_b32_e32 v7, v0
	v_mov_b32_e32 v8, v0
	v_mov_b32_e32 v9, v0
	v_mov_b32_e32 v10, v0
	v_mov_b32_e32 v11, v0
	v_mov_b32_e32 v12, v0
	v_mov_b32_e32 v13, v0
	v_mov_b32_e32 v14, v0
	v_mov_b32_e32 v15, v0
	v_readlane_b32 s37, v254, 7
	v_readlane_b32 s38, v254, 8
	v_readlane_b32 s39, v254, 9
	v_readlane_b32 s42, v254, 12
	v_readlane_b32 s43, v254, 13
	v_readlane_b32 s44, v254, 14
	v_readlane_b32 s45, v254, 15
	v_readlane_b32 s46, v254, 16
	v_readlane_b32 s47, v254, 17
	v_readlane_b32 s48, v254, 18
	v_readlane_b32 s49, v254, 19
	v_readlane_b32 s50, v254, 20
	v_readlane_b32 s51, v254, 21
	s_cbranch_scc1 .LBB0_84
	s_ashr_i32 s2, s3, 31
	s_lshr_b32 s2, s2, 29
	s_add_i32 s2, s3, s2
	s_and_b32 s8, s2, 0x3fffff8
	s_lshl_b32 s2, s2, 3
	s_sub_i32 s8, s3, s8
	s_andn2_b32 s2, s2, 63
	v_and_or_b32 v0, v17, 60, s2
	v_lshl_add_u32 v2, s8, 6, v16
	v_ashrrev_i32_e32 v1, 31, v0
	v_ashrrev_i32_e32 v3, 31, v2
	v_lshl_add_u64 v[0:1], v[0:1], 2, s[6:7]
	v_lshlrev_b64 v[2:3], 12, v[2:3]
	v_lshl_add_u64 v[8:9], v[0:1], 0, v[2:3]
	v_add_co_u32_e32 v4, vcc, s81, v8
	s_mov_b32 s2, 0x30000
	s_nop 0
	v_addc_co_u32_e32 v5, vcc, 0, v9, vcc
	v_add_co_u32_e32 v10, vcc, s78, v8
	global_load_dwordx4 v[0:3], v[8:9], off
	s_nop 0
	global_load_dwordx4 v[4:7], v[4:5], off
	v_addc_co_u32_e32 v11, vcc, 0, v9, vcc
	v_add_co_u32_e32 v12, vcc, s2, v8
	s_nop 1
	v_addc_co_u32_e32 v13, vcc, 0, v9, vcc
	global_load_dwordx4 v[8:11], v[10:11], off
	s_nop 0
	global_load_dwordx4 v[12:15], v[12:13], off
.LBB0_84:
	s_add_i32 s2, s0, 0x7f
	s_sub_i32 s9, 0xffffff81, s0
	s_ashr_i32 s8, s2, 31
	s_max_i32 s2, s2, s9
	s_mul_hi_u32 s9, s2, s63
	s_mul_i32 s26, s9, s61
	s_sub_i32 s2, s2, s26
	s_xor_b32 s8, s8, s66
	s_add_i32 s26, s9, 1
	s_sub_i32 s27, s2, s61
	s_cmp_ge_u32 s2, s61
	s_cselect_b32 s9, s26, s9
	s_cselect_b32 s2, s27, s2
	s_add_i32 s26, s9, 1
	s_cmp_ge_u32 s2, s61
	s_cselect_b32 s2, s26, s9
	s_xor_b32 s2, s2, s8
	s_sub_i32 s2, s2, s8
	s_cmp_gt_i32 s2, 0
	s_cselect_b64 s[8:9], -1, 0
	s_cmp_lt_i32 s2, 1
	s_cbranch_scc1 .LBB0_93
	v_and_b32_e32 v17, 60, v17
	v_lshlrev_b32_e32 v19, 4, v20
	s_movk_i32 s28, 0x104
	v_and_b32_e32 v22, 48, v19
	v_mul_lo_u32 v19, v16, s28
	v_lshlrev_b32_e32 v21, 2, v17
	s_add_u32 s26, s20, 0x1c00000
	v_ashrrev_i32_e32 v18, 2, v20
	v_add3_u32 v19, s60, v19, v21
	v_mul_u32_u24_e32 v21, 0x104, v22
	v_and_b32_e32 v20, -4, v20
	s_addc_u32 s27, s21, 0
	v_add3_u32 v20, s60, v21, v20
	v_lshlrev_b32_e32 v144, 1, v22
	s_mov_b32 s30, s2
	s_mov_b32 s98, 0
	s_branch .LBB0_87

.LBB0_87:
	s_cmpk_lt_i32 s3, 0x80
	s_cselect_b64 s[28:29], -1, 0
	s_cmpk_gt_i32 s3, 0x7f
	s_waitcnt lgkmcnt(0)
	s_barrier
	s_cbranch_scc1 .LBB0_89
	v_add_u32_e32 v21, 0x1040, v19
	s_cmp_eq_u32 s98, 0
	s_cbranch_scc1 .Lcvw3_f
	s_waitcnt vmcnt(2)
	s_branch .Lcvw3_d

.LBB0_89:
	s_add_i32 s31, s0, s3
	s_cmpk_gt_i32 s31, 0x7f
	s_cbranch_scc1 .LBB0_91
	s_ashr_i32 s34, s31, 31
	s_lshr_b32 s34, s34, 29
	s_add_i32 s34, s31, s34
	s_and_b32 s35, s34, 0x3fffff8
	s_lshl_b32 s34, s34, 3
	s_sub_i32 s35, s31, s35
	s_andn2_b32 s34, s34, 63
	s_waitcnt vmcnt(2)
	v_or_b32_e32 v0, s34, v17
	v_lshl_add_u32 v2, s35, 6, v16
	v_ashrrev_i32_e32 v1, 31, v0
	v_ashrrev_i32_e32 v3, 31, v2
	v_lshl_add_u64 v[0:1], v[0:1], 2, s[6:7]
	v_lshlrev_b64 v[2:3], 12, v[2:3]
	v_lshl_add_u64 v[8:9], v[0:1], 0, v[2:3]
	v_add_co_u32_e32 v4, vcc, s81, v8
	s_mov_b32 s34, 0x30000
	s_nop 0
	v_addc_co_u32_e32 v5, vcc, 0, v9, vcc
	v_add_co_u32_e32 v10, vcc, s78, v8
	global_load_dwordx4 v[0:3], v[8:9], off
	s_nop 0
	global_load_dwordx4 v[4:7], v[4:5], off
	v_addc_co_u32_e32 v11, vcc, 0, v9, vcc
	v_add_co_u32_e32 v12, vcc, s34, v8
	s_nop 1
	v_addc_co_u32_e32 v13, vcc, 0, v9, vcc
	global_load_dwordx4 v[8:11], v[10:11], off
	s_nop 0
	global_load_dwordx4 v[12:15], v[12:13], off
.LBB0_91:
	s_andn2_b64 vcc, exec, s[28:29]
	s_waitcnt lgkmcnt(0)
	s_barrier
	s_cbranch_vccnz .LBB0_86
	s_ashr_i32 s28, s3, 31
	s_lshr_b32 s28, s28, 29
	ds_read2_b32 v[22:23], v20 offset1:65
	ds_read2_b32 v[24:25], v20 offset0:130 offset1:195
	v_add_u32_e32 v21, 0x400, v20
	s_add_i32 s28, s3, s28
	s_waitcnt lgkmcnt(0)
	v_cvt_pk_bf16_f32 v22, v22, v23
	v_cvt_pk_bf16_f32 v23, v24, v25
	ds_read2_b32 v[24:25], v21 offset0:4 offset1:69
	ds_read2_b32 v[26:27], v21 offset0:134 offset1:199
	v_add_u32_e32 v21, 0x800, v20
	s_and_b32 s29, s28, 0x3fffff8
	s_waitcnt lgkmcnt(0)
	v_cvt_pk_bf16_f32 v24, v24, v25
	v_cvt_pk_bf16_f32 v25, v26, v27
	ds_read2_b32 v[26:27], v21 offset0:8 offset1:73
	ds_read2_b32 v[28:29], v21 offset0:138 offset1:203
	v_add_u32_e32 v21, 0xc00, v20
	s_lshl_b32 s28, s28, 3
	s_waitcnt lgkmcnt(0)
	v_cvt_pk_bf16_f32 v26, v26, v27
	v_cvt_pk_bf16_f32 v27, v28, v29
	ds_read2_b32 v[28:29], v21 offset0:12 offset1:77
	ds_read2_b32 v[30:31], v21 offset0:142 offset1:207
	s_andn2_b32 s28, s28, 63
	s_waitcnt lgkmcnt(0)
	v_cvt_pk_bf16_f32 v28, v28, v29
	v_cvt_pk_bf16_f32 v29, v30, v31
	v_add_u32_e32 v30, s28, v18
	s_sub_i32 s3, s3, s29
	v_ashrrev_i32_e32 v31, 31, v30
	v_lshlrev_b64 v[30:31], 10, v[30:31]
	s_lshl_b32 s28, s3, 6
	v_lshl_add_u64 v[30:31], s[26:27], 0, v[30:31]
	s_ashr_i32 s29, s28, 31
	v_lshl_add_u64 v[30:31], s[28:29], 1, v[30:31]
	v_lshl_add_u64 v[30:31], v[30:31], 0, v[144:145]
	global_store_dwordx4 v[30:31], v[22:25], off
	global_store_dwordx4 v[30:31], v[26:29], off offset:16
	s_branch .LBB0_86
.LBB0_93:
	v_readlane_b32 s36, v254, 6
	v_readlane_b32 s48, v254, 18
	v_readlane_b32 s49, v254, 19
	s_mov_b64 s[6:7], s[48:49]
	s_mul_hi_u32 s3, s63, 0xe80
	s_add_u32 s26, s6, 0x200000
	s_mul_i32 s3, s3, s61
	s_addc_u32 s27, s7, 0
	s_sub_i32 s3, 0xe80, s3
	s_sub_i32 s6, s3, s61
	s_cmp_ge_u32 s3, s61
	s_cselect_b32 s3, s6, s3
	s_sub_i32 s6, s3, s61
	s_cmp_ge_u32 s3, s61
	s_cselect_b32 s3, s6, s3
	s_sub_i32 s3, s62, s3
	s_ashr_i32 s6, s3, 31
	s_abs_i32 s3, s3
	s_mul_hi_u32 s7, s3, s63
	s_mul_i32 s7, s7, s61
	s_sub_i32 s3, s3, s7
	s_sub_i32 s7, s3, s61
	s_cmp_ge_u32 s3, s61
	s_cselect_b32 s3, s7, s3
	s_sub_i32 s7, s3, s61
	s_cmp_ge_u32 s3, s61
	s_cselect_b32 s3, s7, s3
	s_xor_b32 s3, s3, s6
	v_mov_b32_e32 v20, v191
	s_sub_i32 s3, s3, s6
	s_waitcnt vmcnt(0) lgkmcnt(0)
	v_mov_b32_e32 v0, 0
	s_cmpk_gt_i32 s3, 0x7f
	v_lshlrev_b32_e32 v17, 2, v20
	v_ashrrev_i32_e32 v16, 4, v20
	v_mov_b32_e32 v1, v0
	v_mov_b32_e32 v2, v0
	v_mov_b32_e32 v3, v0
	v_mov_b32_e32 v4, v0
	v_mov_b32_e32 v5, v0
	v_mov_b32_e32 v6, v0
	v_mov_b32_e32 v7, v0
	v_mov_b32_e32 v8, v0
	v_mov_b32_e32 v9, v0
	v_mov_b32_e32 v10, v0
	v_mov_b32_e32 v11, v0
	v_mov_b32_e32 v12, v0
	v_mov_b32_e32 v13, v0
	v_mov_b32_e32 v14, v0
	v_mov_b32_e32 v15, v0
	v_readlane_b32 s37, v254, 7
	v_readlane_b32 s38, v254, 8
	v_readlane_b32 s39, v254, 9
	v_readlane_b32 s40, v254, 10
	v_readlane_b32 s41, v254, 11
	v_readlane_b32 s42, v254, 12
	v_readlane_b32 s43, v254, 13
	v_readlane_b32 s44, v254, 14
	v_readlane_b32 s45, v254, 15
	v_readlane_b32 s46, v254, 16
	v_readlane_b32 s47, v254, 17
	v_readlane_b32 s50, v254, 20
	v_readlane_b32 s51, v254, 21
	s_cbranch_scc1 .LBB0_95
	s_ashr_i32 s6, s3, 31
	s_lshr_b32 s6, s6, 29
	s_add_i32 s6, s3, s6
	s_and_b32 s7, s6, 0x3fffff8
	s_lshl_b32 s6, s6, 3
	s_sub_i32 s7, s3, s7
	s_andn2_b32 s6, s6, 63
	v_and_or_b32 v0, v17, 60, s6
	v_lshl_add_u32 v2, s7, 6, v16
	v_ashrrev_i32_e32 v1, 31, v0
	v_ashrrev_i32_e32 v3, 31, v2
	v_lshl_add_u64 v[0:1], v[0:1], 2, s[26:27]
	v_lshlrev_b64 v[2:3], 12, v[2:3]
	v_lshl_add_u64 v[8:9], v[0:1], 0, v[2:3]
	v_add_co_u32_e32 v4, vcc, s81, v8
	s_mov_b32 s6, 0x30000
	s_nop 0
	v_addc_co_u32_e32 v5, vcc, 0, v9, vcc
	v_add_co_u32_e32 v10, vcc, s78, v8
	global_load_dwordx4 v[0:3], v[8:9], off
	s_nop 0
	global_load_dwordx4 v[4:7], v[4:5], off
	v_addc_co_u32_e32 v11, vcc, 0, v9, vcc
	v_add_co_u32_e32 v12, vcc, s6, v8
	s_nop 1
	v_addc_co_u32_e32 v13, vcc, 0, v9, vcc
	global_load_dwordx4 v[8:11], v[10:11], off
	s_nop 0
	global_load_dwordx4 v[12:15], v[12:13], off
.LBB0_95:
	v_cndmask_b32_e64 v18, 0, 1, s[8:9]
	v_cmp_ne_u32_e64 s[6:7], 1, v18
	s_andn2_b64 vcc, exec, s[8:9]
	s_cbranch_vccnz .LBB0_104
	v_and_b32_e32 v17, 60, v17
	v_lshlrev_b32_e32 v19, 4, v20
	s_movk_i32 s28, 0x104
	v_and_b32_e32 v22, 48, v19
	v_mul_lo_u32 v19, v16, s28
	v_lshlrev_b32_e32 v21, 2, v17
	s_add_u32 s8, s20, 0x1d00000
	v_ashrrev_i32_e32 v18, 2, v20
	v_add3_u32 v19, s60, v19, v21
	v_mul_u32_u24_e32 v21, 0x104, v22
	v_and_b32_e32 v20, -4, v20
	s_addc_u32 s9, s21, 0
	v_add3_u32 v20, s60, v21, v20
	v_lshlrev_b32_e32 v144, 1, v22
	s_mov_b32 s30, s2
	s_mov_b32 s98, 0
	s_branch .LBB0_98

.LBB0_100:
	s_add_i32 s31, s0, s3
	s_cmpk_gt_i32 s31, 0x7f
	s_cbranch_scc1 .LBB0_102
	s_ashr_i32 s34, s31, 31
	s_lshr_b32 s34, s34, 29
	s_add_i32 s34, s31, s34
	s_and_b32 s35, s34, 0x3fffff8
	s_lshl_b32 s34, s34, 3
	s_sub_i32 s35, s31, s35
	s_andn2_b32 s34, s34, 63
	s_waitcnt vmcnt(2)
	v_or_b32_e32 v0, s34, v17
	v_lshl_add_u32 v2, s35, 6, v16
	v_ashrrev_i32_e32 v1, 31, v0
	v_ashrrev_i32_e32 v3, 31, v2
	v_lshl_add_u64 v[0:1], v[0:1], 2, s[26:27]
	v_lshlrev_b64 v[2:3], 12, v[2:3]
	v_lshl_add_u64 v[8:9], v[0:1], 0, v[2:3]
	v_add_co_u32_e32 v4, vcc, s81, v8
	s_mov_b32 s34, 0x30000
	s_nop 0
	v_addc_co_u32_e32 v5, vcc, 0, v9, vcc
	v_add_co_u32_e32 v10, vcc, s78, v8
	global_load_dwordx4 v[0:3], v[8:9], off
	s_nop 0
	global_load_dwordx4 v[4:7], v[4:5], off
	v_addc_co_u32_e32 v11, vcc, 0, v9, vcc
	v_add_co_u32_e32 v12, vcc, s34, v8
	s_nop 1
	v_addc_co_u32_e32 v13, vcc, 0, v9, vcc
	global_load_dwordx4 v[8:11], v[10:11], off
	s_nop 0
	global_load_dwordx4 v[12:15], v[12:13], off
.LBB0_102:
	s_andn2_b64 vcc, exec, s[28:29]
	s_waitcnt lgkmcnt(0)
	s_barrier
	s_cbranch_vccnz .LBB0_97
	s_ashr_i32 s28, s3, 31
	s_lshr_b32 s28, s28, 29
	ds_read2_b32 v[22:23], v20 offset1:65
	ds_read2_b32 v[24:25], v20 offset0:130 offset1:195
	v_add_u32_e32 v21, 0x400, v20
	s_add_i32 s28, s3, s28
	s_waitcnt lgkmcnt(0)
	v_cvt_pk_bf16_f32 v22, v22, v23
	v_cvt_pk_bf16_f32 v23, v24, v25
	ds_read2_b32 v[24:25], v21 offset0:4 offset1:69
	ds_read2_b32 v[26:27], v21 offset0:134 offset1:199
	v_add_u32_e32 v21, 0x800, v20
	s_and_b32 s29, s28, 0x3fffff8
	s_waitcnt lgkmcnt(0)
	v_cvt_pk_bf16_f32 v24, v24, v25
	v_cvt_pk_bf16_f32 v25, v26, v27
	ds_read2_b32 v[26:27], v21 offset0:8 offset1:73
	ds_read2_b32 v[28:29], v21 offset0:138 offset1:203
	v_add_u32_e32 v21, 0xc00, v20
	s_lshl_b32 s28, s28, 3
	s_waitcnt lgkmcnt(0)
	v_cvt_pk_bf16_f32 v26, v26, v27
	v_cvt_pk_bf16_f32 v27, v28, v29
	ds_read2_b32 v[28:29], v21 offset0:12 offset1:77
	ds_read2_b32 v[30:31], v21 offset0:142 offset1:207
	s_andn2_b32 s28, s28, 63
	s_waitcnt lgkmcnt(0)
	v_cvt_pk_bf16_f32 v28, v28, v29
	v_cvt_pk_bf16_f32 v29, v30, v31
	v_add_u32_e32 v30, s28, v18
	s_sub_i32 s3, s3, s29
	v_ashrrev_i32_e32 v31, 31, v30
	v_lshlrev_b64 v[30:31], 10, v[30:31]
	s_lshl_b32 s28, s3, 6
	v_lshl_add_u64 v[30:31], s[8:9], 0, v[30:31]
	s_ashr_i32 s29, s28, 31
	v_lshl_add_u64 v[30:31], s[28:29], 1, v[30:31]
	v_lshl_add_u64 v[30:31], v[30:31], 0, v[144:145]
	global_store_dwordx4 v[30:31], v[22:25], off
	global_store_dwordx4 v[30:31], v[26:29], off offset:16
	s_branch .LBB0_97
.LBB0_104:
	v_readlane_b32 s36, v254, 22
	v_readlane_b32 s48, v254, 34
	v_readlane_b32 s49, v254, 35
	s_mov_b64 s[8:9], s[48:49]
	s_mul_hi_u32 s3, s63, 0xf00
	s_add_u32 s8, s8, 0x200000
	s_mul_i32 s3, s3, s61
	s_addc_u32 s9, s9, 0
	s_sub_i32 s3, 0xf00, s3
	s_sub_i32 s26, s3, s61
	s_cmp_ge_u32 s3, s61
	s_cselect_b32 s3, s26, s3
	s_sub_i32 s26, s3, s61
	s_cmp_ge_u32 s3, s61
	s_cselect_b32 s3, s26, s3
	s_sub_i32 s3, s62, s3
	s_ashr_i32 s26, s3, 31
	s_abs_i32 s3, s3
	s_mul_hi_u32 s27, s3, s63
	s_mul_i32 s27, s27, s61
	s_sub_i32 s3, s3, s27
	s_sub_i32 s27, s3, s61
	s_cmp_ge_u32 s3, s61
	s_cselect_b32 s3, s27, s3
	s_sub_i32 s27, s3, s61
	s_cmp_ge_u32 s3, s61
	s_cselect_b32 s3, s27, s3
	s_xor_b32 s3, s3, s26
	v_mov_b32_e32 v20, v191
	s_sub_i32 s3, s3, s26
	s_waitcnt vmcnt(0) lgkmcnt(0)
	v_mov_b32_e32 v0, 0
	s_cmpk_gt_i32 s3, 0x7f
	v_lshlrev_b32_e32 v17, 2, v20
	v_ashrrev_i32_e32 v16, 4, v20
	v_mov_b32_e32 v1, v0
	v_mov_b32_e32 v2, v0
	v_mov_b32_e32 v3, v0
	v_mov_b32_e32 v4, v0
	v_mov_b32_e32 v5, v0
	v_mov_b32_e32 v6, v0
	v_mov_b32_e32 v7, v0
	v_mov_b32_e32 v8, v0
	v_mov_b32_e32 v9, v0
	v_mov_b32_e32 v10, v0
	v_mov_b32_e32 v11, v0
	v_mov_b32_e32 v12, v0
	v_mov_b32_e32 v13, v0
	v_mov_b32_e32 v14, v0
	v_mov_b32_e32 v15, v0
	v_readlane_b32 s37, v254, 23
	v_readlane_b32 s38, v254, 24
	v_readlane_b32 s39, v254, 25
	v_readlane_b32 s40, v254, 26
	v_readlane_b32 s41, v254, 27
	v_readlane_b32 s42, v254, 28
	v_readlane_b32 s43, v254, 29
	v_readlane_b32 s44, v254, 30
	v_readlane_b32 s45, v254, 31
	v_readlane_b32 s46, v254, 32
	v_readlane_b32 s47, v254, 33
	v_readlane_b32 s50, v254, 36
	v_readlane_b32 s51, v254, 37
	s_cbranch_scc1 .LBB0_106
	s_ashr_i32 s26, s3, 31
	s_lshr_b32 s26, s26, 29
	s_add_i32 s26, s3, s26
	s_and_b32 s27, s26, 0x3fffff8
	s_lshl_b32 s26, s26, 3
	s_sub_i32 s27, s3, s27
	s_andn2_b32 s26, s26, 63
	v_and_or_b32 v0, v17, 60, s26
	v_lshl_add_u32 v2, s27, 6, v16
	v_ashrrev_i32_e32 v1, 31, v0
	v_ashrrev_i32_e32 v3, 31, v2
	v_lshl_add_u64 v[0:1], v[0:1], 2, s[8:9]
	v_lshlrev_b64 v[2:3], 12, v[2:3]
	v_lshl_add_u64 v[8:9], v[0:1], 0, v[2:3]
	v_add_co_u32_e32 v4, vcc, s81, v8
	s_mov_b32 s26, 0x30000
	s_nop 0
	v_addc_co_u32_e32 v5, vcc, 0, v9, vcc
	v_add_co_u32_e32 v10, vcc, s78, v8
	global_load_dwordx4 v[0:3], v[8:9], off
	s_nop 0
	global_load_dwordx4 v[4:7], v[4:5], off
	v_addc_co_u32_e32 v11, vcc, 0, v9, vcc
	v_add_co_u32_e32 v12, vcc, s26, v8
	s_nop 1
	v_addc_co_u32_e32 v13, vcc, 0, v9, vcc
	global_load_dwordx4 v[8:11], v[10:11], off
	s_nop 0
	global_load_dwordx4 v[12:15], v[12:13], off
.LBB0_106:
	s_and_b64 vcc, exec, s[6:7]
	s_cbranch_vccnz .LBB0_115
	v_and_b32_e32 v17, 60, v17
	v_lshlrev_b32_e32 v19, 4, v20
	s_movk_i32 s26, 0x104
	v_and_b32_e32 v22, 48, v19
	v_mul_lo_u32 v19, v16, s26
	v_lshlrev_b32_e32 v21, 2, v17
	s_add_u32 s6, s20, 0x1e00000
	v_ashrrev_i32_e32 v18, 2, v20
	v_add3_u32 v19, s60, v19, v21
	v_mul_u32_u24_e32 v21, 0x104, v22
	v_and_b32_e32 v20, -4, v20
	s_addc_u32 s7, s21, 0
	v_add3_u32 v20, s60, v21, v20
	v_lshlrev_b32_e32 v144, 1, v22
	s_mov_b32 s98, 0
	s_branch .LBB0_109

.LBB0_109:
	s_cmpk_lt_i32 s3, 0x80
	s_cselect_b64 s[26:27], -1, 0
	s_cmpk_gt_i32 s3, 0x7f
	s_waitcnt lgkmcnt(0)
	s_barrier
	s_cbranch_scc1 .LBB0_111
	v_add_u32_e32 v21, 0x1040, v19
	s_cmp_eq_u32 s98, 0
	s_cbranch_scc1 .Lcvw5_f
	s_waitcnt vmcnt(2)
	s_branch .Lcvw5_d

.LBB0_111:
	s_add_i32 s28, s0, s3
	s_cmpk_gt_i32 s28, 0x7f
	s_cbranch_scc1 .LBB0_113
	s_ashr_i32 s29, s28, 31
	s_lshr_b32 s29, s29, 29
	s_add_i32 s29, s28, s29
	s_and_b32 s30, s29, 0x3fffff8
	s_lshl_b32 s29, s29, 3
	s_sub_i32 s30, s28, s30
	s_andn2_b32 s29, s29, 63
	s_waitcnt vmcnt(2)
	v_or_b32_e32 v0, s29, v17
	v_lshl_add_u32 v2, s30, 6, v16
	v_ashrrev_i32_e32 v1, 31, v0
	v_ashrrev_i32_e32 v3, 31, v2
	v_lshl_add_u64 v[0:1], v[0:1], 2, s[8:9]
	v_lshlrev_b64 v[2:3], 12, v[2:3]
	v_lshl_add_u64 v[8:9], v[0:1], 0, v[2:3]
	v_add_co_u32_e32 v4, vcc, s81, v8
	s_mov_b32 s29, 0x30000
	s_nop 0
	v_addc_co_u32_e32 v5, vcc, 0, v9, vcc
	v_add_co_u32_e32 v10, vcc, s78, v8
	global_load_dwordx4 v[0:3], v[8:9], off
	s_nop 0
	global_load_dwordx4 v[4:7], v[4:5], off
	v_addc_co_u32_e32 v11, vcc, 0, v9, vcc
	v_add_co_u32_e32 v12, vcc, s29, v8
	s_nop 1
	v_addc_co_u32_e32 v13, vcc, 0, v9, vcc
	global_load_dwordx4 v[8:11], v[10:11], off
	s_nop 0
	global_load_dwordx4 v[12:15], v[12:13], off
.LBB0_113:
	s_andn2_b64 vcc, exec, s[26:27]
	s_waitcnt lgkmcnt(0)
	s_barrier
	s_cbranch_vccnz .LBB0_108
	s_ashr_i32 s26, s3, 31
	s_lshr_b32 s26, s26, 29
	ds_read2_b32 v[22:23], v20 offset1:65
	ds_read2_b32 v[24:25], v20 offset0:130 offset1:195
	v_add_u32_e32 v21, 0x400, v20
	s_add_i32 s26, s3, s26
	s_waitcnt lgkmcnt(0)
	v_cvt_pk_bf16_f32 v22, v22, v23
	v_cvt_pk_bf16_f32 v23, v24, v25
	ds_read2_b32 v[24:25], v21 offset0:4 offset1:69
	ds_read2_b32 v[26:27], v21 offset0:134 offset1:199
	v_add_u32_e32 v21, 0x800, v20
	s_and_b32 s27, s26, 0x3fffff8
	s_waitcnt lgkmcnt(0)
	v_cvt_pk_bf16_f32 v24, v24, v25
	v_cvt_pk_bf16_f32 v25, v26, v27
	ds_read2_b32 v[26:27], v21 offset0:8 offset1:73
	ds_read2_b32 v[28:29], v21 offset0:138 offset1:203
	v_add_u32_e32 v21, 0xc00, v20
	s_lshl_b32 s26, s26, 3
	s_waitcnt lgkmcnt(0)
	v_cvt_pk_bf16_f32 v26, v26, v27
	v_cvt_pk_bf16_f32 v27, v28, v29
	ds_read2_b32 v[28:29], v21 offset0:12 offset1:77
	ds_read2_b32 v[30:31], v21 offset0:142 offset1:207
	s_andn2_b32 s26, s26, 63
	s_waitcnt lgkmcnt(0)
	v_cvt_pk_bf16_f32 v28, v28, v29
	v_cvt_pk_bf16_f32 v29, v30, v31
	v_add_u32_e32 v30, s26, v18
	s_sub_i32 s3, s3, s27
	v_ashrrev_i32_e32 v31, 31, v30
	v_lshlrev_b64 v[30:31], 10, v[30:31]
	s_lshl_b32 s26, s3, 6
	v_lshl_add_u64 v[30:31], s[6:7], 0, v[30:31]
	s_ashr_i32 s27, s26, 31
	v_lshl_add_u64 v[30:31], s[26:27], 1, v[30:31]
	v_lshl_add_u64 v[30:31], v[30:31], 0, v[144:145]
	global_store_dwordx4 v[30:31], v[22:25], off
	global_store_dwordx4 v[30:31], v[26:29], off offset:16
	s_branch .LBB0_108
.LBB0_115:
	v_readlane_b32 s36, v254, 22
	v_readlane_b32 s50, v254, 36
	v_readlane_b32 s51, v254, 37
	s_mov_b64 s[2:3], s[50:51]
	s_add_u32 s6, s2, 0x400000
	s_mul_hi_u32 s2, s63, 0xf80
	s_mul_i32 s2, s2, s61
	s_addc_u32 s7, s3, 0
	s_sub_i32 s2, 0xf80, s2
	s_sub_i32 s3, s2, s61
	s_cmp_ge_u32 s2, s61
	s_cselect_b32 s2, s3, s2
	s_sub_i32 s3, s2, s61
	s_cmp_ge_u32 s2, s61
	s_cselect_b32 s2, s3, s2
	s_sub_i32 s2, s62, s2
	s_ashr_i32 s3, s2, 31
	s_abs_i32 s2, s2
	s_mul_hi_u32 s8, s2, s63
	s_mul_i32 s8, s8, s61
	s_sub_i32 s2, s2, s8
	s_sub_i32 s8, s2, s61
	s_cmp_ge_u32 s2, s61
	s_cselect_b32 s2, s8, s2
	s_sub_i32 s8, s2, s61
	s_cmp_ge_u32 s2, s61
	s_cselect_b32 s2, s8, s2
	s_xor_b32 s2, s2, s3
	v_mov_b32_e32 v20, v191
	s_sub_i32 s2, s2, s3
	s_waitcnt vmcnt(0) lgkmcnt(0)
	v_mov_b32_e32 v0, 0
	s_cmpk_gt_i32 s2, 0xff
	v_lshlrev_b32_e32 v17, 2, v20
	v_ashrrev_i32_e32 v16, 4, v20
	v_mov_b32_e32 v1, v0
	v_mov_b32_e32 v2, v0
	v_mov_b32_e32 v3, v0
	v_mov_b32_e32 v4, v0
	v_mov_b32_e32 v5, v0
	v_mov_b32_e32 v6, v0
	v_mov_b32_e32 v7, v0
	v_mov_b32_e32 v8, v0
	v_mov_b32_e32 v9, v0
	v_mov_b32_e32 v10, v0
	v_mov_b32_e32 v11, v0
	v_mov_b32_e32 v12, v0
	v_mov_b32_e32 v13, v0
	v_mov_b32_e32 v14, v0
	v_mov_b32_e32 v15, v0
	v_readlane_b32 s37, v254, 23
	v_readlane_b32 s38, v254, 24
	v_readlane_b32 s39, v254, 25
	v_readlane_b32 s40, v254, 26
	v_readlane_b32 s41, v254, 27
	v_readlane_b32 s42, v254, 28
	v_readlane_b32 s43, v254, 29
	v_readlane_b32 s44, v254, 30
	v_readlane_b32 s45, v254, 31
	v_readlane_b32 s46, v254, 32
	v_readlane_b32 s47, v254, 33
	v_readlane_b32 s48, v254, 34
	v_readlane_b32 s49, v254, 35
	s_cbranch_scc1 .LBB0_117
	s_ashr_i32 s3, s2, 31
	s_lshr_b32 s3, s3, 28
	s_add_i32 s3, s2, s3
	s_and_b32 s8, s3, 0x3fffff0
	s_lshl_b32 s3, s3, 2
	s_sub_i32 s8, s2, s8
	s_andn2_b32 s3, s3, 63
	v_and_or_b32 v0, v17, 60, s3
	v_lshl_add_u32 v2, s8, 6, v16
	v_ashrrev_i32_e32 v1, 31, v0
	v_ashrrev_i32_e32 v3, 31, v2
	v_lshl_add_u64 v[0:1], v[0:1], 2, s[6:7]
	v_lshlrev_b64 v[2:3], 12, v[2:3]
	v_lshl_add_u64 v[8:9], v[0:1], 0, v[2:3]
	v_add_co_u32_e32 v4, vcc, s81, v8
	s_mov_b32 s3, 0x30000
	s_nop 0
	v_addc_co_u32_e32 v5, vcc, 0, v9, vcc
	v_add_co_u32_e32 v10, vcc, s78, v8
	global_load_dwordx4 v[0:3], v[8:9], off
	s_nop 0
	global_load_dwordx4 v[4:7], v[4:5], off
	v_addc_co_u32_e32 v11, vcc, 0, v9, vcc
	v_add_co_u32_e32 v12, vcc, s3, v8
	s_nop 1
	v_addc_co_u32_e32 v13, vcc, 0, v9, vcc
	global_load_dwordx4 v[8:11], v[10:11], off
	s_nop 0
	global_load_dwordx4 v[12:15], v[12:13], off
.LBB0_117:
	s_add_i32 s3, s0, 0xff
	s_sub_i32 s9, 0xffffff01, s0
	s_ashr_i32 s8, s3, 31
	s_max_i32 s3, s3, s9
	s_mul_hi_u32 s9, s3, s63
	s_mul_i32 s26, s9, s61
	s_sub_i32 s3, s3, s26
	s_xor_b32 s8, s8, s66
	s_add_i32 s26, s9, 1
	s_sub_i32 s27, s3, s61
	s_cmp_ge_u32 s3, s61
	s_cselect_b32 s9, s26, s9
	s_cselect_b32 s3, s27, s3
	s_add_i32 s26, s9, 1
	s_cmp_ge_u32 s3, s61
	s_cselect_b32 s3, s26, s9
	s_xor_b32 s3, s3, s8
	s_sub_i32 s67, s3, s8
	s_cmp_gt_i32 s67, 0
	s_cselect_b64 s[8:9], -1, 0
	s_cmp_lt_i32 s67, 1
	s_cbranch_scc1 .LBB0_126
	v_and_b32_e32 v17, 60, v17
	v_lshlrev_b32_e32 v19, 4, v20
	s_movk_i32 s3, 0x104
	v_and_b32_e32 v22, 48, v19
	v_mul_lo_u32 v19, v16, s3
	v_lshlrev_b32_e32 v21, 2, v17
	s_add_u32 s26, s20, 0x1f00000
	v_ashrrev_i32_e32 v18, 2, v20
	v_add3_u32 v19, s60, v19, v21
	v_mul_u32_u24_e32 v21, 0x104, v22
	v_and_b32_e32 v20, -4, v20
	s_addc_u32 s27, s21, 0
	v_add3_u32 v20, s60, v21, v20
	v_lshlrev_b32_e32 v144, 1, v22
	s_mov_b32 s3, s67
	s_mov_b32 s98, 0
	s_branch .LBB0_120

.LBB0_120:
	s_cmpk_lt_i32 s2, 0x100
	s_cselect_b64 s[28:29], -1, 0
	s_cmpk_gt_i32 s2, 0xff
	s_waitcnt lgkmcnt(0)
	s_barrier
	s_cbranch_scc1 .LBB0_122
	v_add_u32_e32 v21, 0x1040, v19
	s_cmp_eq_u32 s98, 0
	s_cbranch_scc1 .Lcvw6_f
	s_waitcnt vmcnt(2)
	s_branch .Lcvw6_d

.LBB0_122:
	s_add_i32 s30, s0, s2
	s_cmpk_gt_i32 s30, 0xff
	s_cbranch_scc1 .LBB0_124
	s_ashr_i32 s31, s30, 31
	s_lshr_b32 s31, s31, 28
	s_add_i32 s31, s30, s31
	s_and_b32 s34, s31, 0x3fffff0
	s_lshl_b32 s31, s31, 2
	s_sub_i32 s34, s30, s34
	s_andn2_b32 s31, s31, 63
	s_waitcnt vmcnt(2)
	v_or_b32_e32 v0, s31, v17
	v_lshl_add_u32 v2, s34, 6, v16
	v_ashrrev_i32_e32 v1, 31, v0
	v_ashrrev_i32_e32 v3, 31, v2
	v_lshl_add_u64 v[0:1], v[0:1], 2, s[6:7]
	v_lshlrev_b64 v[2:3], 12, v[2:3]
	v_lshl_add_u64 v[8:9], v[0:1], 0, v[2:3]
	v_add_co_u32_e32 v4, vcc, s81, v8
	s_mov_b32 s31, 0x30000
	s_nop 0
	v_addc_co_u32_e32 v5, vcc, 0, v9, vcc
	v_add_co_u32_e32 v10, vcc, s78, v8
	global_load_dwordx4 v[0:3], v[8:9], off
	s_nop 0
	global_load_dwordx4 v[4:7], v[4:5], off
	v_addc_co_u32_e32 v11, vcc, 0, v9, vcc
	v_add_co_u32_e32 v12, vcc, s31, v8
	s_nop 1
	v_addc_co_u32_e32 v13, vcc, 0, v9, vcc
	global_load_dwordx4 v[8:11], v[10:11], off
	s_nop 0
	global_load_dwordx4 v[12:15], v[12:13], off
.LBB0_124:
	s_andn2_b64 vcc, exec, s[28:29]
	s_waitcnt lgkmcnt(0)
	s_barrier
	s_cbranch_vccnz .LBB0_119
	s_ashr_i32 s28, s2, 31
	s_lshr_b32 s28, s28, 28
	ds_read2_b32 v[22:23], v20 offset1:65
	ds_read2_b32 v[24:25], v20 offset0:130 offset1:195
	v_add_u32_e32 v21, 0x400, v20
	s_add_i32 s28, s2, s28
	s_waitcnt lgkmcnt(0)
	v_cvt_pk_bf16_f32 v22, v22, v23
	v_cvt_pk_bf16_f32 v23, v24, v25
	ds_read2_b32 v[24:25], v21 offset0:4 offset1:69
	ds_read2_b32 v[26:27], v21 offset0:134 offset1:199
	v_add_u32_e32 v21, 0x800, v20
	s_and_b32 s29, s28, 0x3fffff0
	s_waitcnt lgkmcnt(0)
	v_cvt_pk_bf16_f32 v24, v24, v25
	v_cvt_pk_bf16_f32 v25, v26, v27
	ds_read2_b32 v[26:27], v21 offset0:8 offset1:73
	ds_read2_b32 v[28:29], v21 offset0:138 offset1:203
	v_add_u32_e32 v21, 0xc00, v20
	s_lshl_b32 s28, s28, 2
	s_waitcnt lgkmcnt(0)
	v_cvt_pk_bf16_f32 v26, v26, v27
	v_cvt_pk_bf16_f32 v27, v28, v29
	ds_read2_b32 v[28:29], v21 offset0:12 offset1:77
	ds_read2_b32 v[30:31], v21 offset0:142 offset1:207
	s_andn2_b32 s28, s28, 63
	s_waitcnt lgkmcnt(0)
	v_cvt_pk_bf16_f32 v28, v28, v29
	v_cvt_pk_bf16_f32 v29, v30, v31
	v_add_u32_e32 v30, s28, v18
	s_sub_i32 s2, s2, s29
	v_ashrrev_i32_e32 v31, 31, v30
	v_lshlrev_b64 v[30:31], 11, v[30:31]
	s_lshl_b32 s28, s2, 6
	v_lshl_add_u64 v[30:31], s[26:27], 0, v[30:31]
	s_ashr_i32 s29, s28, 31
	v_lshl_add_u64 v[30:31], s[28:29], 1, v[30:31]
	v_lshl_add_u64 v[30:31], v[30:31], 0, v[144:145]
	global_store_dwordx4 v[30:31], v[22:25], off
	global_store_dwordx4 v[30:31], v[26:29], off offset:16
	s_branch .LBB0_119
.LBB0_126:
	v_readlane_b32 s36, v254, 38
	v_readlane_b32 s40, v254, 42
	v_readlane_b32 s41, v254, 43
	s_mov_b64 s[2:3], s[40:41]
	v_readlane_b32 s37, v254, 39
	s_add_u32 s26, s2, 0x400000
	s_addc_u32 s27, s3, 0
	s_mov_b64 s[34:35], s[36:37]
	s_mul_hi_u32 s2, s63, 0x1080
	s_add_u32 s28, s34, 0x1000
	s_mul_i32 s2, s2, s61
	s_addc_u32 s29, s35, 0
	s_sub_i32 s2, 0x1080, s2
	s_sub_i32 s3, s2, s61
	s_cmp_ge_u32 s2, s61
	s_cselect_b32 s2, s3, s2
	s_sub_i32 s3, s2, s61
	s_cmp_ge_u32 s2, s61
	s_cselect_b32 s2, s3, s2
	s_sub_i32 s2, s62, s2
	s_ashr_i32 s3, s2, 31
	s_abs_i32 s2, s2
	s_mul_hi_u32 s6, s2, s63
	s_mul_i32 s6, s6, s61
	s_sub_i32 s2, s2, s6
	s_sub_i32 s6, s2, s61
	s_cmp_ge_u32 s2, s61
	s_cselect_b32 s2, s6, s2
	s_sub_i32 s6, s2, s61
	s_cmp_ge_u32 s2, s61
	s_cselect_b32 s2, s6, s2
	s_xor_b32 s2, s2, s3
	v_mov_b32_e32 v22, v191
	s_sub_i32 s68, s2, s3
	s_waitcnt vmcnt(0) lgkmcnt(0)
	v_mov_b32_e32 v15, 0
	s_cmpk_gt_i32 s68, 0xff
	v_lshlrev_b32_e32 v19, 2, v22
	v_ashrrev_i32_e32 v18, 4, v22
	v_mov_b32_e32 v14, v15
	v_mov_b32_e32 v13, v15
	v_mov_b32_e32 v12, v15
	v_mov_b32_e32 v11, v15
	v_mov_b32_e32 v10, v15
	v_mov_b32_e32 v9, v15
	v_mov_b32_e32 v8, v15
	v_mov_b32_e32 v7, v15
	v_mov_b32_e32 v6, v15
	v_mov_b32_e32 v5, v15
	v_mov_b32_e32 v4, v15
	v_mov_b32_e32 v3, v15
	v_mov_b32_e32 v2, v15
	v_mov_b32_e32 v1, v15
	v_mov_b32_e32 v0, v15
	v_readlane_b32 s38, v254, 40
	v_readlane_b32 s39, v254, 41
	v_readlane_b32 s42, v254, 44
	v_readlane_b32 s43, v254, 45
	v_readlane_b32 s44, v254, 46
	v_readlane_b32 s45, v254, 47
	v_readlane_b32 s46, v254, 48
	v_readlane_b32 s47, v254, 49
	v_readlane_b32 s48, v254, 50
	v_readlane_b32 s49, v254, 51
	v_readlane_b32 s50, v254, 52
	v_readlane_b32 s51, v254, 53
	s_cbranch_scc1 .LBB0_135
	s_ashr_i32 s2, s68, 31
	s_lshr_b32 s2, s2, 28
	s_add_i32 s2, s68, s2
	s_and_b32 s3, s2, 0x3fffff0
	s_lshl_b32 s2, s2, 2
	s_sub_i32 s3, s68, s3
	s_andn2_b32 s2, s2, 63
	v_and_or_b32 v0, v19, 60, s2
	v_lshl_add_u32 v14, s3, 6, v18
	v_ashrrev_i32_e32 v1, 31, v0
	v_ashrrev_i32_e32 v15, 31, v14
	v_lshl_add_u64 v[12:13], v[0:1], 2, s[26:27]
	v_lshlrev_b64 v[0:1], 12, v[14:15]
	v_lshl_add_u64 v[0:1], v[12:13], 0, v[0:1]
	global_load_dwordx4 v[0:3], v[0:1], off
	s_cmp_lg_u64 s[34:35], 0
	s_cselect_b64 s[2:3], -1, 0
	s_cmp_eq_u64 s[34:35], 0
	s_cbranch_scc1 .LBB0_129
	v_lshl_add_u64 v[4:5], v[14:15], 2, s[28:29]
	global_load_dword v40, v[4:5], off
.LBB0_129:
	v_add_u32_e32 v8, 16, v14
	v_ashrrev_i32_e32 v9, 31, v8
	v_lshlrev_b64 v[4:5], 12, v[8:9]
	v_lshl_add_u64 v[4:5], v[12:13], 0, v[4:5]
	global_load_dwordx4 v[4:7], v[4:5], off
	v_cndmask_b32_e64 v10, 0, 1, s[2:3]
	v_cmp_ne_u32_e64 s[6:7], 1, v10
	s_andn2_b64 vcc, exec, s[2:3]
	s_cbranch_vccnz .LBB0_131
	v_lshl_add_u64 v[8:9], v[8:9], 2, s[28:29]
	global_load_dword v42, v[8:9], off
.LBB0_131:
	v_add_u32_e32 v16, 32, v14
	v_ashrrev_i32_e32 v17, 31, v16
	v_lshlrev_b64 v[8:9], 12, v[16:17]
	v_lshl_add_u64 v[8:9], v[12:13], 0, v[8:9]
	global_load_dwordx4 v[8:11], v[8:9], off
	s_and_b64 vcc, exec, s[6:7]
	s_cbranch_vccnz .LBB0_133
	v_lshl_add_u64 v[16:17], v[16:17], 2, s[28:29]
	global_load_dword v44, v[16:17], off
.LBB0_133:
	v_add_u32_e32 v16, 48, v14
	v_ashrrev_i32_e32 v17, 31, v16
	v_lshlrev_b64 v[14:15], 12, v[16:17]
	v_lshl_add_u64 v[12:13], v[12:13], 0, v[14:15]
	global_load_dwordx4 v[12:15], v[12:13], off
	s_and_b64 vcc, exec, s[6:7]
	s_cbranch_vccnz .LBB0_135
	v_lshl_add_u64 v[16:17], v[16:17], 2, s[28:29]
	global_load_dword v46, v[16:17], off
.LBB0_135:
	v_cndmask_b32_e64 v16, 0, 1, s[8:9]
	v_cmp_ne_u32_e64 s[6:7], 1, v16
	s_andn2_b64 vcc, exec, s[8:9]
	s_cbranch_vccnz .LBB0_151
	s_add_u32 s30, s20, 0x2100000
	v_and_b32_e32 v19, 60, v19
	v_lshlrev_b32_e32 v16, 4, v22
	s_movk_i32 s2, 0x104
	s_addc_u32 s31, s21, 0
	v_and_b32_e32 v16, 48, v16
	v_mul_lo_u32 v17, v18, s2
	v_lshlrev_b32_e32 v21, 2, v19
	s_cmp_lg_u64 s[34:35], 0
	v_ashrrev_i32_e32 v20, 2, v22
	v_add3_u32 v21, s60, v17, v21
	v_mul_u32_u24_e32 v17, 0x104, v16
	v_and_b32_e32 v22, -4, v22
	s_cselect_b64 s[34:35], -1, 0
	v_add3_u32 v22, s60, v17, v22
	v_lshlrev_b32_e32 v144, 1, v16
	s_mov_b32 s2, s67
	s_mov_b32 s98, 0
	s_branch .LBB0_138

.LBB0_138:
	s_cmpk_lt_i32 s68, 0x100
	s_cselect_b64 s[36:37], -1, 0
	s_cmpk_gt_i32 s68, 0xff
	s_waitcnt lgkmcnt(0)
	s_barrier
	s_cbranch_scc1 .LBB0_140
	v_add_u32_e32 v16, 0x1040, v21
	s_cmp_eq_u32 s98, 0
	s_cbranch_scc1 .Lcvw7_f
	s_waitcnt vmcnt(2)
	s_branch .Lcvw7_d

.LBB0_140:
	s_add_i32 s3, s0, s68
	s_cmpk_gt_i32 s3, 0xff
	s_cbranch_scc1 .LBB0_149
	s_ashr_i32 s8, s3, 31
	s_lshr_b32 s8, s8, 28
	s_add_i32 s8, s3, s8
	s_and_b32 s9, s8, 0x3fffff0
	s_lshl_b32 s8, s8, 2
	s_sub_i32 s9, s3, s9
	s_andn2_b32 s8, s8, 63
	s_waitcnt vmcnt(2)
	v_or_b32_e32 v0, s8, v19
	v_lshl_add_u32 v14, s9, 6, v18
	v_ashrrev_i32_e32 v1, 31, v0
	v_ashrrev_i32_e32 v15, 31, v14
	v_lshl_add_u64 v[12:13], v[0:1], 2, s[26:27]
	v_lshlrev_b64 v[0:1], 12, v[14:15]
	v_lshl_add_u64 v[0:1], v[12:13], 0, v[0:1]
	global_load_dwordx4 v[0:3], v[0:1], off
	v_cndmask_b32_e64 v4, 0, 1, s[34:35]
	v_cmp_ne_u32_e64 s[8:9], 1, v4
	s_andn2_b64 vcc, exec, s[34:35]
	s_cbranch_vccnz .LBB0_143
	v_lshl_add_u64 v[4:5], v[14:15], 2, s[28:29]
	global_load_dword v40, v[4:5], off
.LBB0_143:
	v_add_u32_e32 v8, 16, v14
	v_ashrrev_i32_e32 v9, 31, v8
	v_lshlrev_b64 v[4:5], 12, v[8:9]
	v_lshl_add_u64 v[4:5], v[12:13], 0, v[4:5]
	global_load_dwordx4 v[4:7], v[4:5], off
	s_and_b64 vcc, exec, s[8:9]
	s_cbranch_vccnz .LBB0_145
	v_lshl_add_u64 v[8:9], v[8:9], 2, s[28:29]
	global_load_dword v42, v[8:9], off
.LBB0_145:
	v_add_u32_e32 v16, 32, v14
	v_ashrrev_i32_e32 v17, 31, v16
	v_lshlrev_b64 v[8:9], 12, v[16:17]
	v_lshl_add_u64 v[8:9], v[12:13], 0, v[8:9]
	global_load_dwordx4 v[8:11], v[8:9], off
	s_and_b64 vcc, exec, s[8:9]
	s_cbranch_vccnz .LBB0_147
	v_lshl_add_u64 v[16:17], v[16:17], 2, s[28:29]
	global_load_dword v44, v[16:17], off
.LBB0_147:
	v_add_u32_e32 v16, 48, v14
	v_ashrrev_i32_e32 v17, 31, v16
	v_lshlrev_b64 v[14:15], 12, v[16:17]
	v_lshl_add_u64 v[12:13], v[12:13], 0, v[14:15]
	global_load_dwordx4 v[12:15], v[12:13], off
	s_and_b64 vcc, exec, s[8:9]
	s_cbranch_vccnz .LBB0_149
	v_lshl_add_u64 v[16:17], v[16:17], 2, s[28:29]
	global_load_dword v46, v[16:17], off
.LBB0_149:
	s_andn2_b64 vcc, exec, s[36:37]
	s_waitcnt lgkmcnt(0)
	s_barrier
	s_cbranch_vccnz .LBB0_137
	ds_read2_b32 v[16:17], v22 offset1:65
	s_waitcnt lgkmcnt(0)
	v_cvt_pk_bf16_f32 v24, v16, v17
	ds_read2_b32 v[16:17], v22 offset0:130 offset1:195
	v_add_u32_e32 v23, 0x400, v22
	s_waitcnt lgkmcnt(0)
	v_cvt_pk_bf16_f32 v25, v16, v17
	ds_read2_b32 v[16:17], v23 offset0:4 offset1:69
	s_ashr_i32 s8, s68, 31
	s_waitcnt lgkmcnt(0)
	v_cvt_pk_bf16_f32 v26, v16, v17
	ds_read2_b32 v[16:17], v23 offset0:134 offset1:199
	v_add_u32_e32 v23, 0x800, v22
	s_lshr_b32 s8, s8, 28
	s_waitcnt lgkmcnt(0)
	v_cvt_pk_bf16_f32 v27, v16, v17
	ds_read2_b32 v[16:17], v23 offset0:8 offset1:73
	s_add_i32 s8, s68, s8
	s_waitcnt lgkmcnt(0)
	v_cvt_pk_bf16_f32 v28, v16, v17
	ds_read2_b32 v[16:17], v23 offset0:138 offset1:203
	v_add_u32_e32 v23, 0xc00, v22
	s_and_b32 s9, s8, 0x3fffff0
	s_waitcnt lgkmcnt(0)
	v_cvt_pk_bf16_f32 v29, v16, v17
	ds_read2_b32 v[16:17], v23 offset0:12 offset1:77
	s_lshl_b32 s8, s8, 2
	s_waitcnt lgkmcnt(0)
	v_cvt_pk_bf16_f32 v30, v16, v17
	ds_read2_b32 v[16:17], v23 offset0:142 offset1:207
	s_andn2_b32 s8, s8, 63
	s_waitcnt lgkmcnt(0)
	v_cvt_pk_bf16_f32 v31, v16, v17
	v_add_u32_e32 v16, s8, v20
	s_sub_i32 s9, s68, s9
	v_ashrrev_i32_e32 v17, 31, v16
	v_lshlrev_b64 v[16:17], 11, v[16:17]
	s_lshl_b32 s8, s9, 6
	v_lshl_add_u64 v[16:17], s[30:31], 0, v[16:17]
	s_ashr_i32 s9, s8, 31
	v_lshl_add_u64 v[16:17], s[8:9], 1, v[16:17]
	v_lshl_add_u64 v[16:17], v[16:17], 0, v[144:145]
	global_store_dwordx4 v[16:17], v[24:27], off
	global_store_dwordx4 v[16:17], v[28:31], off offset:16
	s_branch .LBB0_137
.LBB0_151:
	v_readlane_b32 s36, v254, 38
	v_readlane_b32 s42, v254, 44
	v_readlane_b32 s43, v254, 45
	s_mov_b64 s[2:3], s[42:43]
	s_add_u32 s8, s2, 0x800000
	s_mul_hi_u32 s2, s63, 0x1180
	s_mul_i32 s2, s2, s61
	s_addc_u32 s9, s3, 0
	s_sub_i32 s2, 0x1180, s2
	s_sub_i32 s3, s2, s61
	s_cmp_ge_u32 s2, s61
	s_cselect_b32 s2, s3, s2
	s_sub_i32 s3, s2, s61
	s_cmp_ge_u32 s2, s61
	s_cselect_b32 s2, s3, s2
	s_sub_i32 s2, s62, s2
	s_ashr_i32 s3, s2, 31
	s_abs_i32 s2, s2
	s_mul_hi_u32 s26, s2, s63
	s_mul_i32 s26, s26, s61
	s_sub_i32 s2, s2, s26
	s_sub_i32 s26, s2, s61
	s_cmp_ge_u32 s2, s61
	s_cselect_b32 s2, s26, s2
	s_sub_i32 s26, s2, s61
	s_cmp_ge_u32 s2, s61
	s_cselect_b32 s2, s26, s2
	s_xor_b32 s2, s2, s3
	v_mov_b32_e32 v20, v191
	s_sub_i32 s2, s2, s3
	s_waitcnt vmcnt(0) lgkmcnt(0)
	v_mov_b32_e32 v0, 0
	s_cmpk_gt_i32 s2, 0x1ff
	v_lshlrev_b32_e32 v17, 2, v20
	v_ashrrev_i32_e32 v16, 4, v20
	v_mov_b32_e32 v1, v0
	v_mov_b32_e32 v2, v0
	v_mov_b32_e32 v3, v0
	v_mov_b32_e32 v4, v0
	v_mov_b32_e32 v5, v0
	v_mov_b32_e32 v6, v0
	v_mov_b32_e32 v7, v0
	v_mov_b32_e32 v8, v0
	v_mov_b32_e32 v9, v0
	v_mov_b32_e32 v10, v0
	v_mov_b32_e32 v11, v0
	v_mov_b32_e32 v12, v0
	v_mov_b32_e32 v13, v0
	v_mov_b32_e32 v14, v0
	v_mov_b32_e32 v15, v0
	v_readlane_b32 s37, v254, 39
	v_readlane_b32 s38, v254, 40
	v_readlane_b32 s39, v254, 41
	v_readlane_b32 s40, v254, 42
	v_readlane_b32 s41, v254, 43
	v_readlane_b32 s44, v254, 46
	v_readlane_b32 s45, v254, 47
	v_readlane_b32 s46, v254, 48
	v_readlane_b32 s47, v254, 49
	v_readlane_b32 s48, v254, 50
	v_readlane_b32 s49, v254, 51
	v_readlane_b32 s50, v254, 52
	v_readlane_b32 s51, v254, 53
	s_cbranch_scc1 .LBB0_153
	s_ashr_i32 s3, s2, 31
	s_lshr_b32 s3, s3, 28
	s_add_i32 s3, s2, s3
	s_and_b32 s26, s3, 0x3fffff0
	s_lshl_b32 s3, s3, 2
	s_sub_i32 s26, s2, s26
	s_andn2_b32 s3, s3, 63
	v_and_or_b32 v0, v17, 60, s3
	v_lshl_add_u32 v2, s26, 6, v16
	v_ashrrev_i32_e32 v1, 31, v0
	v_ashrrev_i32_e32 v3, 31, v2
	v_lshl_add_u64 v[0:1], v[0:1], 2, s[8:9]
	v_lshlrev_b64 v[2:3], 13, v[2:3]
	v_lshl_add_u64 v[8:9], v[0:1], 0, v[2:3]
	v_add_co_u32_e32 v4, vcc, s78, v8
	s_mov_b32 s3, 0x40000
	s_nop 0
	v_addc_co_u32_e32 v5, vcc, 0, v9, vcc
	v_add_co_u32_e32 v10, vcc, s3, v8
	s_mov_b32 s3, 0x60000
	s_nop 0
	v_addc_co_u32_e32 v11, vcc, 0, v9, vcc
	v_add_co_u32_e32 v12, vcc, s3, v8
	global_load_dwordx4 v[0:3], v[8:9], off
	s_nop 0
	global_load_dwordx4 v[4:7], v[4:5], off
	v_addc_co_u32_e32 v13, vcc, 0, v9, vcc
	global_load_dwordx4 v[8:11], v[10:11], off
	s_nop 0
	global_load_dwordx4 v[12:15], v[12:13], off
.LBB0_153:
	s_add_i32 s3, s0, 0x1ff
	s_sub_i32 s27, 0xfffffe01, s0
	s_ashr_i32 s26, s3, 31
	s_max_i32 s3, s3, s27
	s_mul_hi_u32 s27, s3, s63
	s_mul_i32 s28, s27, s61
	s_sub_i32 s3, s3, s28
	s_xor_b32 s26, s26, s66
	s_add_i32 s28, s27, 1
	s_sub_i32 s29, s3, s61
	s_cmp_ge_u32 s3, s61
	s_cselect_b32 s27, s28, s27
	s_cselect_b32 s3, s29, s3
	s_add_i32 s28, s27, 1
	s_cmp_ge_u32 s3, s61
	s_cselect_b32 s3, s28, s27
	s_xor_b32 s3, s3, s26
	s_sub_i32 s3, s3, s26
	v_readlane_b32 s74, v255, 24
	s_cmp_lt_i32 s3, 1
	v_readlane_b32 s75, v255, 25
	s_cbranch_scc1 .LBB0_162
	v_and_b32_e32 v17, 60, v17
	v_lshlrev_b32_e32 v19, 4, v20
	s_movk_i32 s28, 0x104
	v_and_b32_e32 v22, 48, v19
	v_mul_lo_u32 v19, v16, s28
	v_lshlrev_b32_e32 v21, 2, v17
	s_add_u32 s26, s20, 0x2300000
	v_ashrrev_i32_e32 v18, 2, v20
	v_add3_u32 v19, s60, v19, v21
	v_mul_u32_u24_e32 v21, 0x104, v22
	v_and_b32_e32 v20, -4, v20
	s_addc_u32 s27, s21, 0
	v_add3_u32 v20, s60, v21, v20
	v_lshlrev_b32_e32 v144, 1, v22
	s_mov_b32 s98, 0
	s_branch .LBB0_156

.LBB0_156:
	s_cmpk_lt_i32 s2, 0x200
	s_cselect_b64 s[28:29], -1, 0
	s_cmpk_gt_i32 s2, 0x1ff
	s_waitcnt lgkmcnt(0)
	s_barrier
	s_cbranch_scc1 .LBB0_158
	v_add_u32_e32 v21, 0x1040, v19
	s_cmp_eq_u32 s98, 0
	s_cbranch_scc1 .Lcvw8_f
	s_waitcnt vmcnt(2)
	s_branch .Lcvw8_d

.LBB0_158:
	s_add_i32 s30, s0, s2
	s_cmpk_gt_i32 s30, 0x1ff
	s_cbranch_scc1 .LBB0_160
	s_ashr_i32 s31, s30, 31
	s_lshr_b32 s31, s31, 28
	s_add_i32 s31, s30, s31
	s_and_b32 s34, s31, 0x3fffff0
	s_lshl_b32 s31, s31, 2
	s_sub_i32 s34, s30, s34
	s_andn2_b32 s31, s31, 63
	s_waitcnt vmcnt(2)
	v_or_b32_e32 v0, s31, v17
	v_lshl_add_u32 v2, s34, 6, v16
	v_ashrrev_i32_e32 v1, 31, v0
	v_ashrrev_i32_e32 v3, 31, v2
	v_lshl_add_u64 v[0:1], v[0:1], 2, s[8:9]
	v_lshlrev_b64 v[2:3], 13, v[2:3]
	v_lshl_add_u64 v[8:9], v[0:1], 0, v[2:3]
	v_add_co_u32_e32 v4, vcc, s78, v8
	s_mov_b32 s31, 0x40000
	s_nop 0
	v_addc_co_u32_e32 v5, vcc, 0, v9, vcc
	v_add_co_u32_e32 v10, vcc, s31, v8
	s_mov_b32 s31, 0x60000
	s_nop 0
	v_addc_co_u32_e32 v11, vcc, 0, v9, vcc
	v_add_co_u32_e32 v12, vcc, s31, v8
	global_load_dwordx4 v[0:3], v[8:9], off
	s_nop 0
	global_load_dwordx4 v[4:7], v[4:5], off
	v_addc_co_u32_e32 v13, vcc, 0, v9, vcc
	global_load_dwordx4 v[8:11], v[10:11], off
	s_nop 0
	global_load_dwordx4 v[12:15], v[12:13], off

.LBB0_162:
	v_readlane_b32 s36, v254, 38
	v_readlane_b32 s44, v254, 46
	v_readlane_b32 s45, v254, 47
	s_mov_b64 s[2:3], s[44:45]
	s_add_u32 s8, s2, 0x400000
	s_mul_hi_u32 s2, s63, 0x1380
	s_mul_i32 s2, s2, s61
	s_addc_u32 s9, s3, 0
	s_sub_i32 s2, 0x1380, s2
	s_sub_i32 s3, s2, s61
	s_cmp_ge_u32 s2, s61
	s_cselect_b32 s2, s3, s2
	s_sub_i32 s3, s2, s61
	s_cmp_ge_u32 s2, s61
	s_cselect_b32 s2, s3, s2
	s_sub_i32 s2, s62, s2
	s_ashr_i32 s3, s2, 31
	s_abs_i32 s2, s2
	s_mul_hi_u32 s26, s2, s63
	s_mul_i32 s26, s26, s61
	s_sub_i32 s2, s2, s26
	s_sub_i32 s26, s2, s61
	s_cmp_ge_u32 s2, s61
	s_cselect_b32 s2, s26, s2
	s_sub_i32 s26, s2, s61
	s_cmp_ge_u32 s2, s61
	s_cselect_b32 s2, s26, s2
	s_xor_b32 s2, s2, s3
	v_mov_b32_e32 v20, v191
	s_sub_i32 s2, s2, s3
	s_waitcnt vmcnt(0) lgkmcnt(0)
	v_mov_b32_e32 v0, 0
	s_cmpk_gt_i32 s2, 0xff
	v_lshlrev_b32_e32 v17, 2, v20
	v_ashrrev_i32_e32 v16, 4, v20
	v_mov_b32_e32 v1, v0
	v_mov_b32_e32 v2, v0
	v_mov_b32_e32 v3, v0
	v_mov_b32_e32 v4, v0
	v_mov_b32_e32 v5, v0
	v_mov_b32_e32 v6, v0
	v_mov_b32_e32 v7, v0
	v_mov_b32_e32 v8, v0
	v_mov_b32_e32 v9, v0
	v_mov_b32_e32 v10, v0
	v_mov_b32_e32 v11, v0
	v_mov_b32_e32 v12, v0
	v_mov_b32_e32 v13, v0
	v_mov_b32_e32 v14, v0
	v_mov_b32_e32 v15, v0
	v_readlane_b32 s37, v254, 39
	v_readlane_b32 s38, v254, 40
	v_readlane_b32 s39, v254, 41
	v_readlane_b32 s40, v254, 42
	v_readlane_b32 s41, v254, 43
	v_readlane_b32 s42, v254, 44
	v_readlane_b32 s43, v254, 45
	v_readlane_b32 s46, v254, 48
	v_readlane_b32 s47, v254, 49
	v_readlane_b32 s48, v254, 50
	v_readlane_b32 s49, v254, 51
	v_readlane_b32 s50, v254, 52
	v_readlane_b32 s51, v254, 53
	s_cbranch_scc1 .LBB0_164
	s_ashr_i32 s3, s2, 31
	s_lshr_b32 s3, s3, 28
	s_add_i32 s3, s2, s3
	s_and_b32 s26, s3, 0x3fffff0
	s_lshl_b32 s3, s3, 2
	s_sub_i32 s26, s2, s26
	s_andn2_b32 s3, s3, 63
	v_and_or_b32 v0, v17, 60, s3
	v_lshl_add_u32 v2, s26, 6, v16
	v_ashrrev_i32_e32 v1, 31, v0
	v_ashrrev_i32_e32 v3, 31, v2
	v_lshl_add_u64 v[0:1], v[0:1], 2, s[8:9]
	v_lshlrev_b64 v[2:3], 12, v[2:3]
	v_lshl_add_u64 v[8:9], v[0:1], 0, v[2:3]
	v_add_co_u32_e32 v4, vcc, s81, v8
	s_mov_b32 s3, 0x30000
	s_nop 0
	v_addc_co_u32_e32 v5, vcc, 0, v9, vcc
	v_add_co_u32_e32 v10, vcc, s78, v8
	global_load_dwordx4 v[0:3], v[8:9], off
	s_nop 0
	global_load_dwordx4 v[4:7], v[4:5], off
	v_addc_co_u32_e32 v11, vcc, 0, v9, vcc
	v_add_co_u32_e32 v12, vcc, s3, v8
	s_nop 1
	v_addc_co_u32_e32 v13, vcc, 0, v9, vcc
	global_load_dwordx4 v[8:11], v[10:11], off
	s_nop 0
	global_load_dwordx4 v[12:15], v[12:13], off
.LBB0_164:
	s_and_b64 vcc, exec, s[6:7]
	s_cbranch_vccnz .LBB0_173
	v_and_b32_e32 v17, 60, v17
	v_lshlrev_b32_e32 v19, 4, v20
	s_movk_i32 s3, 0x104
	v_and_b32_e32 v22, 48, v19
	v_mul_lo_u32 v19, v16, s3
	v_lshlrev_b32_e32 v21, 2, v17
	s_add_u32 s6, s20, 0x2700000
	v_ashrrev_i32_e32 v18, 2, v20
	v_add3_u32 v19, s60, v19, v21
	v_mul_u32_u24_e32 v21, 0x104, v22
	v_and_b32_e32 v20, -4, v20
	s_addc_u32 s7, s21, 0
	v_add3_u32 v20, s60, v21, v20
	v_lshlrev_b32_e32 v144, 1, v22
	s_mov_b32 s98, 0
	s_branch .LBB0_167

.LBB0_167:
	s_cmpk_lt_i32 s2, 0x100
	s_cselect_b64 s[26:27], -1, 0
	s_cmpk_gt_i32 s2, 0xff
	s_waitcnt lgkmcnt(0)
	s_barrier
	s_cbranch_scc1 .LBB0_169
	v_add_u32_e32 v21, 0x1040, v19
	s_cmp_eq_u32 s98, 0
	s_cbranch_scc1 .Lcvw9_f
	s_waitcnt vmcnt(2)
	s_branch .Lcvw9_d

.LBB0_169:
	s_add_i32 s3, s0, s2
	s_cmpk_gt_i32 s3, 0xff
	s_cbranch_scc1 .LBB0_171
	s_ashr_i32 s28, s3, 31
	s_lshr_b32 s28, s28, 28
	s_add_i32 s28, s3, s28
	s_and_b32 s29, s28, 0x3fffff0
	s_lshl_b32 s28, s28, 2
	s_sub_i32 s29, s3, s29
	s_andn2_b32 s28, s28, 63
	s_waitcnt vmcnt(2)
	v_or_b32_e32 v0, s28, v17
	v_lshl_add_u32 v2, s29, 6, v16
	v_ashrrev_i32_e32 v1, 31, v0
	v_ashrrev_i32_e32 v3, 31, v2
	v_lshl_add_u64 v[0:1], v[0:1], 2, s[8:9]
	v_lshlrev_b64 v[2:3], 12, v[2:3]
	v_lshl_add_u64 v[8:9], v[0:1], 0, v[2:3]
	v_add_co_u32_e32 v4, vcc, s81, v8
	s_mov_b32 s28, 0x30000
	s_nop 0
	v_addc_co_u32_e32 v5, vcc, 0, v9, vcc
	v_add_co_u32_e32 v10, vcc, s78, v8
	global_load_dwordx4 v[0:3], v[8:9], off
	s_nop 0
	global_load_dwordx4 v[4:7], v[4:5], off
	v_addc_co_u32_e32 v11, vcc, 0, v9, vcc
	v_add_co_u32_e32 v12, vcc, s28, v8
	s_nop 1
	v_addc_co_u32_e32 v13, vcc, 0, v9, vcc
	global_load_dwordx4 v[8:11], v[10:11], off
	s_nop 0
	global_load_dwordx4 v[12:15], v[12:13], off
.LBB0_171:
	s_andn2_b64 vcc, exec, s[26:27]
	s_waitcnt lgkmcnt(0)
	s_barrier
	s_cbranch_vccnz .LBB0_166
	s_ashr_i32 s26, s2, 31
	s_lshr_b32 s26, s26, 28
	ds_read2_b32 v[22:23], v20 offset1:65
	ds_read2_b32 v[24:25], v20 offset0:130 offset1:195
	v_add_u32_e32 v21, 0x400, v20
	s_add_i32 s26, s2, s26
	s_waitcnt lgkmcnt(0)
	v_cvt_pk_bf16_f32 v22, v22, v23
	v_cvt_pk_bf16_f32 v23, v24, v25
	ds_read2_b32 v[24:25], v21 offset0:4 offset1:69
	ds_read2_b32 v[26:27], v21 offset0:134 offset1:199
	v_add_u32_e32 v21, 0x800, v20
	s_and_b32 s27, s26, 0x3fffff0
	s_waitcnt lgkmcnt(0)
	v_cvt_pk_bf16_f32 v24, v24, v25
	v_cvt_pk_bf16_f32 v25, v26, v27
	ds_read2_b32 v[26:27], v21 offset0:8 offset1:73
	ds_read2_b32 v[28:29], v21 offset0:138 offset1:203
	v_add_u32_e32 v21, 0xc00, v20
	s_lshl_b32 s26, s26, 2
	s_waitcnt lgkmcnt(0)
	v_cvt_pk_bf16_f32 v26, v26, v27
	v_cvt_pk_bf16_f32 v27, v28, v29
	ds_read2_b32 v[28:29], v21 offset0:12 offset1:77
	ds_read2_b32 v[30:31], v21 offset0:142 offset1:207
	s_andn2_b32 s26, s26, 63
	s_waitcnt lgkmcnt(0)
	v_cvt_pk_bf16_f32 v28, v28, v29
	v_cvt_pk_bf16_f32 v29, v30, v31
	v_add_u32_e32 v30, s26, v18
	s_sub_i32 s2, s2, s27
	v_ashrrev_i32_e32 v31, 31, v30
	v_lshlrev_b64 v[30:31], 11, v[30:31]
	s_lshl_b32 s26, s2, 6
	v_lshl_add_u64 v[30:31], s[6:7], 0, v[30:31]
	s_ashr_i32 s27, s26, 31
	v_lshl_add_u64 v[30:31], s[26:27], 1, v[30:31]
	v_lshl_add_u64 v[30:31], v[30:31], 0, v[144:145]
	global_store_dwordx4 v[30:31], v[22:25], off
	global_store_dwordx4 v[30:31], v[26:29], off offset:16
	s_branch .LBB0_166
.LBB0_173:
	v_readlane_b32 s36, v254, 38
	v_readlane_b32 s48, v254, 50
	v_readlane_b32 s49, v254, 51
	s_mov_b64 s[2:3], s[48:49]
	v_readlane_b32 s46, v254, 48
	v_readlane_b32 s47, v254, 49
	s_add_u32 s26, s2, 0x1600000
	s_addc_u32 s27, s3, 0
	s_mov_b64 s[8:9], s[46:47]
	s_mul_hi_u32 s2, s63, 0x1480
	s_add_u32 s28, s8, 0x1000
	s_mul_i32 s2, s2, s61
	s_addc_u32 s29, s9, 0
	s_sub_i32 s2, 0x1480, s2
	s_sub_i32 s3, s2, s61
	s_cmp_ge_u32 s2, s61
	s_cselect_b32 s2, s3, s2
	s_sub_i32 s3, s2, s61
	s_cmp_ge_u32 s2, s61
	s_cselect_b32 s2, s3, s2
	s_sub_i32 s2, s62, s2
	s_ashr_i32 s3, s2, 31
	s_abs_i32 s2, s2
	s_mul_hi_u32 s6, s2, s63
	s_mul_i32 s6, s6, s61
	s_sub_i32 s2, s2, s6
	s_sub_i32 s6, s2, s61
	s_cmp_ge_u32 s2, s61
	s_cselect_b32 s2, s6, s2
	s_sub_i32 s6, s2, s61
	s_cmp_ge_u32 s2, s61
	s_cselect_b32 s2, s6, s2
	v_mov_b32_e32 v24, v191
	s_xor_b32 s2, s2, s3
	s_sub_i32 s36, s2, s3
	s_waitcnt vmcnt(0) lgkmcnt(0)
	v_mov_b32_e32 v15, 0
	v_lshlrev_b32_e32 v20, 2, v24
	s_cmpk_gt_i32 s36, 0x57f
	v_ashrrev_i32_e32 v18, 4, v24
	v_and_b32_e32 v19, 28, v20
	v_mov_b32_e32 v14, v15
	v_mov_b32_e32 v13, v15
	v_mov_b32_e32 v12, v15
	v_mov_b32_e32 v11, v15
	v_mov_b32_e32 v10, v15
	v_mov_b32_e32 v9, v15
	v_mov_b32_e32 v8, v15
	v_mov_b32_e32 v7, v15
	v_mov_b32_e32 v6, v15
	v_mov_b32_e32 v5, v15
	v_mov_b32_e32 v4, v15
	v_mov_b32_e32 v3, v15
	v_mov_b32_e32 v2, v15
	v_mov_b32_e32 v1, v15
	v_mov_b32_e32 v0, v15
	v_readlane_b32 s37, v254, 39
	v_readlane_b32 s38, v254, 40
	v_readlane_b32 s39, v254, 41
	v_readlane_b32 s40, v254, 42
	v_readlane_b32 s41, v254, 43
	v_readlane_b32 s42, v254, 44
	v_readlane_b32 s43, v254, 45
	v_readlane_b32 s44, v254, 46
	v_readlane_b32 s45, v254, 47
	v_readlane_b32 s50, v254, 52
	v_readlane_b32 s51, v254, 53
	s_cbranch_scc1 .LBB0_182
	s_ashr_i32 s2, s36, 31
	s_lshr_b32 s2, s2, 28
	s_add_i32 s2, s36, s2
	s_and_b32 s3, s2, 0x3fffff0
	s_lshl_b32 s2, s2, 2
	s_andn2_b32 s2, s2, 63
	v_and_or_b32 v0, v20, 32, s2
	v_ashrrev_i32_e32 v0, 1, v0
	s_movk_i32 s2, 0xaf0
	v_or_b32_e32 v1, v0, v19
	v_add3_u32 v0, v19, v0, s2
	v_cmp_gt_u32_e32 vcc, 16, v19
	s_sub_i32 s3, s36, s3
	v_lshl_add_u32 v12, s3, 6, v18
	v_cndmask_b32_e32 v0, v0, v1, vcc
	v_ashrrev_i32_e32 v1, 31, v0
	v_lshl_add_u64 v[14:15], v[0:1], 2, s[26:27]
	v_mad_i64_i32 v[0:1], s[2:3], v12, s85, v[14:15]
	global_load_dwordx4 v[0:3], v[0:1], off
	s_cmp_lg_u64 s[8:9], 0
	s_cselect_b64 s[2:3], -1, 0
	s_cmp_eq_u64 s[8:9], 0
	v_ashrrev_i32_e32 v13, 31, v12
	s_cbranch_scc1 .LBB0_176
	v_lshl_add_u64 v[4:5], v[12:13], 2, s[28:29]
	global_load_dword v40, v[4:5], off
.LBB0_176:
	v_add_u32_e32 v8, 16, v12
	v_mad_i64_i32 v[4:5], s[6:7], v8, s85, v[14:15]
	global_load_dwordx4 v[4:7], v[4:5], off
	v_cndmask_b32_e64 v9, 0, 1, s[2:3]
	v_cmp_ne_u32_e64 s[6:7], 1, v9
	s_andn2_b64 vcc, exec, s[2:3]
	s_cbranch_vccnz .LBB0_178
	v_ashrrev_i32_e32 v9, 31, v8
	v_lshl_add_u64 v[8:9], v[8:9], 2, s[28:29]
	global_load_dword v42, v[8:9], off
.LBB0_178:
	v_add_u32_e32 v16, 32, v12
	v_mad_i64_i32 v[8:9], s[2:3], v16, s85, v[14:15]
	global_load_dwordx4 v[8:11], v[8:9], off
	s_and_b64 vcc, exec, s[6:7]
	s_cbranch_vccnz .LBB0_180
	v_ashrrev_i32_e32 v17, 31, v16
	v_lshl_add_u64 v[16:17], v[16:17], 2, s[28:29]
	global_load_dword v44, v[16:17], off
.LBB0_180:
	v_add_u32_e32 v16, 48, v12
	v_mad_i64_i32 v[12:13], s[2:3], v16, s85, v[14:15]
	global_load_dwordx4 v[12:15], v[12:13], off
	s_and_b64 vcc, exec, s[6:7]
	s_cbranch_vccnz .LBB0_182
	v_ashrrev_i32_e32 v17, 31, v16
	v_lshl_add_u64 v[16:17], v[16:17], 2, s[28:29]
	global_load_dword v46, v[16:17], off
.LBB0_182:
	s_andn2_b64 vcc, exec, s[22:23]
	s_cbranch_vccnz .LBB0_198
	s_add_u32 s22, s20, 0x2900000
	v_and_b32_e32 v20, 60, v20
	v_lshlrev_b32_e32 v16, 4, v24
	s_movk_i32 s2, 0x104
	s_addc_u32 s23, s21, 0
	v_and_b32_e32 v16, 48, v16
	v_mul_lo_u32 v17, v18, s2
	v_lshlrev_b32_e32 v23, 2, v20
	s_cmp_lg_u64 s[8:9], 0
	v_ashrrev_i32_e32 v22, 2, v24
	v_add3_u32 v23, s60, v17, v23
	v_mul_u32_u24_e32 v17, 0x104, v16
	v_and_b32_e32 v24, -4, v24
	v_cmp_gt_u32_e64 s[6:7], 16, v19
	v_add_u32_e32 v21, 0xaf0, v19
	s_cselect_b64 s[30:31], -1, 0
	v_add3_u32 v24, s60, v17, v24
	v_lshlrev_b32_e32 v144, 1, v16
	s_mov_b32 s98, 0
	s_branch .LBB0_185

.LBB0_185:
	s_cmpk_lt_i32 s36, 0x580
	s_cselect_b64 s[34:35], -1, 0
	s_cmpk_gt_i32 s36, 0x57f
	s_waitcnt lgkmcnt(0)
	s_barrier
	s_cbranch_scc1 .LBB0_187
	v_add_u32_e32 v16, 0x1040, v23
	s_cmp_eq_u32 s98, 0
	s_cbranch_scc1 .Lcvw10_f
	s_waitcnt vmcnt(2)
	s_branch .Lcvw10_d

.LBB0_187:
	s_add_i32 s2, s0, s36
	s_cmpk_gt_i32 s2, 0x57f
	s_cbranch_scc1 .LBB0_196
	s_ashr_i32 s3, s2, 31
	s_lshr_b32 s3, s3, 28
	s_add_i32 s3, s2, s3
	s_and_b32 s8, s3, 0x3fffff0
	s_lshl_b32 s3, s3, 2
	s_andn2_b32 s3, s3, 63
	s_waitcnt vmcnt(2)
	v_or_b32_e32 v0, s3, v20
	v_ashrrev_i32_e32 v0, 1, v0
	v_and_b32_e32 v0, -16, v0
	v_or_b32_e32 v1, v0, v19
	v_add_u32_e32 v0, v21, v0
	v_cndmask_b32_e64 v0, v0, v1, s[6:7]
	s_sub_i32 s8, s2, s8
	v_ashrrev_i32_e32 v1, 31, v0
	v_lshl_add_u32 v12, s8, 6, v18
	v_lshl_add_u64 v[14:15], v[0:1], 2, s[26:27]
	v_mad_i64_i32 v[0:1], s[8:9], v12, s85, v[14:15]
	global_load_dwordx4 v[0:3], v[0:1], off
	v_cndmask_b32_e64 v4, 0, 1, s[30:31]
	v_ashrrev_i32_e32 v13, 31, v12
	v_cmp_ne_u32_e64 s[8:9], 1, v4
	s_andn2_b64 vcc, exec, s[30:31]
	s_cbranch_vccnz .LBB0_190
	v_lshl_add_u64 v[4:5], v[12:13], 2, s[28:29]
	global_load_dword v40, v[4:5], off
.LBB0_190:
	v_add_u32_e32 v8, 16, v12
	v_mad_i64_i32 v[4:5], s[66:67], v8, s85, v[14:15]
	global_load_dwordx4 v[4:7], v[4:5], off
	s_and_b64 vcc, exec, s[8:9]
	s_cbranch_vccnz .LBB0_192
	v_ashrrev_i32_e32 v9, 31, v8
	v_lshl_add_u64 v[8:9], v[8:9], 2, s[28:29]
	global_load_dword v42, v[8:9], off
.LBB0_192:
	v_add_u32_e32 v16, 32, v12
	v_mad_i64_i32 v[8:9], s[66:67], v16, s85, v[14:15]
	global_load_dwordx4 v[8:11], v[8:9], off
	s_and_b64 vcc, exec, s[8:9]
	s_cbranch_vccnz .LBB0_194
	v_ashrrev_i32_e32 v17, 31, v16
	v_lshl_add_u64 v[16:17], v[16:17], 2, s[28:29]
	global_load_dword v44, v[16:17], off
.LBB0_194:
	v_add_u32_e32 v16, 48, v12
	v_mad_i64_i32 v[12:13], s[66:67], v16, s85, v[14:15]
	global_load_dwordx4 v[12:15], v[12:13], off
	s_and_b64 vcc, exec, s[8:9]
	s_cbranch_vccnz .LBB0_196
	v_ashrrev_i32_e32 v17, 31, v16
	v_lshl_add_u64 v[16:17], v[16:17], 2, s[28:29]
	global_load_dword v46, v[16:17], off
.LBB0_196:
	s_andn2_b64 vcc, exec, s[34:35]
	s_waitcnt lgkmcnt(0)
	s_barrier
	s_cbranch_vccnz .LBB0_184
	ds_read2_b32 v[16:17], v24 offset1:65
	s_waitcnt lgkmcnt(0)
	v_cvt_pk_bf16_f32 v26, v16, v17
	ds_read2_b32 v[16:17], v24 offset0:130 offset1:195
	v_add_u32_e32 v25, 0x400, v24
	s_waitcnt lgkmcnt(0)
	v_cvt_pk_bf16_f32 v27, v16, v17
	ds_read2_b32 v[16:17], v25 offset0:4 offset1:69
	s_ashr_i32 s3, s36, 31
	s_waitcnt lgkmcnt(0)
	v_cvt_pk_bf16_f32 v28, v16, v17
	ds_read2_b32 v[16:17], v25 offset0:134 offset1:199
	v_add_u32_e32 v25, 0x800, v24
	s_lshr_b32 s3, s3, 28
	s_waitcnt lgkmcnt(0)
	v_cvt_pk_bf16_f32 v29, v16, v17
	ds_read2_b32 v[16:17], v25 offset0:8 offset1:73
	s_add_i32 s3, s36, s3
	s_waitcnt lgkmcnt(0)
	v_cvt_pk_bf16_f32 v30, v16, v17
	ds_read2_b32 v[16:17], v25 offset0:138 offset1:203
	v_add_u32_e32 v25, 0xc00, v24
	s_and_b32 s8, s3, 0x3fffff0
	s_waitcnt lgkmcnt(0)
	v_cvt_pk_bf16_f32 v31, v16, v17
	ds_read2_b32 v[16:17], v25 offset0:12 offset1:77
	s_lshl_b32 s3, s3, 2
	s_waitcnt lgkmcnt(0)
	v_cvt_pk_bf16_f32 v32, v16, v17
	ds_read2_b32 v[16:17], v25 offset0:142 offset1:207
	s_andn2_b32 s3, s3, 63
	s_waitcnt lgkmcnt(0)
	v_cvt_pk_bf16_f32 v33, v16, v17
	v_add_u32_e32 v16, s3, v22
	s_sub_i32 s8, s36, s8
	v_ashrrev_i32_e32 v17, 31, v16
	v_lshlrev_b64 v[16:17], 11, v[16:17]
	s_lshl_b32 s8, s8, 6
	v_lshl_add_u64 v[16:17], s[22:23], 0, v[16:17]
	s_ashr_i32 s9, s8, 31
	v_lshl_add_u64 v[16:17], s[8:9], 1, v[16:17]
	v_lshl_add_u64 v[16:17], v[16:17], 0, v[144:145]
	global_store_dwordx4 v[16:17], v[26:29], off
	global_store_dwordx4 v[16:17], v[30:33], off offset:16
	s_branch .LBB0_184
.LBB0_198:
	v_readlane_b32 s36, v254, 38
	v_readlane_b32 s50, v254, 52
	v_readlane_b32 s51, v254, 53
	s_mov_b64 s[2:3], s[50:51]
	s_add_u32 s6, s2, 0xb00000
	s_mul_hi_u32 s2, s63, 0x1a00
	s_mul_i32 s2, s2, s61
	s_addc_u32 s7, s3, 0
	s_sub_i32 s2, 0x1a00, s2
	s_sub_i32 s3, s2, s61
	s_cmp_ge_u32 s2, s61
	s_cselect_b32 s2, s3, s2
	s_sub_i32 s3, s2, s61
	s_cmp_ge_u32 s2, s61
	s_cselect_b32 s2, s3, s2
	s_sub_i32 s2, s62, s2
	s_ashr_i32 s3, s2, 31
	s_abs_i32 s2, s2
	s_mul_hi_u32 s8, s2, s63
	s_mul_i32 s8, s8, s61
	s_sub_i32 s2, s2, s8
	s_sub_i32 s8, s2, s61
	s_cmp_ge_u32 s2, s61
	s_cselect_b32 s2, s8, s2
	s_sub_i32 s8, s2, s61
	s_cmp_ge_u32 s2, s61
	s_cselect_b32 s2, s8, s2
	v_mov_b32_e32 v20, v191
	s_xor_b32 s2, s2, s3
	s_sub_i32 s2, s2, s3
	s_waitcnt vmcnt(0) lgkmcnt(0)
	v_mov_b32_e32 v0, 0
	v_lshlrev_b32_e32 v1, 2, v20
	s_cmpk_gt_i32 s2, 0x2bf
	v_ashrrev_i32_e32 v16, 4, v20
	v_and_b32_e32 v17, 60, v1
	v_mov_b32_e32 v1, v0
	v_mov_b32_e32 v2, v0
	v_mov_b32_e32 v3, v0
	v_mov_b32_e32 v4, v0
	v_mov_b32_e32 v5, v0
	v_mov_b32_e32 v6, v0
	v_mov_b32_e32 v7, v0
	v_mov_b32_e32 v8, v0
	v_mov_b32_e32 v9, v0
	v_mov_b32_e32 v10, v0
	v_mov_b32_e32 v11, v0
	v_mov_b32_e32 v12, v0
	v_mov_b32_e32 v13, v0
	v_mov_b32_e32 v14, v0
	v_mov_b32_e32 v15, v0
	v_readlane_b32 s37, v254, 39
	v_readlane_b32 s38, v254, 40
	v_readlane_b32 s39, v254, 41
	v_readlane_b32 s40, v254, 42
	v_readlane_b32 s41, v254, 43
	v_readlane_b32 s42, v254, 44
	v_readlane_b32 s43, v254, 45
	v_readlane_b32 s44, v254, 46
	v_readlane_b32 s45, v254, 47
	v_readlane_b32 s46, v254, 48
	v_readlane_b32 s47, v254, 49
	v_readlane_b32 s48, v254, 50
	v_readlane_b32 s49, v254, 51
	s_cbranch_scc1 .LBB0_200
	s_mul_hi_i32 s3, s2, 0x2e8ba2e9
	s_lshr_b32 s8, s3, 31
	s_ashr_i32 s3, s3, 3
	s_add_i32 s3, s3, s8
	s_mul_i32 s8, s3, 44
	s_sub_i32 s8, s2, s8
	v_lshl_or_b32 v0, s3, 6, v17
	v_lshl_add_u32 v2, s8, 6, v16
	v_ashrrev_i32_e32 v1, 31, v0
	v_ashrrev_i32_e32 v3, 31, v2
	v_lshl_add_u64 v[0:1], v[0:1], 2, s[6:7]
	v_lshlrev_b64 v[2:3], 12, v[2:3]
	v_lshl_add_u64 v[8:9], v[0:1], 0, v[2:3]
	v_add_co_u32_e32 v4, vcc, s81, v8
	s_mov_b32 s3, 0x30000
	s_nop 0
	v_addc_co_u32_e32 v5, vcc, 0, v9, vcc
	v_add_co_u32_e32 v10, vcc, s78, v8
	global_load_dwordx4 v[0:3], v[8:9], off
	s_nop 0
	global_load_dwordx4 v[4:7], v[4:5], off
	v_addc_co_u32_e32 v11, vcc, 0, v9, vcc
	v_add_co_u32_e32 v12, vcc, s3, v8
	s_nop 1
	v_addc_co_u32_e32 v13, vcc, 0, v9, vcc
	global_load_dwordx4 v[8:11], v[10:11], off
	s_nop 0
	global_load_dwordx4 v[12:15], v[12:13], off
.LBB0_200:
	s_mov_b32 s30, s59
	s_andn2_b64 vcc, exec, s[24:25]
	s_mov_b32 s29, 0xffff
	s_cbranch_vccnz .LBB0_209
	v_lshlrev_b32_e32 v19, 4, v20
	s_movk_i32 s3, 0x104
	v_and_b32_e32 v22, 48, v19
	v_mul_lo_u32 v19, v16, s3
	v_lshlrev_b32_e32 v21, 2, v17
	s_add_u32 s8, s20, 0x3400000
	v_ashrrev_i32_e32 v18, 2, v20
	v_add3_u32 v19, s60, v19, v21
	v_mul_u32_u24_e32 v21, 0x104, v22
	v_and_b32_e32 v20, -4, v20
	s_addc_u32 s9, s21, 0
	v_add3_u32 v20, s60, v21, v20
	v_lshlrev_b32_e32 v144, 1, v22
	s_mov_b32 s98, 0
	s_branch .LBB0_203

.LBB0_203:
	s_cmpk_lt_i32 s2, 0x2c0
	s_cselect_b64 s[22:23], -1, 0
	s_cmpk_gt_i32 s2, 0x2bf
	s_waitcnt lgkmcnt(0)
	s_barrier
	s_cbranch_scc1 .LBB0_205
	v_add_u32_e32 v21, 0x1040, v19
	s_cmp_eq_u32 s98, 0
	s_cbranch_scc1 .Lcvw11_f
	s_waitcnt vmcnt(2)
	s_branch .Lcvw11_d

.LBB0_205:
	s_add_i32 s3, s0, s2
	s_cmpk_gt_i32 s3, 0x2bf
	s_cbranch_scc1 .LBB0_207
	s_mul_hi_i32 s24, s3, 0x2e8ba2e9
	s_lshr_b32 s25, s24, 31
	s_ashr_i32 s24, s24, 3
	s_add_i32 s24, s24, s25
	s_mul_i32 s25, s24, 44
	s_sub_i32 s25, s3, s25
	s_waitcnt vmcnt(2)
	v_lshl_or_b32 v0, s24, 6, v17
	v_lshl_add_u32 v2, s25, 6, v16
	v_ashrrev_i32_e32 v1, 31, v0
	v_ashrrev_i32_e32 v3, 31, v2
	v_lshl_add_u64 v[0:1], v[0:1], 2, s[6:7]
	v_lshlrev_b64 v[2:3], 12, v[2:3]
	v_lshl_add_u64 v[8:9], v[0:1], 0, v[2:3]
	v_add_co_u32_e32 v4, vcc, s81, v8
	s_mov_b32 s24, 0x30000
	s_nop 0
	v_addc_co_u32_e32 v5, vcc, 0, v9, vcc
	v_add_co_u32_e32 v10, vcc, s78, v8
	global_load_dwordx4 v[0:3], v[8:9], off
	s_nop 0
	global_load_dwordx4 v[4:7], v[4:5], off
	v_addc_co_u32_e32 v11, vcc, 0, v9, vcc
	v_add_co_u32_e32 v12, vcc, s24, v8
	s_nop 1
	v_addc_co_u32_e32 v13, vcc, 0, v9, vcc
	global_load_dwordx4 v[8:11], v[10:11], off
	s_nop 0
	global_load_dwordx4 v[12:15], v[12:13], off
.LBB0_207:
	s_andn2_b64 vcc, exec, s[22:23]
	s_waitcnt lgkmcnt(0)
	s_barrier
	s_cbranch_vccnz .LBB0_202
	ds_read2_b32 v[22:23], v20 offset1:65
	ds_read2_b32 v[24:25], v20 offset0:130 offset1:195
	v_add_u32_e32 v21, 0x400, v20
	s_mul_hi_i32 s22, s2, 0x2e8ba2e9
	s_waitcnt lgkmcnt(0)
	v_cvt_pk_bf16_f32 v22, v22, v23
	v_cvt_pk_bf16_f32 v23, v24, v25
	ds_read2_b32 v[24:25], v21 offset0:4 offset1:69
	ds_read2_b32 v[26:27], v21 offset0:134 offset1:199
	v_add_u32_e32 v21, 0x800, v20
	s_lshr_b32 s23, s22, 31
	s_ashr_i32 s22, s22, 3
	s_waitcnt lgkmcnt(0)
	v_cvt_pk_bf16_f32 v24, v24, v25
	v_cvt_pk_bf16_f32 v25, v26, v27
	ds_read2_b32 v[26:27], v21 offset0:8 offset1:73
	ds_read2_b32 v[28:29], v21 offset0:138 offset1:203
	v_add_u32_e32 v21, 0xc00, v20
	s_add_i32 s22, s22, s23
	s_waitcnt lgkmcnt(0)
	v_cvt_pk_bf16_f32 v26, v26, v27
	v_cvt_pk_bf16_f32 v27, v28, v29
	ds_read2_b32 v[28:29], v21 offset0:12 offset1:77
	ds_read2_b32 v[30:31], v21 offset0:142 offset1:207
	s_mul_i32 s23, s22, 44
	s_waitcnt lgkmcnt(0)
	v_cvt_pk_bf16_f32 v28, v28, v29
	v_cvt_pk_bf16_f32 v29, v30, v31
	v_lshl_add_u32 v21, s22, 6, v18
	v_mov_b64_e32 v[30:31], s[8:9]
	s_sub_i32 s2, s2, s23
	v_mad_i64_i32 v[30:31], s[22:23], v21, s33, v[30:31]
	s_lshl_b32 s22, s2, 6
	s_ashr_i32 s23, s22, 31
	v_lshl_add_u64 v[30:31], s[22:23], 1, v[30:31]
	v_lshl_add_u64 v[30:31], v[30:31], 0, v[144:145]
	global_store_dwordx4 v[30:31], v[22:25], off
	global_store_dwordx4 v[30:31], v[26:29], off offset:16
	s_branch .LBB0_202

.LBB0_709:
	s_and_b64 vcc, exec, s[2:3]
	s_cbranch_vccz .LBB0_928
	s_mov_b32 s0, s70
	s_abs_i32 s34, s0
	s_waitcnt vmcnt(0) lgkmcnt(0)
	v_cvt_f32_u32_e32 v0, s34
	v_readlane_b32 s36, v255, 27
	s_sub_i32 s6, 0, s34
	s_add_i32 s35, s0, s77
	v_rcp_iflag_f32_e32 v0, v0
	s_abs_i32 s3, s35
	s_ashr_i32 s2, s35, 31
	v_readlane_b32 s40, v255, 31
	v_mul_f32_e32 v0, 0x4f7ffffe, v0
	v_cvt_u32_f32_e32 v0, v0
	v_readlane_b32 s41, v255, 32
	v_readlane_b32 s42, v255, 33
	v_readlane_b32 s43, v255, 34
	v_readfirstlane_b32 s36, v0
	s_mul_i32 s6, s6, s36
	s_mul_hi_u32 s6, s36, s6
	s_add_i32 s36, s36, s6
	s_mul_hi_u32 s6, s3, s36
	s_mul_i32 s6, s6, s34
	s_sub_i32 s3, s3, s6
	s_sub_i32 s6, s3, s34
	s_cmp_ge_u32 s3, s34
	s_cselect_b32 s3, s6, s3
	s_sub_i32 s6, s3, s34
	s_cmp_ge_u32 s3, s34
	s_cselect_b32 s3, s6, s3
	s_mov_b64 s[12:13], s[74:75]
	s_mov_b64 s[20:21], s[42:43]
	s_mov_b64 s[22:23], s[40:41]
	v_mov_b32_e32 v24, v191
	s_xor_b32 s3, s3, s2
	s_sub_i32 s28, s3, s2
	v_mov_b32_e32 v15, 0
	v_lshlrev_b32_e32 v20, 2, v24
	s_cmpk_gt_i32 s28, 0x57f
	v_ashrrev_i32_e32 v18, 4, v24
	v_and_b32_e32 v19, 28, v20
	v_mov_b32_e32 v14, v15
	v_mov_b32_e32 v13, v15
	v_mov_b32_e32 v12, v15
	v_mov_b32_e32 v11, v15
	v_mov_b32_e32 v10, v15
	v_mov_b32_e32 v9, v15
	v_mov_b32_e32 v8, v15
	v_mov_b32_e32 v7, v15
	v_mov_b32_e32 v6, v15
	v_mov_b32_e32 v5, v15
	v_mov_b32_e32 v4, v15
	v_mov_b32_e32 v3, v15
	v_mov_b32_e32 v2, v15
	v_mov_b32_e32 v1, v15
	v_mov_b32_e32 v0, v15
	s_movk_i32 s58, 0x104
	s_mov_b32 s59, 0x30000
	s_movk_i32 s61, 0x5c00
	s_mov_b32 s62, 0x40000
	s_mov_b32 s63, 0x60000
	v_readlane_b32 s37, v255, 28
	v_readlane_b32 s38, v255, 29
	v_readlane_b32 s39, v255, 30
	v_readlane_b32 s44, v255, 35
	v_readlane_b32 s45, v255, 36
	v_readlane_b32 s46, v255, 37
	v_readlane_b32 s47, v255, 38
	v_readlane_b32 s48, v255, 39
	v_readlane_b32 s49, v255, 40
	v_readlane_b32 s50, v255, 41
	v_readlane_b32 s51, v255, 42
	s_cbranch_scc1 .LBB0_719
	s_ashr_i32 s2, s28, 31
	s_lshr_b32 s2, s2, 28
	s_add_i32 s2, s28, s2
	s_and_b32 s3, s2, 0x3fffff0
	s_lshl_b32 s2, s2, 2
	s_andn2_b32 s2, s2, 63
	v_and_or_b32 v0, v20, 32, s2
	v_ashrrev_i32_e32 v0, 1, v0
	s_movk_i32 s2, 0xaf0
	v_or_b32_e32 v1, v0, v19
	v_add3_u32 v0, v19, v0, s2
	v_cmp_gt_u32_e32 vcc, 16, v19
	s_sub_i32 s3, s28, s3
	v_lshl_add_u32 v12, s3, 6, v18
	v_cndmask_b32_e32 v0, v0, v1, vcc
	v_ashrrev_i32_e32 v1, 31, v0
	v_lshl_add_u64 v[14:15], v[0:1], 2, s[20:21]
	v_mad_i64_i32 v[0:1], s[2:3], v12, s85, v[14:15]
	global_load_dwordx4 v[0:3], v[0:1], off
	s_cmp_lg_u64 s[22:23], 0
	v_ashrrev_i32_e32 v13, 31, v12
	s_cselect_b64 s[2:3], -1, 0
	s_cmp_eq_u64 s[22:23], 0
	v_lshl_add_u64 v[16:17], v[12:13], 2, s[22:23]
	s_cbranch_scc1 .LBB0_713
	global_load_dword v40, v[16:17], off
.LBB0_713:
	v_add_u32_e32 v4, 16, v12
	v_mad_i64_i32 v[4:5], s[6:7], v4, s85, v[14:15]
	global_load_dwordx4 v[4:7], v[4:5], off
	v_cndmask_b32_e64 v8, 0, 1, s[2:3]
	v_cmp_ne_u32_e64 s[6:7], 1, v8
	s_andn2_b64 vcc, exec, s[2:3]
	s_cbranch_vccnz .LBB0_715
	global_load_dword v42, v[16:17], off offset:64
.LBB0_715:
	v_add_u32_e32 v8, 32, v12
	v_mad_i64_i32 v[8:9], s[2:3], v8, s85, v[14:15]
	global_load_dwordx4 v[8:11], v[8:9], off
	s_and_b64 vcc, exec, s[6:7]
	s_cbranch_vccnz .LBB0_717
	global_load_dword v44, v[16:17], off offset:128
.LBB0_717:
	v_add_u32_e32 v12, 48, v12
	v_mad_i64_i32 v[12:13], s[2:3], v12, s85, v[14:15]
	global_load_dwordx4 v[12:15], v[12:13], off
	s_and_b64 vcc, exec, s[6:7]
	s_cbranch_vccnz .LBB0_719
	global_load_dword v46, v[16:17], off offset:192
.LBB0_719:
	s_add_i32 s2, s0, 0x57f
	s_sub_i32 s6, 0xfffffa81, s0
	s_ashr_i32 s3, s2, 31
	s_max_i32 s2, s2, s6
	s_mul_hi_u32 s6, s2, s36
	s_mul_i32 s7, s6, s34
	s_ashr_i32 s39, s0, 31
	s_sub_i32 s2, s2, s7
	s_xor_b32 s3, s3, s39
	s_add_i32 s7, s6, 1
	s_sub_i32 s8, s2, s34
	s_cmp_ge_u32 s2, s34
	s_cselect_b32 s6, s7, s6
	s_cselect_b32 s2, s8, s2
	s_add_i32 s7, s6, 1
	s_cmp_ge_u32 s2, s34
	s_cselect_b32 s2, s7, s6
	s_xor_b32 s2, s2, s3
	s_sub_i32 s37, s2, s3
	s_cmp_gt_i32 s37, 0
	s_cselect_b64 s[18:19], -1, 0
	s_cmp_lt_i32 s37, 1
	s_cbranch_scc1 .LBB0_735
	v_and_b32_e32 v20, 60, v20
	v_lshlrev_b32_e32 v16, 4, v24
	v_and_b32_e32 v16, 48, v16
	v_mul_lo_u32 v17, v18, s58
	v_lshlrev_b32_e32 v23, 2, v20
	s_cmp_lg_u64 s[22:23], 0
	v_ashrrev_i32_e32 v22, 2, v24
	v_add3_u32 v23, s60, v17, v23
	v_mul_u32_u24_e32 v17, 0x104, v16
	v_and_b32_e32 v24, -4, v24
	v_cmp_gt_u32_e64 s[6:7], 16, v19
	v_add_u32_e32 v21, 0xaf0, v19
	s_cselect_b64 s[24:25], -1, 0
	v_add3_u32 v24, s60, v17, v24
	v_lshlrev_b32_e32 v144, 1, v16
	s_mov_b32 s2, s37
	s_mov_b32 s98, 0
	s_branch .LBB0_722

.LBB0_722:
	s_cmpk_lt_i32 s28, 0x580
	s_cselect_b64 s[26:27], -1, 0
	s_cmpk_gt_i32 s28, 0x57f
	s_waitcnt lgkmcnt(0)
	s_barrier
	s_cbranch_scc1 .LBB0_724
	v_add_u32_e32 v16, 0x1040, v23
	s_cmp_eq_u32 s98, 0
	s_cbranch_scc1 .Lcvw12_f
	s_waitcnt vmcnt(2)
	s_branch .Lcvw12_d

.LBB0_724:
	s_add_i32 s3, s0, s28
	s_cmpk_gt_i32 s3, 0x57f
	s_cbranch_scc1 .LBB0_733
	s_ashr_i32 s8, s3, 31
	s_lshr_b32 s8, s8, 28
	s_add_i32 s8, s3, s8
	s_and_b32 s9, s8, 0x3fffff0
	s_lshl_b32 s8, s8, 2
	s_andn2_b32 s8, s8, 63
	s_waitcnt vmcnt(2)
	v_or_b32_e32 v0, s8, v20
	v_ashrrev_i32_e32 v0, 1, v0
	v_and_b32_e32 v0, -16, v0
	v_or_b32_e32 v1, v0, v19
	v_add_u32_e32 v0, v21, v0
	v_cndmask_b32_e64 v0, v0, v1, s[6:7]
	s_sub_i32 s9, s3, s9
	v_ashrrev_i32_e32 v1, 31, v0
	v_lshl_add_u32 v12, s9, 6, v18
	v_lshl_add_u64 v[14:15], v[0:1], 2, s[20:21]
	v_mad_i64_i32 v[0:1], s[8:9], v12, s85, v[14:15]
	global_load_dwordx4 v[0:3], v[0:1], off
	v_ashrrev_i32_e32 v13, 31, v12
	v_cndmask_b32_e64 v4, 0, 1, s[24:25]
	v_cmp_ne_u32_e64 s[8:9], 1, v4
	s_andn2_b64 vcc, exec, s[24:25]
	v_lshl_add_u64 v[16:17], v[12:13], 2, s[22:23]
	s_cbranch_vccnz .LBB0_727
	global_load_dword v40, v[16:17], off
.LBB0_727:
	v_add_u32_e32 v4, 16, v12
	v_mad_i64_i32 v[4:5], s[30:31], v4, s85, v[14:15]
	global_load_dwordx4 v[4:7], v[4:5], off
	s_and_b64 vcc, exec, s[8:9]
	s_cbranch_vccnz .LBB0_729
	global_load_dword v42, v[16:17], off offset:64
.LBB0_729:
	v_add_u32_e32 v8, 32, v12
	v_mad_i64_i32 v[8:9], s[30:31], v8, s85, v[14:15]
	global_load_dwordx4 v[8:11], v[8:9], off
	s_and_b64 vcc, exec, s[8:9]
	s_cbranch_vccnz .LBB0_731
	global_load_dword v44, v[16:17], off offset:128
.LBB0_731:
	v_add_u32_e32 v12, 48, v12
	v_mad_i64_i32 v[12:13], s[30:31], v12, s85, v[14:15]
	global_load_dwordx4 v[12:15], v[12:13], off
	s_and_b64 vcc, exec, s[8:9]
	s_cbranch_vccnz .LBB0_733
	global_load_dword v46, v[16:17], off offset:192
.LBB0_733:
	s_andn2_b64 vcc, exec, s[26:27]
	s_waitcnt lgkmcnt(0)
	s_barrier
	s_cbranch_vccnz .LBB0_721
	ds_read2_b32 v[16:17], v24 offset1:65
	s_waitcnt lgkmcnt(0)
	v_cvt_pk_bf16_f32 v26, v16, v17
	ds_read2_b32 v[16:17], v24 offset0:130 offset1:195
	v_add_u32_e32 v25, 0x400, v24
	s_waitcnt lgkmcnt(0)
	v_cvt_pk_bf16_f32 v27, v16, v17
	ds_read2_b32 v[16:17], v25 offset0:4 offset1:69
	s_ashr_i32 s8, s28, 31
	s_waitcnt lgkmcnt(0)
	v_cvt_pk_bf16_f32 v28, v16, v17
	ds_read2_b32 v[16:17], v25 offset0:134 offset1:199
	v_add_u32_e32 v25, 0x800, v24
	s_lshr_b32 s8, s8, 28
	s_waitcnt lgkmcnt(0)
	v_cvt_pk_bf16_f32 v29, v16, v17
	ds_read2_b32 v[16:17], v25 offset0:8 offset1:73
	s_add_i32 s8, s28, s8
	s_waitcnt lgkmcnt(0)
	v_cvt_pk_bf16_f32 v30, v16, v17
	ds_read2_b32 v[16:17], v25 offset0:138 offset1:203
	v_add_u32_e32 v25, 0xc00, v24
	s_and_b32 s9, s8, 0x3fffff0
	s_waitcnt lgkmcnt(0)
	v_cvt_pk_bf16_f32 v31, v16, v17
	ds_read2_b32 v[16:17], v25 offset0:12 offset1:77
	s_lshl_b32 s8, s8, 2
	s_waitcnt lgkmcnt(0)
	v_cvt_pk_bf16_f32 v32, v16, v17
	ds_read2_b32 v[16:17], v25 offset0:142 offset1:207
	s_andn2_b32 s8, s8, 63
	s_waitcnt lgkmcnt(0)
	v_cvt_pk_bf16_f32 v33, v16, v17
	v_add_u32_e32 v16, s8, v22
	s_sub_i32 s9, s28, s9
	v_ashrrev_i32_e32 v17, 31, v16
	v_lshlrev_b64 v[16:17], 11, v[16:17]
	s_lshl_b32 s8, s9, 6
	v_lshl_add_u64 v[16:17], s[12:13], 0, v[16:17]
	s_ashr_i32 s9, s8, 31
	v_lshl_add_u64 v[16:17], s[8:9], 1, v[16:17]
	v_lshl_add_u64 v[16:17], v[16:17], 0, v[144:145]
	global_store_dwordx4 v[16:17], v[26:29], off
	global_store_dwordx4 v[16:17], v[30:33], off offset:16
	s_branch .LBB0_721
.LBB0_735:
	s_mul_hi_u32 s2, s36, 0x580
	s_mul_i32 s2, s2, s34
	s_sub_i32 s2, 0x580, s2
	s_sub_i32 s3, s2, s34
	s_cmp_ge_u32 s2, s34
	s_cselect_b32 s2, s3, s2
	s_sub_i32 s3, s2, s34
	s_cmp_ge_u32 s2, s34
	s_cselect_b32 s2, s3, s2
	s_sub_i32 s2, s35, s2
	s_ashr_i32 s3, s2, 31
	s_abs_i32 s2, s2
	s_mul_hi_u32 s8, s2, s36
	s_mul_i32 s8, s8, s34
	s_sub_i32 s2, s2, s8
	s_sub_i32 s8, s2, s34
	s_cmp_ge_u32 s2, s34
	s_cselect_b32 s2, s8, s2
	s_sub_i32 s8, s2, s34
	v_readlane_b32 s40, v255, 27
	s_cmp_ge_u32 s2, s34
	v_readlane_b32 s48, v255, 35
	v_readlane_b32 s49, v255, 36
	s_cselect_b32 s2, s8, s2
	s_mov_b64 s[6:7], s[48:49]
	v_mov_b32_e32 v20, v191
	s_xor_b32 s2, s2, s3
	s_sub_i32 s2, s2, s3
	s_waitcnt vmcnt(0) lgkmcnt(0)
	v_mov_b32_e32 v0, 0
	v_lshlrev_b32_e32 v1, 2, v20
	s_cmpk_gt_i32 s2, 0x2bf
	v_ashrrev_i32_e32 v16, 4, v20
	v_and_b32_e32 v17, 60, v1
	v_mov_b32_e32 v1, v0
	v_mov_b32_e32 v2, v0
	v_mov_b32_e32 v3, v0
	v_mov_b32_e32 v4, v0
	v_mov_b32_e32 v5, v0
	v_mov_b32_e32 v6, v0
	v_mov_b32_e32 v7, v0
	v_mov_b32_e32 v8, v0
	v_mov_b32_e32 v9, v0
	v_mov_b32_e32 v10, v0
	v_mov_b32_e32 v11, v0
	v_mov_b32_e32 v12, v0
	v_mov_b32_e32 v13, v0
	v_mov_b32_e32 v14, v0
	v_mov_b32_e32 v15, v0
	v_readlane_b32 s41, v255, 28
	v_readlane_b32 s42, v255, 29
	v_readlane_b32 s43, v255, 30
	v_readlane_b32 s44, v255, 31
	v_readlane_b32 s45, v255, 32
	v_readlane_b32 s46, v255, 33
	v_readlane_b32 s47, v255, 34
	v_readlane_b32 s50, v255, 37
	v_readlane_b32 s51, v255, 38
	v_readlane_b32 s52, v255, 39
	v_readlane_b32 s53, v255, 40
	v_readlane_b32 s54, v255, 41
	v_readlane_b32 s55, v255, 42
	s_cbranch_scc1 .LBB0_737
	s_mul_hi_i32 s3, s2, 0x2e8ba2e9
	s_lshr_b32 s8, s3, 31
	s_ashr_i32 s3, s3, 3
	s_add_i32 s3, s3, s8
	s_mul_i32 s8, s3, 44
	s_sub_i32 s8, s2, s8
	v_lshl_or_b32 v0, s3, 6, v17
	v_lshl_add_u32 v2, s8, 6, v16
	v_ashrrev_i32_e32 v1, 31, v0
	v_ashrrev_i32_e32 v3, 31, v2
	v_lshl_add_u64 v[0:1], v[0:1], 2, s[6:7]
	v_lshlrev_b64 v[2:3], 12, v[2:3]
	v_lshl_add_u64 v[8:9], v[0:1], 0, v[2:3]
	v_add_co_u32_e32 v4, vcc, s81, v8
	s_nop 1
	v_addc_co_u32_e32 v5, vcc, 0, v9, vcc
	v_add_co_u32_e32 v10, vcc, s78, v8
	global_load_dwordx4 v[0:3], v[8:9], off
	s_nop 0
	global_load_dwordx4 v[4:7], v[4:5], off
	v_addc_co_u32_e32 v11, vcc, 0, v9, vcc
	v_add_co_u32_e32 v12, vcc, s59, v8
	s_nop 1
	v_addc_co_u32_e32 v13, vcc, 0, v9, vcc
	global_load_dwordx4 v[8:11], v[10:11], off
	s_nop 0
	global_load_dwordx4 v[12:15], v[12:13], off
.LBB0_737:
	s_add_i32 s3, s0, 0x2bf
	s_sub_i32 s9, 0xfffffd41, s0
	s_ashr_i32 s8, s3, 31
	s_max_i32 s3, s3, s9
	s_mul_hi_u32 s9, s3, s36
	s_mul_i32 s20, s9, s34
	s_sub_i32 s3, s3, s20
	s_xor_b32 s8, s8, s39
	s_add_i32 s20, s9, 1
	s_sub_i32 s21, s3, s34
	s_cmp_ge_u32 s3, s34
	s_cselect_b32 s9, s20, s9
	s_cselect_b32 s3, s21, s3
	s_add_i32 s20, s9, 1
	s_cmp_ge_u32 s3, s34
	s_cselect_b32 s3, s20, s9
	s_xor_b32 s3, s3, s8
	s_sub_i32 s38, s3, s8
	s_cmp_gt_i32 s38, 0
	s_cselect_b64 s[20:21], -1, 0
	s_cmp_lt_i32 s38, 1
	s_cbranch_scc1 .LBB0_746
	v_lshlrev_b32_e32 v19, 4, v20
	v_and_b32_e32 v22, 48, v19
	v_mul_lo_u32 v19, v16, s58
	v_lshlrev_b32_e32 v21, 2, v17
	s_add_u32 s8, s12, 0xb00000
	v_ashrrev_i32_e32 v18, 2, v20
	v_add3_u32 v19, s60, v19, v21
	v_mul_u32_u24_e32 v21, 0x104, v22
	v_and_b32_e32 v20, -4, v20
	s_addc_u32 s9, s13, 0
	v_add3_u32 v20, s60, v21, v20
	v_lshlrev_b32_e32 v144, 1, v22
	s_mov_b32 s3, s38
	s_mov_b32 s98, 0
	s_branch .LBB0_740

.LBB0_742:
	s_add_i32 s24, s0, s2
	s_cmpk_gt_i32 s24, 0x2bf
	s_cbranch_scc1 .LBB0_744
	s_mul_hi_i32 s25, s24, 0x2e8ba2e9
	s_lshr_b32 s26, s25, 31
	s_ashr_i32 s25, s25, 3
	s_add_i32 s25, s25, s26
	s_mul_i32 s26, s25, 44
	s_sub_i32 s26, s24, s26
	s_waitcnt vmcnt(2)
	v_lshl_or_b32 v0, s25, 6, v17
	v_lshl_add_u32 v2, s26, 6, v16
	v_ashrrev_i32_e32 v1, 31, v0
	v_ashrrev_i32_e32 v3, 31, v2
	v_lshl_add_u64 v[0:1], v[0:1], 2, s[6:7]
	v_lshlrev_b64 v[2:3], 12, v[2:3]
	v_lshl_add_u64 v[8:9], v[0:1], 0, v[2:3]
	v_add_co_u32_e32 v4, vcc, s81, v8
	s_nop 1
	v_addc_co_u32_e32 v5, vcc, 0, v9, vcc
	v_add_co_u32_e32 v10, vcc, s78, v8
	global_load_dwordx4 v[0:3], v[8:9], off
	s_nop 0
	global_load_dwordx4 v[4:7], v[4:5], off
	v_addc_co_u32_e32 v11, vcc, 0, v9, vcc
	v_add_co_u32_e32 v12, vcc, s59, v8
	s_nop 1
	v_addc_co_u32_e32 v13, vcc, 0, v9, vcc
	global_load_dwordx4 v[8:11], v[10:11], off
	s_nop 0
	global_load_dwordx4 v[12:15], v[12:13], off

.LBB0_746:
	s_mul_hi_u32 s2, s36, 0x840
	s_mul_i32 s2, s2, s34
	s_sub_i32 s2, 0x840, s2
	s_sub_i32 s3, s2, s34
	s_cmp_ge_u32 s2, s34
	s_cselect_b32 s2, s3, s2
	s_sub_i32 s3, s2, s34
	s_cmp_ge_u32 s2, s34
	s_cselect_b32 s2, s3, s2
	s_sub_i32 s2, s35, s2
	s_ashr_i32 s3, s2, 31
	s_abs_i32 s2, s2
	s_mul_hi_u32 s6, s2, s36
	s_mul_i32 s6, s6, s34
	s_sub_i32 s2, s2, s6
	s_sub_i32 s6, s2, s34
	s_cmp_ge_u32 s2, s34
	s_cselect_b32 s2, s6, s2
	s_sub_i32 s6, s2, s34
	s_cmp_ge_u32 s2, s34
	v_readlane_b32 s40, v255, 27
	s_cselect_b32 s2, s6, s2
	v_readlane_b32 s50, v255, 37
	v_readlane_b32 s51, v255, 38
	v_readlane_b32 s52, v255, 39
	v_readlane_b32 s53, v255, 40
	s_xor_b32 s2, s2, s3
	s_mov_b64 s[8:9], s[52:53]
	s_mov_b64 s[22:23], s[50:51]
	v_mov_b32_e32 v22, v191
	s_sub_i32 s30, s2, s3
	s_waitcnt vmcnt(0) lgkmcnt(0)
	v_mov_b32_e32 v15, 0
	s_cmpk_gt_i32 s30, 0x5bf
	v_lshlrev_b32_e32 v19, 2, v22
	v_ashrrev_i32_e32 v18, 4, v22
	v_mov_b32_e32 v14, v15
	v_mov_b32_e32 v13, v15
	v_mov_b32_e32 v12, v15
	v_mov_b32_e32 v11, v15
	v_mov_b32_e32 v10, v15
	v_mov_b32_e32 v9, v15
	v_mov_b32_e32 v8, v15
	v_mov_b32_e32 v7, v15
	v_mov_b32_e32 v6, v15
	v_mov_b32_e32 v5, v15
	v_mov_b32_e32 v4, v15
	v_mov_b32_e32 v3, v15
	v_mov_b32_e32 v2, v15
	v_mov_b32_e32 v1, v15
	v_mov_b32_e32 v0, v15
	v_readlane_b32 s41, v255, 28
	v_readlane_b32 s42, v255, 29
	v_readlane_b32 s43, v255, 30
	v_readlane_b32 s44, v255, 31
	v_readlane_b32 s45, v255, 32
	v_readlane_b32 s46, v255, 33
	v_readlane_b32 s47, v255, 34
	v_readlane_b32 s48, v255, 35
	v_readlane_b32 s49, v255, 36
	v_readlane_b32 s54, v255, 41
	v_readlane_b32 s55, v255, 42
	s_cbranch_scc1 .LBB0_755
	s_ashr_i32 s2, s30, 31
	s_lshr_b32 s2, s2, 28
	s_add_i32 s2, s30, s2
	s_and_b32 s3, s2, 0x3fffff0
	s_lshl_b32 s2, s2, 2
	s_andn2_b32 s2, s2, 63
	v_and_or_b32 v0, v19, 60, s2
	s_sub_i32 s3, s30, s3
	v_ashrrev_i32_e32 v1, 31, v0
	v_lshl_add_u32 v12, s3, 6, v18
	v_lshl_add_u64 v[14:15], v[0:1], 2, s[8:9]
	v_mad_i64_i32 v[0:1], s[2:3], v12, s61, v[14:15]
	global_load_dwordx4 v[0:3], v[0:1], off
	s_cmp_lg_u64 s[22:23], 0
	v_ashrrev_i32_e32 v13, 31, v12
	s_cselect_b64 s[2:3], -1, 0
	s_cmp_eq_u64 s[22:23], 0
	v_lshl_add_u64 v[16:17], v[12:13], 2, s[22:23]
	s_cbranch_scc1 .LBB0_749
	global_load_dword v40, v[16:17], off
.LBB0_749:
	v_add_u32_e32 v4, 16, v12
	v_mad_i64_i32 v[4:5], s[6:7], v4, s61, v[14:15]
	global_load_dwordx4 v[4:7], v[4:5], off
	v_cndmask_b32_e64 v8, 0, 1, s[2:3]
	v_cmp_ne_u32_e64 s[6:7], 1, v8
	s_andn2_b64 vcc, exec, s[2:3]
	s_cbranch_vccnz .LBB0_751
	global_load_dword v42, v[16:17], off offset:64
.LBB0_751:
	v_add_u32_e32 v8, 32, v12
	v_mad_i64_i32 v[8:9], s[2:3], v8, s61, v[14:15]
	global_load_dwordx4 v[8:11], v[8:9], off
	s_and_b64 vcc, exec, s[6:7]
	s_cbranch_vccnz .LBB0_753
	global_load_dword v44, v[16:17], off offset:128
.LBB0_753:
	v_add_u32_e32 v12, 48, v12
	v_mad_i64_i32 v[12:13], s[2:3], v12, s61, v[14:15]
	global_load_dwordx4 v[12:15], v[12:13], off
	s_and_b64 vcc, exec, s[6:7]
	s_cbranch_vccnz .LBB0_755
	global_load_dword v46, v[16:17], off offset:192
.LBB0_755:
	s_add_i32 s2, s0, 0x5bf
	s_sub_i32 s6, 0xfffffa41, s0
	s_ashr_i32 s3, s2, 31
	s_max_i32 s2, s2, s6
	s_mul_hi_u32 s6, s2, s36
	s_mul_i32 s7, s6, s34
	s_sub_i32 s2, s2, s7
	s_xor_b32 s3, s3, s39
	s_add_i32 s7, s6, 1
	s_sub_i32 s24, s2, s34
	s_cmp_ge_u32 s2, s34
	s_cselect_b32 s6, s7, s6
	s_cselect_b32 s2, s24, s2
	s_add_i32 s7, s6, 1
	s_cmp_ge_u32 s2, s34
	s_cselect_b32 s2, s7, s6
	s_xor_b32 s2, s2, s3
	s_sub_i32 s2, s2, s3
	s_cmp_lt_i32 s2, 1
	s_cbranch_scc1 .LBB0_771
	s_add_u32 s24, s12, 0x1080000
	v_and_b32_e32 v19, 60, v19
	v_lshlrev_b32_e32 v16, 4, v22
	s_addc_u32 s25, s13, 0
	v_and_b32_e32 v16, 48, v16
	v_mul_lo_u32 v17, v18, s58
	v_lshlrev_b32_e32 v21, 2, v19
	s_cmp_lg_u64 s[22:23], 0
	v_ashrrev_i32_e32 v20, 2, v22
	v_add3_u32 v21, s60, v17, v21
	v_mul_u32_u24_e32 v17, 0x104, v16
	v_and_b32_e32 v22, -4, v22
	s_cselect_b64 s[26:27], -1, 0
	v_add3_u32 v22, s60, v17, v22
	v_lshlrev_b32_e32 v144, 1, v16
	s_mov_b32 s98, 0
	s_branch .LBB0_758

.LBB0_758:
	s_cmpk_lt_i32 s30, 0x5c0
	s_cselect_b64 s[28:29], -1, 0
	s_cmpk_gt_i32 s30, 0x5bf
	s_waitcnt lgkmcnt(0)
	s_barrier
	s_cbranch_scc1 .LBB0_760
	v_add_u32_e32 v16, 0x1040, v21
	s_cmp_eq_u32 s98, 0
	s_cbranch_scc1 .Lcvw14_f
	s_waitcnt vmcnt(2)
	s_branch .Lcvw14_d

.LBB0_760:
	s_add_i32 s3, s0, s30
	s_cmpk_gt_i32 s3, 0x5bf
	s_cbranch_scc1 .LBB0_769
	s_ashr_i32 s6, s3, 31
	s_lshr_b32 s6, s6, 28
	s_add_i32 s6, s3, s6
	s_and_b32 s7, s6, 0x3fffff0
	s_lshl_b32 s6, s6, 2
	s_andn2_b32 s6, s6, 63
	s_waitcnt vmcnt(2)
	v_or_b32_e32 v0, s6, v19
	s_sub_i32 s7, s3, s7
	v_ashrrev_i32_e32 v1, 31, v0
	v_lshl_add_u32 v12, s7, 6, v18
	v_lshl_add_u64 v[14:15], v[0:1], 2, s[8:9]
	v_mad_i64_i32 v[0:1], s[6:7], v12, s61, v[14:15]
	global_load_dwordx4 v[0:3], v[0:1], off
	v_ashrrev_i32_e32 v13, 31, v12
	v_cndmask_b32_e64 v4, 0, 1, s[26:27]
	v_cmp_ne_u32_e64 s[6:7], 1, v4
	s_andn2_b64 vcc, exec, s[26:27]
	v_lshl_add_u64 v[16:17], v[12:13], 2, s[22:23]
	s_cbranch_vccnz .LBB0_763
	global_load_dword v40, v[16:17], off
.LBB0_763:
	v_add_u32_e32 v4, 16, v12
	v_mad_i64_i32 v[4:5], s[56:57], v4, s61, v[14:15]
	global_load_dwordx4 v[4:7], v[4:5], off
	s_and_b64 vcc, exec, s[6:7]
	s_cbranch_vccnz .LBB0_765
	global_load_dword v42, v[16:17], off offset:64
.LBB0_765:
	v_add_u32_e32 v8, 32, v12
	v_mad_i64_i32 v[8:9], s[56:57], v8, s61, v[14:15]
	global_load_dwordx4 v[8:11], v[8:9], off
	s_and_b64 vcc, exec, s[6:7]
	s_cbranch_vccnz .LBB0_767
	global_load_dword v44, v[16:17], off offset:128
.LBB0_767:
	v_add_u32_e32 v12, 48, v12
	v_mad_i64_i32 v[12:13], s[56:57], v12, s61, v[14:15]
	global_load_dwordx4 v[12:15], v[12:13], off
	s_and_b64 vcc, exec, s[6:7]
	s_cbranch_vccnz .LBB0_769
	global_load_dword v46, v[16:17], off offset:192
.LBB0_769:
	s_andn2_b64 vcc, exec, s[28:29]
	s_waitcnt lgkmcnt(0)
	s_barrier
	s_cbranch_vccnz .LBB0_757
	ds_read2_b32 v[16:17], v22 offset1:65
	s_waitcnt lgkmcnt(0)
	v_cvt_pk_bf16_f32 v24, v16, v17
	ds_read2_b32 v[16:17], v22 offset0:130 offset1:195
	v_add_u32_e32 v23, 0x400, v22
	s_waitcnt lgkmcnt(0)
	v_cvt_pk_bf16_f32 v25, v16, v17
	ds_read2_b32 v[16:17], v23 offset0:4 offset1:69
	s_ashr_i32 s6, s30, 31
	s_waitcnt lgkmcnt(0)
	v_cvt_pk_bf16_f32 v26, v16, v17
	ds_read2_b32 v[16:17], v23 offset0:134 offset1:199
	v_add_u32_e32 v23, 0x800, v22
	s_lshr_b32 s6, s6, 28
	s_waitcnt lgkmcnt(0)
	v_cvt_pk_bf16_f32 v27, v16, v17
	ds_read2_b32 v[16:17], v23 offset0:8 offset1:73
	s_add_i32 s6, s30, s6
	s_waitcnt lgkmcnt(0)
	v_cvt_pk_bf16_f32 v28, v16, v17
	ds_read2_b32 v[16:17], v23 offset0:138 offset1:203
	v_add_u32_e32 v23, 0xc00, v22
	s_and_b32 s7, s6, 0x3fffff0
	s_waitcnt lgkmcnt(0)
	v_cvt_pk_bf16_f32 v29, v16, v17
	ds_read2_b32 v[16:17], v23 offset0:12 offset1:77
	s_lshl_b32 s6, s6, 2
	s_waitcnt lgkmcnt(0)
	v_cvt_pk_bf16_f32 v30, v16, v17
	ds_read2_b32 v[16:17], v23 offset0:142 offset1:207
	s_andn2_b32 s6, s6, 63
	s_waitcnt lgkmcnt(0)
	v_cvt_pk_bf16_f32 v31, v16, v17
	v_add_u32_e32 v16, s6, v20
	s_sub_i32 s7, s30, s7
	v_ashrrev_i32_e32 v17, 31, v16
	v_lshlrev_b64 v[16:17], 11, v[16:17]
	s_lshl_b32 s6, s7, 6
	v_lshl_add_u64 v[16:17], s[24:25], 0, v[16:17]
	s_ashr_i32 s7, s6, 31
	v_lshl_add_u64 v[16:17], s[6:7], 1, v[16:17]
	v_lshl_add_u64 v[16:17], v[16:17], 0, v[144:145]
	global_store_dwordx4 v[16:17], v[24:27], off
	global_store_dwordx4 v[16:17], v[28:31], off offset:16
	s_branch .LBB0_757
.LBB0_771:
	s_mul_hi_u32 s2, s36, 0xe00
	s_mul_i32 s2, s2, s34
	s_sub_i32 s2, 0xe00, s2
	s_sub_i32 s3, s2, s34
	s_cmp_ge_u32 s2, s34
	s_cselect_b32 s2, s3, s2
	s_sub_i32 s3, s2, s34
	s_cmp_ge_u32 s2, s34
	s_cselect_b32 s2, s3, s2
	s_sub_i32 s2, s35, s2
	s_ashr_i32 s3, s2, 31
	s_abs_i32 s2, s2
	s_mul_hi_u32 s8, s2, s36
	s_mul_i32 s8, s8, s34
	s_sub_i32 s2, s2, s8
	s_sub_i32 s8, s2, s34
	s_cmp_ge_u32 s2, s34
	s_cselect_b32 s2, s8, s2
	s_sub_i32 s8, s2, s34
	s_cmp_ge_u32 s2, s34
	v_readlane_b32 s40, v254, 6
	s_cselect_b32 s2, s8, s2
	v_readlane_b32 s44, v254, 10
	v_readlane_b32 s45, v254, 11
	s_xor_b32 s2, s2, s3
	s_mov_b64 s[6:7], s[44:45]
	v_mov_b32_e32 v20, v191
	s_sub_i32 s3, s2, s3
	s_waitcnt vmcnt(0) lgkmcnt(0)
	v_mov_b32_e32 v0, 0
	s_cmpk_gt_i32 s3, 0x7f
	v_lshlrev_b32_e32 v17, 2, v20
	v_ashrrev_i32_e32 v16, 4, v20
	v_mov_b32_e32 v1, v0
	v_mov_b32_e32 v2, v0
	v_mov_b32_e32 v3, v0
	v_mov_b32_e32 v4, v0
	v_mov_b32_e32 v5, v0
	v_mov_b32_e32 v6, v0
	v_mov_b32_e32 v7, v0
	v_mov_b32_e32 v8, v0
	v_mov_b32_e32 v9, v0
	v_mov_b32_e32 v10, v0
	v_mov_b32_e32 v11, v0
	v_mov_b32_e32 v12, v0
	v_mov_b32_e32 v13, v0
	v_mov_b32_e32 v14, v0
	v_mov_b32_e32 v15, v0
	v_readlane_b32 s41, v254, 7
	v_readlane_b32 s42, v254, 8
	v_readlane_b32 s43, v254, 9
	v_readlane_b32 s46, v254, 12
	v_readlane_b32 s47, v254, 13
	v_readlane_b32 s48, v254, 14
	v_readlane_b32 s49, v254, 15
	v_readlane_b32 s50, v254, 16
	v_readlane_b32 s51, v254, 17
	v_readlane_b32 s52, v254, 18
	v_readlane_b32 s53, v254, 19
	v_readlane_b32 s54, v254, 20
	v_readlane_b32 s55, v254, 21
	s_cbranch_scc1 .LBB0_773
	s_ashr_i32 s2, s3, 31
	s_lshr_b32 s2, s2, 29
	s_add_i32 s2, s3, s2
	s_and_b32 s8, s2, 0x3fffff8
	s_lshl_b32 s2, s2, 3
	s_sub_i32 s8, s3, s8
	s_andn2_b32 s2, s2, 63
	v_and_or_b32 v0, v17, 60, s2
	v_lshl_add_u32 v2, s8, 6, v16
	v_ashrrev_i32_e32 v1, 31, v0
	v_ashrrev_i32_e32 v3, 31, v2
	v_lshl_add_u64 v[0:1], v[0:1], 2, s[6:7]
	v_lshlrev_b64 v[2:3], 12, v[2:3]
	v_lshl_add_u64 v[8:9], v[0:1], 0, v[2:3]
	v_add_co_u32_e32 v4, vcc, s81, v8
	s_nop 1
	v_addc_co_u32_e32 v5, vcc, 0, v9, vcc
	v_add_co_u32_e32 v10, vcc, s78, v8
	global_load_dwordx4 v[0:3], v[8:9], off
	s_nop 0
	global_load_dwordx4 v[4:7], v[4:5], off
	v_addc_co_u32_e32 v11, vcc, 0, v9, vcc
	v_add_co_u32_e32 v12, vcc, s59, v8
	s_nop 1
	v_addc_co_u32_e32 v13, vcc, 0, v9, vcc
	global_load_dwordx4 v[8:11], v[10:11], off
	s_nop 0
	global_load_dwordx4 v[12:15], v[12:13], off
.LBB0_773:
	s_add_i32 s2, s0, 0x7f
	s_sub_i32 s9, 0xffffff81, s0
	s_ashr_i32 s8, s2, 31
	s_max_i32 s2, s2, s9
	s_mul_hi_u32 s9, s2, s36
	s_mul_i32 s22, s9, s34
	s_sub_i32 s2, s2, s22
	s_xor_b32 s8, s8, s39
	s_add_i32 s22, s9, 1
	s_sub_i32 s23, s2, s34
	s_cmp_ge_u32 s2, s34
	s_cselect_b32 s9, s22, s9
	s_cselect_b32 s2, s23, s2
	s_add_i32 s22, s9, 1
	s_cmp_ge_u32 s2, s34
	s_cselect_b32 s2, s22, s9
	s_xor_b32 s2, s2, s8
	s_sub_i32 s2, s2, s8
	s_cmp_gt_i32 s2, 0
	s_cselect_b64 s[8:9], -1, 0
	s_cmp_lt_i32 s2, 1
	s_cbranch_scc1 .LBB0_782
	v_and_b32_e32 v17, 60, v17
	v_lshlrev_b32_e32 v19, 4, v20
	v_and_b32_e32 v22, 48, v19
	v_mul_lo_u32 v19, v16, s58
	v_lshlrev_b32_e32 v21, 2, v17
	s_add_u32 s22, s12, 0x1c00000
	v_ashrrev_i32_e32 v18, 2, v20
	v_add3_u32 v19, s60, v19, v21
	v_mul_u32_u24_e32 v21, 0x104, v22
	v_and_b32_e32 v20, -4, v20
	s_addc_u32 s23, s13, 0
	v_add3_u32 v20, s60, v21, v20
	v_lshlrev_b32_e32 v144, 1, v22
	s_mov_b32 s26, s2
	s_mov_b32 s98, 0
	s_branch .LBB0_776

.LBB0_776:
	s_cmpk_lt_i32 s3, 0x80
	s_cselect_b64 s[24:25], -1, 0
	s_cmpk_gt_i32 s3, 0x7f
	s_waitcnt lgkmcnt(0)
	s_barrier
	s_cbranch_scc1 .LBB0_778
	v_add_u32_e32 v21, 0x1040, v19
	s_cmp_eq_u32 s98, 0
	s_cbranch_scc1 .Lcvw15_f
	s_waitcnt vmcnt(2)
	s_branch .Lcvw15_d

.LBB0_778:
	s_add_i32 s27, s0, s3
	s_cmpk_gt_i32 s27, 0x7f
	s_cbranch_scc1 .LBB0_780
	s_ashr_i32 s28, s27, 31
	s_lshr_b32 s28, s28, 29
	s_add_i32 s28, s27, s28
	s_and_b32 s29, s28, 0x3fffff8
	s_lshl_b32 s28, s28, 3
	s_sub_i32 s29, s27, s29
	s_andn2_b32 s28, s28, 63
	s_waitcnt vmcnt(2)
	v_or_b32_e32 v0, s28, v17
	v_lshl_add_u32 v2, s29, 6, v16
	v_ashrrev_i32_e32 v1, 31, v0
	v_ashrrev_i32_e32 v3, 31, v2
	v_lshl_add_u64 v[0:1], v[0:1], 2, s[6:7]
	v_lshlrev_b64 v[2:3], 12, v[2:3]
	v_lshl_add_u64 v[8:9], v[0:1], 0, v[2:3]
	v_add_co_u32_e32 v4, vcc, s81, v8
	s_nop 1
	v_addc_co_u32_e32 v5, vcc, 0, v9, vcc
	v_add_co_u32_e32 v10, vcc, s78, v8
	global_load_dwordx4 v[0:3], v[8:9], off
	s_nop 0
	global_load_dwordx4 v[4:7], v[4:5], off
	v_addc_co_u32_e32 v11, vcc, 0, v9, vcc
	v_add_co_u32_e32 v12, vcc, s59, v8
	s_nop 1
	v_addc_co_u32_e32 v13, vcc, 0, v9, vcc
	global_load_dwordx4 v[8:11], v[10:11], off
	s_nop 0
	global_load_dwordx4 v[12:15], v[12:13], off
.LBB0_780:
	s_andn2_b64 vcc, exec, s[24:25]
	s_waitcnt lgkmcnt(0)
	s_barrier
	s_cbranch_vccnz .LBB0_775
	s_ashr_i32 s24, s3, 31
	s_lshr_b32 s24, s24, 29
	ds_read2_b32 v[22:23], v20 offset1:65
	ds_read2_b32 v[24:25], v20 offset0:130 offset1:195
	v_add_u32_e32 v21, 0x400, v20
	s_add_i32 s24, s3, s24
	s_waitcnt lgkmcnt(0)
	v_cvt_pk_bf16_f32 v22, v22, v23
	v_cvt_pk_bf16_f32 v23, v24, v25
	ds_read2_b32 v[24:25], v21 offset0:4 offset1:69
	ds_read2_b32 v[26:27], v21 offset0:134 offset1:199
	v_add_u32_e32 v21, 0x800, v20
	s_and_b32 s25, s24, 0x3fffff8
	s_waitcnt lgkmcnt(0)
	v_cvt_pk_bf16_f32 v24, v24, v25
	v_cvt_pk_bf16_f32 v25, v26, v27
	ds_read2_b32 v[26:27], v21 offset0:8 offset1:73
	ds_read2_b32 v[28:29], v21 offset0:138 offset1:203
	v_add_u32_e32 v21, 0xc00, v20
	s_lshl_b32 s24, s24, 3
	s_waitcnt lgkmcnt(0)
	v_cvt_pk_bf16_f32 v26, v26, v27
	v_cvt_pk_bf16_f32 v27, v28, v29
	ds_read2_b32 v[28:29], v21 offset0:12 offset1:77
	ds_read2_b32 v[30:31], v21 offset0:142 offset1:207
	s_andn2_b32 s24, s24, 63
	s_waitcnt lgkmcnt(0)
	v_cvt_pk_bf16_f32 v28, v28, v29
	v_cvt_pk_bf16_f32 v29, v30, v31
	v_add_u32_e32 v30, s24, v18
	s_sub_i32 s3, s3, s25
	v_ashrrev_i32_e32 v31, 31, v30
	v_lshlrev_b64 v[30:31], 10, v[30:31]
	s_lshl_b32 s24, s3, 6
	v_lshl_add_u64 v[30:31], s[22:23], 0, v[30:31]
	s_ashr_i32 s25, s24, 31
	v_lshl_add_u64 v[30:31], s[24:25], 1, v[30:31]
	v_lshl_add_u64 v[30:31], v[30:31], 0, v[144:145]
	global_store_dwordx4 v[30:31], v[22:25], off
	global_store_dwordx4 v[30:31], v[26:29], off offset:16
	s_branch .LBB0_775
.LBB0_782:
	s_mul_hi_u32 s3, s36, 0xe80
	s_mul_i32 s3, s3, s34
	s_sub_i32 s3, 0xe80, s3
	s_sub_i32 s6, s3, s34
	s_cmp_ge_u32 s3, s34
	s_cselect_b32 s3, s6, s3
	s_sub_i32 s6, s3, s34
	s_cmp_ge_u32 s3, s34
	s_cselect_b32 s3, s6, s3
	s_sub_i32 s3, s35, s3
	s_ashr_i32 s6, s3, 31
	s_abs_i32 s3, s3
	s_mul_hi_u32 s7, s3, s36
	s_mul_i32 s7, s7, s34
	s_sub_i32 s3, s3, s7
	s_sub_i32 s7, s3, s34
	s_cmp_ge_u32 s3, s34
	s_cselect_b32 s3, s7, s3
	s_sub_i32 s7, s3, s34
	s_cmp_ge_u32 s3, s34
	v_readlane_b32 s40, v254, 6
	s_cselect_b32 s3, s7, s3
	v_readlane_b32 s52, v254, 18
	v_readlane_b32 s53, v254, 19
	s_xor_b32 s3, s3, s6
	s_mov_b64 s[22:23], s[52:53]
	v_mov_b32_e32 v20, v191
	s_sub_i32 s3, s3, s6
	s_waitcnt vmcnt(0) lgkmcnt(0)
	v_mov_b32_e32 v0, 0
	s_cmpk_gt_i32 s3, 0x7f
	v_lshlrev_b32_e32 v17, 2, v20
	v_ashrrev_i32_e32 v16, 4, v20
	v_mov_b32_e32 v1, v0
	v_mov_b32_e32 v2, v0
	v_mov_b32_e32 v3, v0
	v_mov_b32_e32 v4, v0
	v_mov_b32_e32 v5, v0
	v_mov_b32_e32 v6, v0
	v_mov_b32_e32 v7, v0
	v_mov_b32_e32 v8, v0
	v_mov_b32_e32 v9, v0
	v_mov_b32_e32 v10, v0
	v_mov_b32_e32 v11, v0
	v_mov_b32_e32 v12, v0
	v_mov_b32_e32 v13, v0
	v_mov_b32_e32 v14, v0
	v_mov_b32_e32 v15, v0
	v_readlane_b32 s41, v254, 7
	v_readlane_b32 s42, v254, 8
	v_readlane_b32 s43, v254, 9
	v_readlane_b32 s44, v254, 10
	v_readlane_b32 s45, v254, 11
	v_readlane_b32 s46, v254, 12
	v_readlane_b32 s47, v254, 13
	v_readlane_b32 s48, v254, 14
	v_readlane_b32 s49, v254, 15
	v_readlane_b32 s50, v254, 16
	v_readlane_b32 s51, v254, 17
	v_readlane_b32 s54, v254, 20
	v_readlane_b32 s55, v254, 21
	s_cbranch_scc1 .LBB0_784
	s_ashr_i32 s6, s3, 31
	s_lshr_b32 s6, s6, 29
	s_add_i32 s6, s3, s6
	s_and_b32 s7, s6, 0x3fffff8
	s_lshl_b32 s6, s6, 3
	s_sub_i32 s7, s3, s7
	s_andn2_b32 s6, s6, 63
	v_and_or_b32 v0, v17, 60, s6
	v_lshl_add_u32 v2, s7, 6, v16
	v_ashrrev_i32_e32 v1, 31, v0
	v_ashrrev_i32_e32 v3, 31, v2
	v_lshl_add_u64 v[0:1], v[0:1], 2, s[22:23]
	v_lshlrev_b64 v[2:3], 12, v[2:3]
	v_lshl_add_u64 v[8:9], v[0:1], 0, v[2:3]
	v_add_co_u32_e32 v4, vcc, s81, v8
	s_nop 1
	v_addc_co_u32_e32 v5, vcc, 0, v9, vcc
	v_add_co_u32_e32 v10, vcc, s78, v8
	global_load_dwordx4 v[0:3], v[8:9], off
	s_nop 0
	global_load_dwordx4 v[4:7], v[4:5], off
	v_addc_co_u32_e32 v11, vcc, 0, v9, vcc
	v_add_co_u32_e32 v12, vcc, s59, v8
	s_nop 1
	v_addc_co_u32_e32 v13, vcc, 0, v9, vcc
	global_load_dwordx4 v[8:11], v[10:11], off
	s_nop 0
	global_load_dwordx4 v[12:15], v[12:13], off
.LBB0_784:
	v_cndmask_b32_e64 v18, 0, 1, s[8:9]
	v_cmp_ne_u32_e64 s[6:7], 1, v18
	s_andn2_b64 vcc, exec, s[8:9]
	s_cbranch_vccnz .LBB0_793
	v_and_b32_e32 v17, 60, v17
	v_lshlrev_b32_e32 v19, 4, v20
	v_and_b32_e32 v22, 48, v19
	v_mul_lo_u32 v19, v16, s58
	v_lshlrev_b32_e32 v21, 2, v17
	s_add_u32 s8, s12, 0x1d00000
	v_ashrrev_i32_e32 v18, 2, v20
	v_add3_u32 v19, s60, v19, v21
	v_mul_u32_u24_e32 v21, 0x104, v22
	v_and_b32_e32 v20, -4, v20
	s_addc_u32 s9, s13, 0
	v_add3_u32 v20, s60, v21, v20
	v_lshlrev_b32_e32 v144, 1, v22
	s_mov_b32 s26, s2
	s_mov_b32 s98, 0
	s_branch .LBB0_787

.LBB0_789:
	s_add_i32 s27, s0, s3
	s_cmpk_gt_i32 s27, 0x7f
	s_cbranch_scc1 .LBB0_791
	s_ashr_i32 s28, s27, 31
	s_lshr_b32 s28, s28, 29
	s_add_i32 s28, s27, s28
	s_and_b32 s29, s28, 0x3fffff8
	s_lshl_b32 s28, s28, 3
	s_sub_i32 s29, s27, s29
	s_andn2_b32 s28, s28, 63
	s_waitcnt vmcnt(2)
	v_or_b32_e32 v0, s28, v17
	v_lshl_add_u32 v2, s29, 6, v16
	v_ashrrev_i32_e32 v1, 31, v0
	v_ashrrev_i32_e32 v3, 31, v2
	v_lshl_add_u64 v[0:1], v[0:1], 2, s[22:23]
	v_lshlrev_b64 v[2:3], 12, v[2:3]
	v_lshl_add_u64 v[8:9], v[0:1], 0, v[2:3]
	v_add_co_u32_e32 v4, vcc, s81, v8
	s_nop 1
	v_addc_co_u32_e32 v5, vcc, 0, v9, vcc
	v_add_co_u32_e32 v10, vcc, s78, v8
	global_load_dwordx4 v[0:3], v[8:9], off
	s_nop 0
	global_load_dwordx4 v[4:7], v[4:5], off
	v_addc_co_u32_e32 v11, vcc, 0, v9, vcc
	v_add_co_u32_e32 v12, vcc, s59, v8
	s_nop 1
	v_addc_co_u32_e32 v13, vcc, 0, v9, vcc
	global_load_dwordx4 v[8:11], v[10:11], off
	s_nop 0
	global_load_dwordx4 v[12:15], v[12:13], off
.LBB0_791:
	s_andn2_b64 vcc, exec, s[24:25]
	s_waitcnt lgkmcnt(0)
	s_barrier
	s_cbranch_vccnz .LBB0_786
	s_ashr_i32 s24, s3, 31
	s_lshr_b32 s24, s24, 29
	ds_read2_b32 v[22:23], v20 offset1:65
	ds_read2_b32 v[24:25], v20 offset0:130 offset1:195
	v_add_u32_e32 v21, 0x400, v20
	s_add_i32 s24, s3, s24
	s_waitcnt lgkmcnt(0)
	v_cvt_pk_bf16_f32 v22, v22, v23
	v_cvt_pk_bf16_f32 v23, v24, v25
	ds_read2_b32 v[24:25], v21 offset0:4 offset1:69
	ds_read2_b32 v[26:27], v21 offset0:134 offset1:199
	v_add_u32_e32 v21, 0x800, v20
	s_and_b32 s25, s24, 0x3fffff8
	s_waitcnt lgkmcnt(0)
	v_cvt_pk_bf16_f32 v24, v24, v25
	v_cvt_pk_bf16_f32 v25, v26, v27
	ds_read2_b32 v[26:27], v21 offset0:8 offset1:73
	ds_read2_b32 v[28:29], v21 offset0:138 offset1:203
	v_add_u32_e32 v21, 0xc00, v20
	s_lshl_b32 s24, s24, 3
	s_waitcnt lgkmcnt(0)
	v_cvt_pk_bf16_f32 v26, v26, v27
	v_cvt_pk_bf16_f32 v27, v28, v29
	ds_read2_b32 v[28:29], v21 offset0:12 offset1:77
	ds_read2_b32 v[30:31], v21 offset0:142 offset1:207
	s_andn2_b32 s24, s24, 63
	s_waitcnt lgkmcnt(0)
	v_cvt_pk_bf16_f32 v28, v28, v29
	v_cvt_pk_bf16_f32 v29, v30, v31
	v_add_u32_e32 v30, s24, v18
	s_sub_i32 s3, s3, s25
	v_ashrrev_i32_e32 v31, 31, v30
	v_lshlrev_b64 v[30:31], 10, v[30:31]
	s_lshl_b32 s24, s3, 6
	v_lshl_add_u64 v[30:31], s[8:9], 0, v[30:31]
	s_ashr_i32 s25, s24, 31
	v_lshl_add_u64 v[30:31], s[24:25], 1, v[30:31]
	v_lshl_add_u64 v[30:31], v[30:31], 0, v[144:145]
	global_store_dwordx4 v[30:31], v[22:25], off
	global_store_dwordx4 v[30:31], v[26:29], off offset:16
	s_branch .LBB0_786
.LBB0_793:
	s_mul_hi_u32 s3, s36, 0xf00
	s_mul_i32 s3, s3, s34
	s_sub_i32 s3, 0xf00, s3
	s_sub_i32 s22, s3, s34
	s_cmp_ge_u32 s3, s34
	s_cselect_b32 s3, s22, s3
	s_sub_i32 s22, s3, s34
	s_cmp_ge_u32 s3, s34
	s_cselect_b32 s3, s22, s3
	s_sub_i32 s3, s35, s3
	s_ashr_i32 s22, s3, 31
	s_abs_i32 s3, s3
	s_mul_hi_u32 s23, s3, s36
	s_mul_i32 s23, s23, s34
	s_sub_i32 s3, s3, s23
	s_sub_i32 s23, s3, s34
	s_cmp_ge_u32 s3, s34
	s_cselect_b32 s3, s23, s3
	s_sub_i32 s23, s3, s34
	s_cmp_ge_u32 s3, s34
	v_readlane_b32 s40, v254, 22
	s_cselect_b32 s3, s23, s3
	v_readlane_b32 s52, v254, 34
	v_readlane_b32 s53, v254, 35
	s_xor_b32 s3, s3, s22
	s_mov_b64 s[8:9], s[52:53]
	v_mov_b32_e32 v20, v191
	s_sub_i32 s3, s3, s22
	s_waitcnt vmcnt(0) lgkmcnt(0)
	v_mov_b32_e32 v0, 0
	s_cmpk_gt_i32 s3, 0x7f
	v_lshlrev_b32_e32 v17, 2, v20
	v_ashrrev_i32_e32 v16, 4, v20
	v_mov_b32_e32 v1, v0
	v_mov_b32_e32 v2, v0
	v_mov_b32_e32 v3, v0
	v_mov_b32_e32 v4, v0
	v_mov_b32_e32 v5, v0
	v_mov_b32_e32 v6, v0
	v_mov_b32_e32 v7, v0
	v_mov_b32_e32 v8, v0
	v_mov_b32_e32 v9, v0
	v_mov_b32_e32 v10, v0
	v_mov_b32_e32 v11, v0
	v_mov_b32_e32 v12, v0
	v_mov_b32_e32 v13, v0
	v_mov_b32_e32 v14, v0
	v_mov_b32_e32 v15, v0
	v_readlane_b32 s41, v254, 23
	v_readlane_b32 s42, v254, 24
	v_readlane_b32 s43, v254, 25
	v_readlane_b32 s44, v254, 26
	v_readlane_b32 s45, v254, 27
	v_readlane_b32 s46, v254, 28
	v_readlane_b32 s47, v254, 29
	v_readlane_b32 s48, v254, 30
	v_readlane_b32 s49, v254, 31
	v_readlane_b32 s50, v254, 32
	v_readlane_b32 s51, v254, 33
	v_readlane_b32 s54, v254, 36
	v_readlane_b32 s55, v254, 37
	s_cbranch_scc1 .LBB0_795
	s_ashr_i32 s22, s3, 31
	s_lshr_b32 s22, s22, 29
	s_add_i32 s22, s3, s22
	s_and_b32 s23, s22, 0x3fffff8
	s_lshl_b32 s22, s22, 3
	s_sub_i32 s23, s3, s23
	s_andn2_b32 s22, s22, 63
	v_and_or_b32 v0, v17, 60, s22
	v_lshl_add_u32 v2, s23, 6, v16
	v_ashrrev_i32_e32 v1, 31, v0
	v_ashrrev_i32_e32 v3, 31, v2
	v_lshl_add_u64 v[0:1], v[0:1], 2, s[8:9]
	v_lshlrev_b64 v[2:3], 12, v[2:3]
	v_lshl_add_u64 v[8:9], v[0:1], 0, v[2:3]
	v_add_co_u32_e32 v4, vcc, s81, v8
	s_nop 1
	v_addc_co_u32_e32 v5, vcc, 0, v9, vcc
	v_add_co_u32_e32 v10, vcc, s78, v8
	global_load_dwordx4 v[0:3], v[8:9], off
	s_nop 0
	global_load_dwordx4 v[4:7], v[4:5], off
	v_addc_co_u32_e32 v11, vcc, 0, v9, vcc
	v_add_co_u32_e32 v12, vcc, s59, v8
	s_nop 1
	v_addc_co_u32_e32 v13, vcc, 0, v9, vcc
	global_load_dwordx4 v[8:11], v[10:11], off
	s_nop 0
	global_load_dwordx4 v[12:15], v[12:13], off
.LBB0_795:
	s_and_b64 vcc, exec, s[6:7]
	s_cbranch_vccnz .LBB0_804
	v_and_b32_e32 v17, 60, v17
	v_lshlrev_b32_e32 v19, 4, v20
	v_and_b32_e32 v22, 48, v19
	v_mul_lo_u32 v19, v16, s58
	v_lshlrev_b32_e32 v21, 2, v17
	s_add_u32 s6, s12, 0x1e00000
	v_ashrrev_i32_e32 v18, 2, v20
	v_add3_u32 v19, s60, v19, v21
	v_mul_u32_u24_e32 v21, 0x104, v22
	v_and_b32_e32 v20, -4, v20
	s_addc_u32 s7, s13, 0
	v_add3_u32 v20, s60, v21, v20
	v_lshlrev_b32_e32 v144, 1, v22
	s_mov_b32 s98, 0
	s_branch .LBB0_798

.LBB0_798:
	s_cmpk_lt_i32 s3, 0x80
	s_cselect_b64 s[22:23], -1, 0
	s_cmpk_gt_i32 s3, 0x7f
	s_waitcnt lgkmcnt(0)
	s_barrier
	s_cbranch_scc1 .LBB0_800
	v_add_u32_e32 v21, 0x1040, v19
	s_cmp_eq_u32 s98, 0
	s_cbranch_scc1 .Lcvw17_f
	s_waitcnt vmcnt(2)
	s_branch .Lcvw17_d

.LBB0_800:
	s_add_i32 s24, s0, s3
	s_cmpk_gt_i32 s24, 0x7f
	s_cbranch_scc1 .LBB0_802
	s_ashr_i32 s25, s24, 31
	s_lshr_b32 s25, s25, 29
	s_add_i32 s25, s24, s25
	s_and_b32 s26, s25, 0x3fffff8
	s_lshl_b32 s25, s25, 3
	s_sub_i32 s26, s24, s26
	s_andn2_b32 s25, s25, 63
	s_waitcnt vmcnt(2)
	v_or_b32_e32 v0, s25, v17
	v_lshl_add_u32 v2, s26, 6, v16
	v_ashrrev_i32_e32 v1, 31, v0
	v_ashrrev_i32_e32 v3, 31, v2
	v_lshl_add_u64 v[0:1], v[0:1], 2, s[8:9]
	v_lshlrev_b64 v[2:3], 12, v[2:3]
	v_lshl_add_u64 v[8:9], v[0:1], 0, v[2:3]
	v_add_co_u32_e32 v4, vcc, s81, v8
	s_nop 1
	v_addc_co_u32_e32 v5, vcc, 0, v9, vcc
	v_add_co_u32_e32 v10, vcc, s78, v8
	global_load_dwordx4 v[0:3], v[8:9], off
	s_nop 0
	global_load_dwordx4 v[4:7], v[4:5], off
	v_addc_co_u32_e32 v11, vcc, 0, v9, vcc
	v_add_co_u32_e32 v12, vcc, s59, v8
	s_nop 1
	v_addc_co_u32_e32 v13, vcc, 0, v9, vcc
	global_load_dwordx4 v[8:11], v[10:11], off
	s_nop 0
	global_load_dwordx4 v[12:15], v[12:13], off
.LBB0_802:
	s_andn2_b64 vcc, exec, s[22:23]
	s_waitcnt lgkmcnt(0)
	s_barrier
	s_cbranch_vccnz .LBB0_797
	s_ashr_i32 s22, s3, 31
	s_lshr_b32 s22, s22, 29
	ds_read2_b32 v[22:23], v20 offset1:65
	ds_read2_b32 v[24:25], v20 offset0:130 offset1:195
	v_add_u32_e32 v21, 0x400, v20
	s_add_i32 s22, s3, s22
	s_waitcnt lgkmcnt(0)
	v_cvt_pk_bf16_f32 v22, v22, v23
	v_cvt_pk_bf16_f32 v23, v24, v25
	ds_read2_b32 v[24:25], v21 offset0:4 offset1:69
	ds_read2_b32 v[26:27], v21 offset0:134 offset1:199
	v_add_u32_e32 v21, 0x800, v20
	s_and_b32 s23, s22, 0x3fffff8
	s_waitcnt lgkmcnt(0)
	v_cvt_pk_bf16_f32 v24, v24, v25
	v_cvt_pk_bf16_f32 v25, v26, v27
	ds_read2_b32 v[26:27], v21 offset0:8 offset1:73
	ds_read2_b32 v[28:29], v21 offset0:138 offset1:203
	v_add_u32_e32 v21, 0xc00, v20
	s_lshl_b32 s22, s22, 3
	s_waitcnt lgkmcnt(0)
	v_cvt_pk_bf16_f32 v26, v26, v27
	v_cvt_pk_bf16_f32 v27, v28, v29
	ds_read2_b32 v[28:29], v21 offset0:12 offset1:77
	ds_read2_b32 v[30:31], v21 offset0:142 offset1:207
	s_andn2_b32 s22, s22, 63
	s_waitcnt lgkmcnt(0)
	v_cvt_pk_bf16_f32 v28, v28, v29
	v_cvt_pk_bf16_f32 v29, v30, v31
	v_add_u32_e32 v30, s22, v18
	s_sub_i32 s3, s3, s23
	v_ashrrev_i32_e32 v31, 31, v30
	v_lshlrev_b64 v[30:31], 10, v[30:31]
	s_lshl_b32 s22, s3, 6
	v_lshl_add_u64 v[30:31], s[6:7], 0, v[30:31]
	s_ashr_i32 s23, s22, 31
	v_lshl_add_u64 v[30:31], s[22:23], 1, v[30:31]
	v_lshl_add_u64 v[30:31], v[30:31], 0, v[144:145]
	global_store_dwordx4 v[30:31], v[22:25], off
	global_store_dwordx4 v[30:31], v[26:29], off offset:16
	s_branch .LBB0_797
.LBB0_804:
	s_mul_hi_u32 s2, s36, 0xf80
	s_mul_i32 s2, s2, s34
	s_sub_i32 s2, 0xf80, s2
	s_sub_i32 s3, s2, s34
	s_cmp_ge_u32 s2, s34
	s_cselect_b32 s2, s3, s2
	s_sub_i32 s3, s2, s34
	s_cmp_ge_u32 s2, s34
	s_cselect_b32 s2, s3, s2
	s_sub_i32 s2, s35, s2
	s_ashr_i32 s3, s2, 31
	s_abs_i32 s2, s2
	s_mul_hi_u32 s8, s2, s36
	s_mul_i32 s8, s8, s34
	s_sub_i32 s2, s2, s8
	s_sub_i32 s8, s2, s34
	s_cmp_ge_u32 s2, s34
	s_cselect_b32 s2, s8, s2
	s_sub_i32 s8, s2, s34
	s_cmp_ge_u32 s2, s34
	v_readlane_b32 s40, v254, 22
	s_cselect_b32 s2, s8, s2
	v_readlane_b32 s54, v254, 36
	v_readlane_b32 s55, v254, 37
	s_xor_b32 s2, s2, s3
	s_mov_b64 s[6:7], s[54:55]
	v_mov_b32_e32 v20, v191
	s_sub_i32 s2, s2, s3
	s_waitcnt vmcnt(0) lgkmcnt(0)
	v_mov_b32_e32 v0, 0
	s_cmpk_gt_i32 s2, 0xff
	v_lshlrev_b32_e32 v17, 2, v20
	v_ashrrev_i32_e32 v16, 4, v20
	v_mov_b32_e32 v1, v0
	v_mov_b32_e32 v2, v0
	v_mov_b32_e32 v3, v0
	v_mov_b32_e32 v4, v0
	v_mov_b32_e32 v5, v0
	v_mov_b32_e32 v6, v0
	v_mov_b32_e32 v7, v0
	v_mov_b32_e32 v8, v0
	v_mov_b32_e32 v9, v0
	v_mov_b32_e32 v10, v0
	v_mov_b32_e32 v11, v0
	v_mov_b32_e32 v12, v0
	v_mov_b32_e32 v13, v0
	v_mov_b32_e32 v14, v0
	v_mov_b32_e32 v15, v0
	v_readlane_b32 s41, v254, 23
	v_readlane_b32 s42, v254, 24
	v_readlane_b32 s43, v254, 25
	v_readlane_b32 s44, v254, 26
	v_readlane_b32 s45, v254, 27
	v_readlane_b32 s46, v254, 28
	v_readlane_b32 s47, v254, 29
	v_readlane_b32 s48, v254, 30
	v_readlane_b32 s49, v254, 31
	v_readlane_b32 s50, v254, 32
	v_readlane_b32 s51, v254, 33
	v_readlane_b32 s52, v254, 34
	v_readlane_b32 s53, v254, 35
	s_cbranch_scc1 .LBB0_806
	s_ashr_i32 s3, s2, 31
	s_lshr_b32 s3, s3, 28
	s_add_i32 s3, s2, s3
	s_and_b32 s8, s3, 0x3fffff0
	s_lshl_b32 s3, s3, 2
	s_sub_i32 s8, s2, s8
	s_andn2_b32 s3, s3, 63
	v_and_or_b32 v0, v17, 60, s3
	v_lshl_add_u32 v2, s8, 6, v16
	v_ashrrev_i32_e32 v1, 31, v0
	v_ashrrev_i32_e32 v3, 31, v2
	v_lshl_add_u64 v[0:1], v[0:1], 2, s[6:7]
	v_lshlrev_b64 v[2:3], 12, v[2:3]
	v_lshl_add_u64 v[8:9], v[0:1], 0, v[2:3]
	v_add_co_u32_e32 v4, vcc, s81, v8
	s_nop 1
	v_addc_co_u32_e32 v5, vcc, 0, v9, vcc
	v_add_co_u32_e32 v10, vcc, s78, v8
	global_load_dwordx4 v[0:3], v[8:9], off
	s_nop 0
	global_load_dwordx4 v[4:7], v[4:5], off
	v_addc_co_u32_e32 v11, vcc, 0, v9, vcc
	v_add_co_u32_e32 v12, vcc, s59, v8
	s_nop 1
	v_addc_co_u32_e32 v13, vcc, 0, v9, vcc
	global_load_dwordx4 v[8:11], v[10:11], off
	s_nop 0
	global_load_dwordx4 v[12:15], v[12:13], off
.LBB0_806:
	s_add_i32 s3, s0, 0xff
	s_sub_i32 s9, 0xffffff01, s0
	s_ashr_i32 s8, s3, 31
	s_max_i32 s3, s3, s9
	s_mul_hi_u32 s9, s3, s36
	s_mul_i32 s22, s9, s34
	s_sub_i32 s3, s3, s22
	s_xor_b32 s8, s8, s39
	s_add_i32 s22, s9, 1
	s_sub_i32 s23, s3, s34
	s_cmp_ge_u32 s3, s34
	s_cselect_b32 s9, s22, s9
	s_cselect_b32 s3, s23, s3
	s_add_i32 s22, s9, 1
	s_cmp_ge_u32 s3, s34
	s_cselect_b32 s3, s22, s9
	s_xor_b32 s3, s3, s8
	s_sub_i32 s56, s3, s8
	s_cmp_gt_i32 s56, 0
	s_cselect_b64 s[8:9], -1, 0
	s_cmp_lt_i32 s56, 1
	s_cbranch_scc1 .LBB0_815
	v_and_b32_e32 v17, 60, v17
	v_lshlrev_b32_e32 v19, 4, v20
	v_and_b32_e32 v22, 48, v19
	v_mul_lo_u32 v19, v16, s58
	v_lshlrev_b32_e32 v21, 2, v17
	s_add_u32 s22, s12, 0x1f00000
	v_ashrrev_i32_e32 v18, 2, v20
	v_add3_u32 v19, s60, v19, v21
	v_mul_u32_u24_e32 v21, 0x104, v22
	v_and_b32_e32 v20, -4, v20
	s_addc_u32 s23, s13, 0
	v_add3_u32 v20, s60, v21, v20
	v_lshlrev_b32_e32 v144, 1, v22
	s_mov_b32 s3, s56
	s_mov_b32 s98, 0
	s_branch .LBB0_809

.LBB0_809:
	s_cmpk_lt_i32 s2, 0x100
	s_cselect_b64 s[24:25], -1, 0
	s_cmpk_gt_i32 s2, 0xff
	s_waitcnt lgkmcnt(0)
	s_barrier
	s_cbranch_scc1 .LBB0_811
	v_add_u32_e32 v21, 0x1040, v19
	s_cmp_eq_u32 s98, 0
	s_cbranch_scc1 .Lcvw18_f
	s_waitcnt vmcnt(2)
	s_branch .Lcvw18_d

.LBB0_811:
	s_add_i32 s26, s0, s2
	s_cmpk_gt_i32 s26, 0xff
	s_cbranch_scc1 .LBB0_813
	s_ashr_i32 s27, s26, 31
	s_lshr_b32 s27, s27, 28
	s_add_i32 s27, s26, s27
	s_and_b32 s28, s27, 0x3fffff0
	s_lshl_b32 s27, s27, 2
	s_sub_i32 s28, s26, s28
	s_andn2_b32 s27, s27, 63
	s_waitcnt vmcnt(2)
	v_or_b32_e32 v0, s27, v17
	v_lshl_add_u32 v2, s28, 6, v16
	v_ashrrev_i32_e32 v1, 31, v0
	v_ashrrev_i32_e32 v3, 31, v2
	v_lshl_add_u64 v[0:1], v[0:1], 2, s[6:7]
	v_lshlrev_b64 v[2:3], 12, v[2:3]
	v_lshl_add_u64 v[8:9], v[0:1], 0, v[2:3]
	v_add_co_u32_e32 v4, vcc, s81, v8
	s_nop 1
	v_addc_co_u32_e32 v5, vcc, 0, v9, vcc
	v_add_co_u32_e32 v10, vcc, s78, v8
	global_load_dwordx4 v[0:3], v[8:9], off
	s_nop 0
	global_load_dwordx4 v[4:7], v[4:5], off
	v_addc_co_u32_e32 v11, vcc, 0, v9, vcc
	v_add_co_u32_e32 v12, vcc, s59, v8
	s_nop 1
	v_addc_co_u32_e32 v13, vcc, 0, v9, vcc
	global_load_dwordx4 v[8:11], v[10:11], off
	s_nop 0
	global_load_dwordx4 v[12:15], v[12:13], off
.LBB0_813:
	s_andn2_b64 vcc, exec, s[24:25]
	s_waitcnt lgkmcnt(0)
	s_barrier
	s_cbranch_vccnz .LBB0_808
	s_ashr_i32 s24, s2, 31
	s_lshr_b32 s24, s24, 28
	ds_read2_b32 v[22:23], v20 offset1:65
	ds_read2_b32 v[24:25], v20 offset0:130 offset1:195
	v_add_u32_e32 v21, 0x400, v20
	s_add_i32 s24, s2, s24
	s_waitcnt lgkmcnt(0)
	v_cvt_pk_bf16_f32 v22, v22, v23
	v_cvt_pk_bf16_f32 v23, v24, v25
	ds_read2_b32 v[24:25], v21 offset0:4 offset1:69
	ds_read2_b32 v[26:27], v21 offset0:134 offset1:199
	v_add_u32_e32 v21, 0x800, v20
	s_and_b32 s25, s24, 0x3fffff0
	s_waitcnt lgkmcnt(0)
	v_cvt_pk_bf16_f32 v24, v24, v25
	v_cvt_pk_bf16_f32 v25, v26, v27
	ds_read2_b32 v[26:27], v21 offset0:8 offset1:73
	ds_read2_b32 v[28:29], v21 offset0:138 offset1:203
	v_add_u32_e32 v21, 0xc00, v20
	s_lshl_b32 s24, s24, 2
	s_waitcnt lgkmcnt(0)
	v_cvt_pk_bf16_f32 v26, v26, v27
	v_cvt_pk_bf16_f32 v27, v28, v29
	ds_read2_b32 v[28:29], v21 offset0:12 offset1:77
	ds_read2_b32 v[30:31], v21 offset0:142 offset1:207
	s_andn2_b32 s24, s24, 63
	s_waitcnt lgkmcnt(0)
	v_cvt_pk_bf16_f32 v28, v28, v29
	v_cvt_pk_bf16_f32 v29, v30, v31
	v_add_u32_e32 v30, s24, v18
	s_sub_i32 s2, s2, s25
	v_ashrrev_i32_e32 v31, 31, v30
	v_lshlrev_b64 v[30:31], 11, v[30:31]
	s_lshl_b32 s24, s2, 6
	v_lshl_add_u64 v[30:31], s[22:23], 0, v[30:31]
	s_ashr_i32 s25, s24, 31
	v_lshl_add_u64 v[30:31], s[24:25], 1, v[30:31]
	v_lshl_add_u64 v[30:31], v[30:31], 0, v[144:145]
	global_store_dwordx4 v[30:31], v[22:25], off
	global_store_dwordx4 v[30:31], v[26:29], off offset:16
	s_branch .LBB0_808
.LBB0_815:
	s_mul_hi_u32 s2, s36, 0x1080
	s_mul_i32 s2, s2, s34
	s_sub_i32 s2, 0x1080, s2
	s_sub_i32 s3, s2, s34
	s_cmp_ge_u32 s2, s34
	s_cselect_b32 s2, s3, s2
	s_sub_i32 s3, s2, s34
	s_cmp_ge_u32 s2, s34
	s_cselect_b32 s2, s3, s2
	s_sub_i32 s2, s35, s2
	s_ashr_i32 s3, s2, 31
	s_abs_i32 s2, s2
	s_mul_hi_u32 s6, s2, s36
	s_mul_i32 s6, s6, s34
	s_sub_i32 s2, s2, s6
	s_sub_i32 s6, s2, s34
	s_cmp_ge_u32 s2, s34
	s_cselect_b32 s2, s6, s2
	s_sub_i32 s6, s2, s34
	s_cmp_ge_u32 s2, s34
	v_readlane_b32 s40, v254, 38
	s_cselect_b32 s2, s6, s2
	v_readlane_b32 s41, v254, 39
	v_readlane_b32 s44, v254, 42
	v_readlane_b32 s45, v254, 43
	s_xor_b32 s2, s2, s3
	s_mov_b64 s[22:23], s[44:45]
	s_mov_b64 s[24:25], s[40:41]
	v_mov_b32_e32 v22, v191
	s_sub_i32 s57, s2, s3
	s_waitcnt vmcnt(0) lgkmcnt(0)
	v_mov_b32_e32 v15, 0
	s_cmpk_gt_i32 s57, 0xff
	v_lshlrev_b32_e32 v19, 2, v22
	v_ashrrev_i32_e32 v18, 4, v22
	v_mov_b32_e32 v14, v15
	v_mov_b32_e32 v13, v15
	v_mov_b32_e32 v12, v15
	v_mov_b32_e32 v11, v15
	v_mov_b32_e32 v10, v15
	v_mov_b32_e32 v9, v15
	v_mov_b32_e32 v8, v15
	v_mov_b32_e32 v7, v15
	v_mov_b32_e32 v6, v15
	v_mov_b32_e32 v5, v15
	v_mov_b32_e32 v4, v15
	v_mov_b32_e32 v3, v15
	v_mov_b32_e32 v2, v15
	v_mov_b32_e32 v1, v15
	v_mov_b32_e32 v0, v15
	v_readlane_b32 s42, v254, 40
	v_readlane_b32 s43, v254, 41
	v_readlane_b32 s46, v254, 44
	v_readlane_b32 s47, v254, 45
	v_readlane_b32 s48, v254, 46
	v_readlane_b32 s49, v254, 47
	v_readlane_b32 s50, v254, 48
	v_readlane_b32 s51, v254, 49
	v_readlane_b32 s52, v254, 50
	v_readlane_b32 s53, v254, 51
	v_readlane_b32 s54, v254, 52
	v_readlane_b32 s55, v254, 53
	s_cbranch_scc1 .LBB0_824
	s_ashr_i32 s2, s57, 31
	s_lshr_b32 s2, s2, 28
	s_add_i32 s2, s57, s2
	s_and_b32 s3, s2, 0x3fffff0
	s_lshl_b32 s2, s2, 2
	s_sub_i32 s3, s57, s3
	s_andn2_b32 s2, s2, 63
	v_and_or_b32 v0, v19, 60, s2
	v_lshl_add_u32 v4, s3, 6, v18
	v_ashrrev_i32_e32 v1, 31, v0
	v_ashrrev_i32_e32 v5, 31, v4
	v_lshl_add_u64 v[0:1], v[0:1], 2, s[22:23]
	v_lshlrev_b64 v[2:3], 12, v[4:5]
	v_lshl_add_u64 v[12:13], v[0:1], 0, v[2:3]
	global_load_dwordx4 v[0:3], v[12:13], off
	s_cmp_lg_u64 s[24:25], 0
	s_cselect_b64 s[2:3], -1, 0
	s_cmp_eq_u64 s[24:25], 0
	v_lshl_add_u64 v[16:17], v[4:5], 2, s[24:25]
	s_cbranch_scc1 .LBB0_818
	global_load_dword v40, v[16:17], off
.LBB0_818:
	v_add_co_u32_e32 v4, vcc, 0x10000, v12
	v_cndmask_b32_e64 v8, 0, 1, s[2:3]
	s_nop 0
	v_addc_co_u32_e32 v5, vcc, 0, v13, vcc
	global_load_dwordx4 v[4:7], v[4:5], off
	v_cmp_ne_u32_e64 s[6:7], 1, v8
	s_andn2_b64 vcc, exec, s[2:3]
	s_cbranch_vccnz .LBB0_820
	global_load_dword v42, v[16:17], off offset:64
.LBB0_820:
	v_add_co_u32_e32 v8, vcc, 0x20000, v12
	s_nop 1
	v_addc_co_u32_e32 v9, vcc, 0, v13, vcc
	global_load_dwordx4 v[8:11], v[8:9], off
	s_and_b64 vcc, exec, s[6:7]
	s_cbranch_vccnz .LBB0_822
	global_load_dword v44, v[16:17], off offset:128
.LBB0_822:
	v_add_co_u32_e32 v12, vcc, 0x30000, v12
	s_nop 1
	v_addc_co_u32_e32 v13, vcc, 0, v13, vcc
	global_load_dwordx4 v[12:15], v[12:13], off
	s_and_b64 vcc, exec, s[6:7]
	s_cbranch_vccnz .LBB0_824
	global_load_dword v46, v[16:17], off offset:192
.LBB0_824:
	v_cndmask_b32_e64 v16, 0, 1, s[8:9]
	v_cmp_ne_u32_e64 s[6:7], 1, v16
	s_andn2_b64 vcc, exec, s[8:9]
	s_cbranch_vccnz .LBB0_840
	s_add_u32 s26, s12, 0x2100000
	v_and_b32_e32 v19, 60, v19
	v_lshlrev_b32_e32 v16, 4, v22
	s_addc_u32 s27, s13, 0
	v_and_b32_e32 v16, 48, v16
	v_mul_lo_u32 v17, v18, s58
	v_lshlrev_b32_e32 v21, 2, v19
	s_cmp_lg_u64 s[24:25], 0
	v_ashrrev_i32_e32 v20, 2, v22
	v_add3_u32 v21, s60, v17, v21
	v_mul_u32_u24_e32 v17, 0x104, v16
	v_and_b32_e32 v22, -4, v22
	s_cselect_b64 s[28:29], -1, 0
	v_add3_u32 v22, s60, v17, v22
	v_lshlrev_b32_e32 v144, 1, v16
	s_mov_b32 s2, s56
	s_mov_b32 s98, 0
	s_branch .LBB0_827

.LBB0_827:
	s_cmpk_lt_i32 s57, 0x100
	s_cselect_b64 s[30:31], -1, 0
	s_cmpk_gt_i32 s57, 0xff
	s_waitcnt lgkmcnt(0)
	s_barrier
	s_cbranch_scc1 .LBB0_829
	v_add_u32_e32 v16, 0x1040, v21
	s_cmp_eq_u32 s98, 0
	s_cbranch_scc1 .Lcvw19_f
	s_waitcnt vmcnt(2)
	s_branch .Lcvw19_d

.LBB0_829:
	s_add_i32 s3, s0, s57
	s_cmpk_gt_i32 s3, 0xff
	s_cbranch_scc1 .LBB0_838
	s_ashr_i32 s8, s3, 31
	s_lshr_b32 s8, s8, 28
	s_add_i32 s8, s3, s8
	s_and_b32 s9, s8, 0x3fffff0
	s_lshl_b32 s8, s8, 2
	s_sub_i32 s9, s3, s9
	s_andn2_b32 s8, s8, 63
	s_waitcnt vmcnt(2)
	v_or_b32_e32 v0, s8, v19
	v_lshl_add_u32 v4, s9, 6, v18
	v_ashrrev_i32_e32 v1, 31, v0
	v_ashrrev_i32_e32 v5, 31, v4
	v_lshl_add_u64 v[0:1], v[0:1], 2, s[22:23]
	v_lshlrev_b64 v[2:3], 12, v[4:5]
	v_lshl_add_u64 v[12:13], v[0:1], 0, v[2:3]
	global_load_dwordx4 v[0:3], v[12:13], off
	v_cndmask_b32_e64 v6, 0, 1, s[28:29]
	v_cmp_ne_u32_e64 s[8:9], 1, v6
	s_andn2_b64 vcc, exec, s[28:29]
	v_lshl_add_u64 v[16:17], v[4:5], 2, s[24:25]
	s_cbranch_vccnz .LBB0_832
	global_load_dword v40, v[16:17], off
.LBB0_832:
	v_add_co_u32_e32 v4, vcc, 0x10000, v12
	s_nop 1
	v_addc_co_u32_e32 v5, vcc, 0, v13, vcc
	global_load_dwordx4 v[4:7], v[4:5], off
	s_and_b64 vcc, exec, s[8:9]
	s_cbranch_vccnz .LBB0_834
	global_load_dword v42, v[16:17], off offset:64
.LBB0_834:
	v_add_co_u32_e32 v8, vcc, 0x20000, v12
	s_nop 1
	v_addc_co_u32_e32 v9, vcc, 0, v13, vcc
	global_load_dwordx4 v[8:11], v[8:9], off
	s_and_b64 vcc, exec, s[8:9]
	s_cbranch_vccnz .LBB0_836
	global_load_dword v44, v[16:17], off offset:128
.LBB0_836:
	v_add_co_u32_e32 v12, vcc, 0x30000, v12
	s_nop 1
	v_addc_co_u32_e32 v13, vcc, 0, v13, vcc
	global_load_dwordx4 v[12:15], v[12:13], off
	s_and_b64 vcc, exec, s[8:9]
	s_cbranch_vccnz .LBB0_838
	global_load_dword v46, v[16:17], off offset:192
.LBB0_838:
	s_andn2_b64 vcc, exec, s[30:31]
	s_waitcnt lgkmcnt(0)
	s_barrier
	s_cbranch_vccnz .LBB0_826
	ds_read2_b32 v[16:17], v22 offset1:65
	s_waitcnt lgkmcnt(0)
	v_cvt_pk_bf16_f32 v24, v16, v17
	ds_read2_b32 v[16:17], v22 offset0:130 offset1:195
	v_add_u32_e32 v23, 0x400, v22
	s_waitcnt lgkmcnt(0)
	v_cvt_pk_bf16_f32 v25, v16, v17
	ds_read2_b32 v[16:17], v23 offset0:4 offset1:69
	s_ashr_i32 s8, s57, 31
	s_waitcnt lgkmcnt(0)
	v_cvt_pk_bf16_f32 v26, v16, v17
	ds_read2_b32 v[16:17], v23 offset0:134 offset1:199
	v_add_u32_e32 v23, 0x800, v22
	s_lshr_b32 s8, s8, 28
	s_waitcnt lgkmcnt(0)
	v_cvt_pk_bf16_f32 v27, v16, v17
	ds_read2_b32 v[16:17], v23 offset0:8 offset1:73
	s_add_i32 s8, s57, s8
	s_waitcnt lgkmcnt(0)
	v_cvt_pk_bf16_f32 v28, v16, v17
	ds_read2_b32 v[16:17], v23 offset0:138 offset1:203
	v_add_u32_e32 v23, 0xc00, v22
	s_and_b32 s9, s8, 0x3fffff0
	s_waitcnt lgkmcnt(0)
	v_cvt_pk_bf16_f32 v29, v16, v17
	ds_read2_b32 v[16:17], v23 offset0:12 offset1:77
	s_lshl_b32 s8, s8, 2
	s_waitcnt lgkmcnt(0)
	v_cvt_pk_bf16_f32 v30, v16, v17
	ds_read2_b32 v[16:17], v23 offset0:142 offset1:207
	s_andn2_b32 s8, s8, 63
	s_waitcnt lgkmcnt(0)
	v_cvt_pk_bf16_f32 v31, v16, v17
	v_add_u32_e32 v16, s8, v20
	s_sub_i32 s9, s57, s9
	v_ashrrev_i32_e32 v17, 31, v16
	v_lshlrev_b64 v[16:17], 11, v[16:17]
	s_lshl_b32 s8, s9, 6
	v_lshl_add_u64 v[16:17], s[26:27], 0, v[16:17]
	s_ashr_i32 s9, s8, 31
	v_lshl_add_u64 v[16:17], s[8:9], 1, v[16:17]
	v_lshl_add_u64 v[16:17], v[16:17], 0, v[144:145]
	global_store_dwordx4 v[16:17], v[24:27], off
	global_store_dwordx4 v[16:17], v[28:31], off offset:16
	s_branch .LBB0_826
.LBB0_840:
	s_mul_hi_u32 s2, s36, 0x1180
	s_mul_i32 s2, s2, s34
	s_sub_i32 s2, 0x1180, s2
	s_sub_i32 s3, s2, s34
	s_cmp_ge_u32 s2, s34
	s_cselect_b32 s2, s3, s2
	s_sub_i32 s3, s2, s34
	s_cmp_ge_u32 s2, s34
	s_cselect_b32 s2, s3, s2
	s_sub_i32 s2, s35, s2
	s_ashr_i32 s3, s2, 31
	s_abs_i32 s2, s2
	s_mul_hi_u32 s22, s2, s36
	s_mul_i32 s22, s22, s34
	s_sub_i32 s2, s2, s22
	s_sub_i32 s22, s2, s34
	s_cmp_ge_u32 s2, s34
	s_cselect_b32 s2, s22, s2
	s_sub_i32 s22, s2, s34
	s_cmp_ge_u32 s2, s34
	v_readlane_b32 s40, v254, 38
	s_cselect_b32 s2, s22, s2
	v_readlane_b32 s46, v254, 44
	v_readlane_b32 s47, v254, 45
	s_xor_b32 s2, s2, s3
	s_mov_b64 s[8:9], s[46:47]
	v_mov_b32_e32 v20, v191
	s_sub_i32 s2, s2, s3
	s_waitcnt vmcnt(0) lgkmcnt(0)
	v_mov_b32_e32 v0, 0
	s_cmpk_gt_i32 s2, 0x1ff
	v_lshlrev_b32_e32 v17, 2, v20
	v_ashrrev_i32_e32 v16, 4, v20
	v_mov_b32_e32 v1, v0
	v_mov_b32_e32 v2, v0
	v_mov_b32_e32 v3, v0
	v_mov_b32_e32 v4, v0
	v_mov_b32_e32 v5, v0
	v_mov_b32_e32 v6, v0
	v_mov_b32_e32 v7, v0
	v_mov_b32_e32 v8, v0
	v_mov_b32_e32 v9, v0
	v_mov_b32_e32 v10, v0
	v_mov_b32_e32 v11, v0
	v_mov_b32_e32 v12, v0
	v_mov_b32_e32 v13, v0
	v_mov_b32_e32 v14, v0
	v_mov_b32_e32 v15, v0
	v_readlane_b32 s41, v254, 39
	v_readlane_b32 s42, v254, 40
	v_readlane_b32 s43, v254, 41
	v_readlane_b32 s44, v254, 42
	v_readlane_b32 s45, v254, 43
	v_readlane_b32 s48, v254, 46
	v_readlane_b32 s49, v254, 47
	v_readlane_b32 s50, v254, 48
	v_readlane_b32 s51, v254, 49
	v_readlane_b32 s52, v254, 50
	v_readlane_b32 s53, v254, 51
	v_readlane_b32 s54, v254, 52
	v_readlane_b32 s55, v254, 53
	s_cbranch_scc1 .LBB0_842
	s_ashr_i32 s3, s2, 31
	s_lshr_b32 s3, s3, 28
	s_add_i32 s3, s2, s3
	s_and_b32 s22, s3, 0x3fffff0
	s_lshl_b32 s3, s3, 2
	s_sub_i32 s22, s2, s22
	s_andn2_b32 s3, s3, 63
	v_and_or_b32 v0, v17, 60, s3
	v_lshl_add_u32 v2, s22, 6, v16
	v_ashrrev_i32_e32 v1, 31, v0
	v_ashrrev_i32_e32 v3, 31, v2
	v_lshl_add_u64 v[0:1], v[0:1], 2, s[8:9]
	v_lshlrev_b64 v[2:3], 13, v[2:3]
	v_lshl_add_u64 v[8:9], v[0:1], 0, v[2:3]
	v_add_co_u32_e32 v4, vcc, s78, v8
	s_nop 1
	v_addc_co_u32_e32 v5, vcc, 0, v9, vcc
	v_add_co_u32_e32 v10, vcc, s62, v8
	global_load_dwordx4 v[0:3], v[8:9], off
	s_nop 0
	global_load_dwordx4 v[4:7], v[4:5], off
	v_addc_co_u32_e32 v11, vcc, 0, v9, vcc
	v_add_co_u32_e32 v12, vcc, s63, v8
	s_nop 1
	v_addc_co_u32_e32 v13, vcc, 0, v9, vcc
	global_load_dwordx4 v[8:11], v[10:11], off
	s_nop 0
	global_load_dwordx4 v[12:15], v[12:13], off
.LBB0_842:
	s_add_i32 s3, s0, 0x1ff
	s_sub_i32 s23, 0xfffffe01, s0
	s_ashr_i32 s22, s3, 31
	s_max_i32 s3, s3, s23
	s_mul_hi_u32 s23, s3, s36
	s_mul_i32 s24, s23, s34
	s_sub_i32 s3, s3, s24
	s_xor_b32 s22, s22, s39
	s_add_i32 s24, s23, 1
	s_sub_i32 s25, s3, s34
	s_cmp_ge_u32 s3, s34
	s_cselect_b32 s23, s24, s23
	s_cselect_b32 s3, s25, s3
	s_add_i32 s24, s23, 1
	s_cmp_ge_u32 s3, s34
	s_cselect_b32 s3, s24, s23
	s_xor_b32 s3, s3, s22
	s_sub_i32 s3, s3, s22
	s_cmp_lt_i32 s3, 1
	s_cbranch_scc1 .LBB0_851
	v_and_b32_e32 v17, 60, v17
	v_lshlrev_b32_e32 v19, 4, v20
	v_and_b32_e32 v22, 48, v19
	v_mul_lo_u32 v19, v16, s58
	v_lshlrev_b32_e32 v21, 2, v17
	s_add_u32 s22, s12, 0x2300000
	v_ashrrev_i32_e32 v18, 2, v20
	v_add3_u32 v19, s60, v19, v21
	v_mul_u32_u24_e32 v21, 0x104, v22
	v_and_b32_e32 v20, -4, v20
	s_addc_u32 s23, s13, 0
	v_add3_u32 v20, s60, v21, v20
	v_lshlrev_b32_e32 v144, 1, v22
	s_mov_b32 s98, 0
	s_branch .LBB0_845

.LBB0_845:
	s_cmpk_lt_i32 s2, 0x200
	s_cselect_b64 s[24:25], -1, 0
	s_cmpk_gt_i32 s2, 0x1ff
	s_waitcnt lgkmcnt(0)
	s_barrier
	s_cbranch_scc1 .LBB0_847
	v_add_u32_e32 v21, 0x1040, v19
	s_cmp_eq_u32 s98, 0
	s_cbranch_scc1 .Lcvw20_f
	s_waitcnt vmcnt(2)
	s_branch .Lcvw20_d

.LBB0_847:
	s_add_i32 s26, s0, s2
	s_cmpk_gt_i32 s26, 0x1ff
	s_cbranch_scc1 .LBB0_849
	s_ashr_i32 s27, s26, 31
	s_lshr_b32 s27, s27, 28
	s_add_i32 s27, s26, s27
	s_and_b32 s28, s27, 0x3fffff0
	s_lshl_b32 s27, s27, 2
	s_sub_i32 s28, s26, s28
	s_andn2_b32 s27, s27, 63
	s_waitcnt vmcnt(2)
	v_or_b32_e32 v0, s27, v17
	v_lshl_add_u32 v2, s28, 6, v16
	v_ashrrev_i32_e32 v1, 31, v0
	v_ashrrev_i32_e32 v3, 31, v2
	v_lshl_add_u64 v[0:1], v[0:1], 2, s[8:9]
	v_lshlrev_b64 v[2:3], 13, v[2:3]
	v_lshl_add_u64 v[8:9], v[0:1], 0, v[2:3]
	v_add_co_u32_e32 v4, vcc, s78, v8
	s_nop 1
	v_addc_co_u32_e32 v5, vcc, 0, v9, vcc
	v_add_co_u32_e32 v10, vcc, s62, v8
	global_load_dwordx4 v[0:3], v[8:9], off
	s_nop 0
	global_load_dwordx4 v[4:7], v[4:5], off
	v_addc_co_u32_e32 v11, vcc, 0, v9, vcc
	v_add_co_u32_e32 v12, vcc, s63, v8
	s_nop 1
	v_addc_co_u32_e32 v13, vcc, 0, v9, vcc
	global_load_dwordx4 v[8:11], v[10:11], off
	s_nop 0
	global_load_dwordx4 v[12:15], v[12:13], off

.LBB0_851:
	s_mul_hi_u32 s2, s36, 0x1380
	s_mul_i32 s2, s2, s34
	s_sub_i32 s2, 0x1380, s2
	s_sub_i32 s3, s2, s34
	s_cmp_ge_u32 s2, s34
	s_cselect_b32 s2, s3, s2
	s_sub_i32 s3, s2, s34
	s_cmp_ge_u32 s2, s34
	s_cselect_b32 s2, s3, s2
	s_sub_i32 s2, s35, s2
	s_ashr_i32 s3, s2, 31
	s_abs_i32 s2, s2
	s_mul_hi_u32 s22, s2, s36
	s_mul_i32 s22, s22, s34
	s_sub_i32 s2, s2, s22
	s_sub_i32 s22, s2, s34
	s_cmp_ge_u32 s2, s34
	s_cselect_b32 s2, s22, s2
	s_sub_i32 s22, s2, s34
	s_cmp_ge_u32 s2, s34
	v_readlane_b32 s40, v254, 38
	s_cselect_b32 s2, s22, s2
	v_readlane_b32 s48, v254, 46
	v_readlane_b32 s49, v254, 47
	s_xor_b32 s2, s2, s3
	s_mov_b64 s[8:9], s[48:49]
	v_mov_b32_e32 v20, v191
	s_sub_i32 s2, s2, s3
	s_waitcnt vmcnt(0) lgkmcnt(0)
	v_mov_b32_e32 v0, 0
	s_cmpk_gt_i32 s2, 0xff
	v_lshlrev_b32_e32 v17, 2, v20
	v_ashrrev_i32_e32 v16, 4, v20
	v_mov_b32_e32 v1, v0
	v_mov_b32_e32 v2, v0
	v_mov_b32_e32 v3, v0
	v_mov_b32_e32 v4, v0
	v_mov_b32_e32 v5, v0
	v_mov_b32_e32 v6, v0
	v_mov_b32_e32 v7, v0
	v_mov_b32_e32 v8, v0
	v_mov_b32_e32 v9, v0
	v_mov_b32_e32 v10, v0
	v_mov_b32_e32 v11, v0
	v_mov_b32_e32 v12, v0
	v_mov_b32_e32 v13, v0
	v_mov_b32_e32 v14, v0
	v_mov_b32_e32 v15, v0
	v_readlane_b32 s41, v254, 39
	v_readlane_b32 s42, v254, 40
	v_readlane_b32 s43, v254, 41
	v_readlane_b32 s44, v254, 42
	v_readlane_b32 s45, v254, 43
	v_readlane_b32 s46, v254, 44
	v_readlane_b32 s47, v254, 45
	v_readlane_b32 s50, v254, 48
	v_readlane_b32 s51, v254, 49
	v_readlane_b32 s52, v254, 50
	v_readlane_b32 s53, v254, 51
	v_readlane_b32 s54, v254, 52
	v_readlane_b32 s55, v254, 53
	s_cbranch_scc1 .LBB0_853
	s_ashr_i32 s3, s2, 31
	s_lshr_b32 s3, s3, 28
	s_add_i32 s3, s2, s3
	s_and_b32 s22, s3, 0x3fffff0
	s_lshl_b32 s3, s3, 2
	s_sub_i32 s22, s2, s22
	s_andn2_b32 s3, s3, 63
	v_and_or_b32 v0, v17, 60, s3
	v_lshl_add_u32 v2, s22, 6, v16
	v_ashrrev_i32_e32 v1, 31, v0
	v_ashrrev_i32_e32 v3, 31, v2
	v_lshl_add_u64 v[0:1], v[0:1], 2, s[8:9]
	v_lshlrev_b64 v[2:3], 12, v[2:3]
	v_lshl_add_u64 v[8:9], v[0:1], 0, v[2:3]
	v_add_co_u32_e32 v4, vcc, s81, v8
	s_nop 1
	v_addc_co_u32_e32 v5, vcc, 0, v9, vcc
	v_add_co_u32_e32 v10, vcc, s78, v8
	global_load_dwordx4 v[0:3], v[8:9], off
	s_nop 0
	global_load_dwordx4 v[4:7], v[4:5], off
	v_addc_co_u32_e32 v11, vcc, 0, v9, vcc
	v_add_co_u32_e32 v12, vcc, s59, v8
	s_nop 1
	v_addc_co_u32_e32 v13, vcc, 0, v9, vcc
	global_load_dwordx4 v[8:11], v[10:11], off
	s_nop 0
	global_load_dwordx4 v[12:15], v[12:13], off
.LBB0_853:
	s_and_b64 vcc, exec, s[6:7]
	s_cbranch_vccnz .LBB0_862
	v_and_b32_e32 v17, 60, v17
	v_lshlrev_b32_e32 v19, 4, v20
	v_and_b32_e32 v22, 48, v19
	v_mul_lo_u32 v19, v16, s58
	v_lshlrev_b32_e32 v21, 2, v17
	s_add_u32 s6, s12, 0x2700000
	v_ashrrev_i32_e32 v18, 2, v20
	v_add3_u32 v19, s60, v19, v21
	v_mul_u32_u24_e32 v21, 0x104, v22
	v_and_b32_e32 v20, -4, v20
	s_addc_u32 s7, s13, 0
	v_add3_u32 v20, s60, v21, v20
	v_lshlrev_b32_e32 v144, 1, v22
	s_mov_b32 s98, 0
	s_branch .LBB0_856

.LBB0_856:
	s_cmpk_lt_i32 s2, 0x100
	s_cselect_b64 s[22:23], -1, 0
	s_cmpk_gt_i32 s2, 0xff
	s_waitcnt lgkmcnt(0)
	s_barrier
	s_cbranch_scc1 .LBB0_858
	v_add_u32_e32 v21, 0x1040, v19
	s_cmp_eq_u32 s98, 0
	s_cbranch_scc1 .Lcvw21_f
	s_waitcnt vmcnt(2)
	s_branch .Lcvw21_d

.LBB0_858:
	s_add_i32 s3, s0, s2
	s_cmpk_gt_i32 s3, 0xff
	s_cbranch_scc1 .LBB0_860
	s_ashr_i32 s24, s3, 31
	s_lshr_b32 s24, s24, 28
	s_add_i32 s24, s3, s24
	s_and_b32 s25, s24, 0x3fffff0
	s_lshl_b32 s24, s24, 2
	s_sub_i32 s25, s3, s25
	s_andn2_b32 s24, s24, 63
	s_waitcnt vmcnt(2)
	v_or_b32_e32 v0, s24, v17
	v_lshl_add_u32 v2, s25, 6, v16
	v_ashrrev_i32_e32 v1, 31, v0
	v_ashrrev_i32_e32 v3, 31, v2
	v_lshl_add_u64 v[0:1], v[0:1], 2, s[8:9]
	v_lshlrev_b64 v[2:3], 12, v[2:3]
	v_lshl_add_u64 v[8:9], v[0:1], 0, v[2:3]
	v_add_co_u32_e32 v4, vcc, s81, v8
	s_nop 1
	v_addc_co_u32_e32 v5, vcc, 0, v9, vcc
	v_add_co_u32_e32 v10, vcc, s78, v8
	global_load_dwordx4 v[0:3], v[8:9], off
	s_nop 0
	global_load_dwordx4 v[4:7], v[4:5], off
	v_addc_co_u32_e32 v11, vcc, 0, v9, vcc
	v_add_co_u32_e32 v12, vcc, s59, v8
	s_nop 1
	v_addc_co_u32_e32 v13, vcc, 0, v9, vcc
	global_load_dwordx4 v[8:11], v[10:11], off
	s_nop 0
	global_load_dwordx4 v[12:15], v[12:13], off
.LBB0_860:
	s_andn2_b64 vcc, exec, s[22:23]
	s_waitcnt lgkmcnt(0)
	s_barrier
	s_cbranch_vccnz .LBB0_855
	s_ashr_i32 s22, s2, 31
	s_lshr_b32 s22, s22, 28
	ds_read2_b32 v[22:23], v20 offset1:65
	ds_read2_b32 v[24:25], v20 offset0:130 offset1:195
	v_add_u32_e32 v21, 0x400, v20
	s_add_i32 s22, s2, s22
	s_waitcnt lgkmcnt(0)
	v_cvt_pk_bf16_f32 v22, v22, v23
	v_cvt_pk_bf16_f32 v23, v24, v25
	ds_read2_b32 v[24:25], v21 offset0:4 offset1:69
	ds_read2_b32 v[26:27], v21 offset0:134 offset1:199
	v_add_u32_e32 v21, 0x800, v20
	s_and_b32 s23, s22, 0x3fffff0
	s_waitcnt lgkmcnt(0)
	v_cvt_pk_bf16_f32 v24, v24, v25
	v_cvt_pk_bf16_f32 v25, v26, v27
	ds_read2_b32 v[26:27], v21 offset0:8 offset1:73
	ds_read2_b32 v[28:29], v21 offset0:138 offset1:203
	v_add_u32_e32 v21, 0xc00, v20
	s_lshl_b32 s22, s22, 2
	s_waitcnt lgkmcnt(0)
	v_cvt_pk_bf16_f32 v26, v26, v27
	v_cvt_pk_bf16_f32 v27, v28, v29
	ds_read2_b32 v[28:29], v21 offset0:12 offset1:77
	ds_read2_b32 v[30:31], v21 offset0:142 offset1:207
	s_andn2_b32 s22, s22, 63
	s_waitcnt lgkmcnt(0)
	v_cvt_pk_bf16_f32 v28, v28, v29
	v_cvt_pk_bf16_f32 v29, v30, v31
	v_add_u32_e32 v30, s22, v18
	s_sub_i32 s2, s2, s23
	v_ashrrev_i32_e32 v31, 31, v30
	v_lshlrev_b64 v[30:31], 11, v[30:31]
	s_lshl_b32 s22, s2, 6
	v_lshl_add_u64 v[30:31], s[6:7], 0, v[30:31]
	s_ashr_i32 s23, s22, 31
	v_lshl_add_u64 v[30:31], s[22:23], 1, v[30:31]
	v_lshl_add_u64 v[30:31], v[30:31], 0, v[144:145]
	global_store_dwordx4 v[30:31], v[22:25], off
	global_store_dwordx4 v[30:31], v[26:29], off offset:16
	s_branch .LBB0_855
.LBB0_862:
	s_mul_hi_u32 s2, s36, 0x1480
	s_mul_i32 s2, s2, s34
	s_sub_i32 s2, 0x1480, s2
	s_sub_i32 s3, s2, s34
	s_cmp_ge_u32 s2, s34
	s_cselect_b32 s2, s3, s2
	s_sub_i32 s3, s2, s34
	s_cmp_ge_u32 s2, s34
	s_cselect_b32 s2, s3, s2
	s_sub_i32 s2, s35, s2
	s_ashr_i32 s3, s2, 31
	s_abs_i32 s2, s2
	s_mul_hi_u32 s6, s2, s36
	s_mul_i32 s6, s6, s34
	s_sub_i32 s2, s2, s6
	s_sub_i32 s6, s2, s34
	s_cmp_ge_u32 s2, s34
	s_cselect_b32 s2, s6, s2
	s_sub_i32 s6, s2, s34
	v_readlane_b32 s40, v254, 38
	s_cmp_ge_u32 s2, s34
	v_readlane_b32 s50, v254, 48
	v_readlane_b32 s51, v254, 49
	v_readlane_b32 s52, v254, 50
	v_readlane_b32 s53, v254, 51
	s_cselect_b32 s2, s6, s2
	s_mov_b64 s[22:23], s[52:53]
	s_mov_b64 s[24:25], s[50:51]
	v_mov_b32_e32 v24, v191
	s_xor_b32 s2, s2, s3
	s_sub_i32 s30, s2, s3
	s_waitcnt vmcnt(0) lgkmcnt(0)
	v_mov_b32_e32 v15, 0
	v_lshlrev_b32_e32 v20, 2, v24
	s_cmpk_gt_i32 s30, 0x57f
	v_ashrrev_i32_e32 v18, 4, v24
	v_and_b32_e32 v19, 28, v20
	v_mov_b32_e32 v14, v15
	v_mov_b32_e32 v13, v15
	v_mov_b32_e32 v12, v15
	v_mov_b32_e32 v11, v15
	v_mov_b32_e32 v10, v15
	v_mov_b32_e32 v9, v15
	v_mov_b32_e32 v8, v15
	v_mov_b32_e32 v7, v15
	v_mov_b32_e32 v6, v15
	v_mov_b32_e32 v5, v15
	v_mov_b32_e32 v4, v15
	v_mov_b32_e32 v3, v15
	v_mov_b32_e32 v2, v15
	v_mov_b32_e32 v1, v15
	v_mov_b32_e32 v0, v15
	v_readlane_b32 s41, v254, 39
	v_readlane_b32 s42, v254, 40
	v_readlane_b32 s43, v254, 41
	v_readlane_b32 s44, v254, 42
	v_readlane_b32 s45, v254, 43
	v_readlane_b32 s46, v254, 44
	v_readlane_b32 s47, v254, 45
	v_readlane_b32 s48, v254, 46
	v_readlane_b32 s49, v254, 47
	v_readlane_b32 s54, v254, 52
	v_readlane_b32 s55, v254, 53
	s_cbranch_scc1 .LBB0_871
	s_ashr_i32 s2, s30, 31
	s_lshr_b32 s2, s2, 28
	s_add_i32 s2, s30, s2
	s_and_b32 s3, s2, 0x3fffff0
	s_lshl_b32 s2, s2, 2
	s_andn2_b32 s2, s2, 63
	v_and_or_b32 v0, v20, 32, s2
	v_ashrrev_i32_e32 v0, 1, v0
	s_movk_i32 s2, 0xaf0
	v_or_b32_e32 v1, v0, v19
	v_add3_u32 v0, v19, v0, s2
	v_cmp_gt_u32_e32 vcc, 16, v19
	s_sub_i32 s3, s30, s3
	v_lshl_add_u32 v12, s3, 6, v18
	v_cndmask_b32_e32 v0, v0, v1, vcc
	v_ashrrev_i32_e32 v1, 31, v0
	v_lshl_add_u64 v[14:15], v[0:1], 2, s[22:23]
	v_mad_i64_i32 v[0:1], s[2:3], v12, s85, v[14:15]
	global_load_dwordx4 v[0:3], v[0:1], off
	s_cmp_lg_u64 s[24:25], 0
	v_ashrrev_i32_e32 v13, 31, v12
	s_cselect_b64 s[2:3], -1, 0
	s_cmp_eq_u64 s[24:25], 0
	v_lshl_add_u64 v[16:17], v[12:13], 2, s[24:25]
	s_cbranch_scc1 .LBB0_865
	global_load_dword v40, v[16:17], off

.LBB0_871:
	s_andn2_b64 vcc, exec, s[18:19]
	s_cbranch_vccnz .LBB0_887
	s_add_u32 s18, s12, 0x2900000
	v_and_b32_e32 v20, 60, v20
	v_lshlrev_b32_e32 v16, 4, v24
	s_addc_u32 s19, s13, 0
	v_and_b32_e32 v16, 48, v16
	v_mul_lo_u32 v17, v18, s58
	v_lshlrev_b32_e32 v23, 2, v20
	s_cmp_lg_u64 s[24:25], 0
	v_ashrrev_i32_e32 v22, 2, v24
	v_add3_u32 v23, s60, v17, v23
	v_mul_u32_u24_e32 v17, 0x104, v16
	v_and_b32_e32 v24, -4, v24
	v_cmp_gt_u32_e64 s[6:7], 16, v19
	v_add_u32_e32 v21, 0xaf0, v19
	s_cselect_b64 s[26:27], -1, 0
	v_add3_u32 v24, s60, v17, v24
	v_lshlrev_b32_e32 v144, 1, v16
	s_mov_b32 s98, 0
	s_branch .LBB0_874

.LBB0_874:
	s_cmpk_lt_i32 s30, 0x580
	s_cselect_b64 s[28:29], -1, 0
	s_cmpk_gt_i32 s30, 0x57f
	s_waitcnt lgkmcnt(0)
	s_barrier
	s_cbranch_scc1 .LBB0_876
	v_add_u32_e32 v16, 0x1040, v23
	s_cmp_eq_u32 s98, 0
	s_cbranch_scc1 .Lcvw22_f
	s_waitcnt vmcnt(2)
	s_branch .Lcvw22_d

.LBB0_876:
	s_add_i32 s2, s0, s30
	s_cmpk_gt_i32 s2, 0x57f
	s_cbranch_scc1 .LBB0_885
	s_ashr_i32 s3, s2, 31
	s_lshr_b32 s3, s3, 28
	s_add_i32 s3, s2, s3
	s_and_b32 s8, s3, 0x3fffff0
	s_lshl_b32 s3, s3, 2
	s_andn2_b32 s3, s3, 63
	s_waitcnt vmcnt(2)
	v_or_b32_e32 v0, s3, v20
	v_ashrrev_i32_e32 v0, 1, v0
	v_and_b32_e32 v0, -16, v0
	v_or_b32_e32 v1, v0, v19
	v_add_u32_e32 v0, v21, v0
	v_cndmask_b32_e64 v0, v0, v1, s[6:7]
	s_sub_i32 s8, s2, s8
	v_ashrrev_i32_e32 v1, 31, v0
	v_lshl_add_u32 v12, s8, 6, v18
	v_lshl_add_u64 v[14:15], v[0:1], 2, s[22:23]
	v_mad_i64_i32 v[0:1], s[8:9], v12, s85, v[14:15]
	global_load_dwordx4 v[0:3], v[0:1], off
	v_ashrrev_i32_e32 v13, 31, v12
	v_cndmask_b32_e64 v4, 0, 1, s[26:27]
	v_cmp_ne_u32_e64 s[8:9], 1, v4
	s_andn2_b64 vcc, exec, s[26:27]
	v_lshl_add_u64 v[16:17], v[12:13], 2, s[24:25]
	s_cbranch_vccnz .LBB0_879
	global_load_dword v40, v[16:17], off
.LBB0_879:
	v_add_u32_e32 v4, 16, v12
	v_mad_i64_i32 v[4:5], s[56:57], v4, s85, v[14:15]
	global_load_dwordx4 v[4:7], v[4:5], off
	s_and_b64 vcc, exec, s[8:9]
	s_cbranch_vccnz .LBB0_881
	global_load_dword v42, v[16:17], off offset:64
.LBB0_881:
	v_add_u32_e32 v8, 32, v12
	v_mad_i64_i32 v[8:9], s[56:57], v8, s85, v[14:15]
	global_load_dwordx4 v[8:11], v[8:9], off
	s_and_b64 vcc, exec, s[8:9]
	s_cbranch_vccnz .LBB0_883
	global_load_dword v44, v[16:17], off offset:128
.LBB0_883:
	v_add_u32_e32 v12, 48, v12
	v_mad_i64_i32 v[12:13], s[56:57], v12, s85, v[14:15]
	global_load_dwordx4 v[12:15], v[12:13], off
	s_and_b64 vcc, exec, s[8:9]
	s_cbranch_vccnz .LBB0_885
	global_load_dword v46, v[16:17], off offset:192
.LBB0_885:
	s_andn2_b64 vcc, exec, s[28:29]
	s_waitcnt lgkmcnt(0)
	s_barrier
	s_cbranch_vccnz .LBB0_873
	ds_read2_b32 v[16:17], v24 offset1:65
	s_waitcnt lgkmcnt(0)
	v_cvt_pk_bf16_f32 v26, v16, v17
	ds_read2_b32 v[16:17], v24 offset0:130 offset1:195
	v_add_u32_e32 v25, 0x400, v24
	s_waitcnt lgkmcnt(0)
	v_cvt_pk_bf16_f32 v27, v16, v17
	ds_read2_b32 v[16:17], v25 offset0:4 offset1:69
	s_ashr_i32 s3, s30, 31
	s_waitcnt lgkmcnt(0)
	v_cvt_pk_bf16_f32 v28, v16, v17
	ds_read2_b32 v[16:17], v25 offset0:134 offset1:199
	v_add_u32_e32 v25, 0x800, v24
	s_lshr_b32 s3, s3, 28
	s_waitcnt lgkmcnt(0)
	v_cvt_pk_bf16_f32 v29, v16, v17
	ds_read2_b32 v[16:17], v25 offset0:8 offset1:73
	s_add_i32 s3, s30, s3
	s_waitcnt lgkmcnt(0)
	v_cvt_pk_bf16_f32 v30, v16, v17
	ds_read2_b32 v[16:17], v25 offset0:138 offset1:203
	v_add_u32_e32 v25, 0xc00, v24
	s_and_b32 s8, s3, 0x3fffff0
	s_waitcnt lgkmcnt(0)
	v_cvt_pk_bf16_f32 v31, v16, v17
	ds_read2_b32 v[16:17], v25 offset0:12 offset1:77
	s_lshl_b32 s3, s3, 2
	s_waitcnt lgkmcnt(0)
	v_cvt_pk_bf16_f32 v32, v16, v17
	ds_read2_b32 v[16:17], v25 offset0:142 offset1:207
	s_andn2_b32 s3, s3, 63
	s_waitcnt lgkmcnt(0)
	v_cvt_pk_bf16_f32 v33, v16, v17
	v_add_u32_e32 v16, s3, v22
	s_sub_i32 s8, s30, s8
	v_ashrrev_i32_e32 v17, 31, v16
	v_lshlrev_b64 v[16:17], 11, v[16:17]
	s_lshl_b32 s8, s8, 6
	v_lshl_add_u64 v[16:17], s[18:19], 0, v[16:17]
	s_ashr_i32 s9, s8, 31
	v_lshl_add_u64 v[16:17], s[8:9], 1, v[16:17]
	v_lshl_add_u64 v[16:17], v[16:17], 0, v[144:145]
	global_store_dwordx4 v[16:17], v[26:29], off
	global_store_dwordx4 v[16:17], v[30:33], off offset:16
	s_branch .LBB0_873
.LBB0_887:
	s_mul_hi_u32 s2, s36, 0x1a00
	s_mul_i32 s2, s2, s34
	s_sub_i32 s2, 0x1a00, s2
	s_sub_i32 s3, s2, s34
	s_cmp_ge_u32 s2, s34
	s_cselect_b32 s2, s3, s2
	s_sub_i32 s3, s2, s34
	s_cmp_ge_u32 s2, s34
	s_cselect_b32 s2, s3, s2
	s_sub_i32 s2, s35, s2
	s_ashr_i32 s3, s2, 31
	s_abs_i32 s2, s2
	s_mul_hi_u32 s8, s2, s36
	s_mul_i32 s8, s8, s34
	s_sub_i32 s2, s2, s8
	s_sub_i32 s8, s2, s34
	s_cmp_ge_u32 s2, s34
	s_cselect_b32 s2, s8, s2
	s_sub_i32 s8, s2, s34
	v_readlane_b32 s40, v254, 38
	s_cmp_ge_u32 s2, s34
	v_readlane_b32 s54, v254, 52
	v_readlane_b32 s55, v254, 53
	s_cselect_b32 s2, s8, s2
	s_mov_b64 s[6:7], s[54:55]
	v_mov_b32_e32 v20, v191
	s_xor_b32 s2, s2, s3
	s_sub_i32 s2, s2, s3
	s_waitcnt vmcnt(0) lgkmcnt(0)
	v_mov_b32_e32 v0, 0
	v_lshlrev_b32_e32 v1, 2, v20
	s_cmpk_gt_i32 s2, 0x2bf
	v_ashrrev_i32_e32 v16, 4, v20
	v_and_b32_e32 v17, 60, v1
	v_mov_b32_e32 v1, v0
	v_mov_b32_e32 v2, v0
	v_mov_b32_e32 v3, v0
	v_mov_b32_e32 v4, v0
	v_mov_b32_e32 v5, v0
	v_mov_b32_e32 v6, v0
	v_mov_b32_e32 v7, v0
	v_mov_b32_e32 v8, v0
	v_mov_b32_e32 v9, v0
	v_mov_b32_e32 v10, v0
	v_mov_b32_e32 v11, v0
	v_mov_b32_e32 v12, v0
	v_mov_b32_e32 v13, v0
	v_mov_b32_e32 v14, v0
	v_mov_b32_e32 v15, v0
	v_readlane_b32 s41, v254, 39
	v_readlane_b32 s42, v254, 40
	v_readlane_b32 s43, v254, 41
	v_readlane_b32 s44, v254, 42
	v_readlane_b32 s45, v254, 43
	v_readlane_b32 s46, v254, 44
	v_readlane_b32 s47, v254, 45
	v_readlane_b32 s48, v254, 46
	v_readlane_b32 s49, v254, 47
	v_readlane_b32 s50, v254, 48
	v_readlane_b32 s51, v254, 49
	v_readlane_b32 s52, v254, 50
	v_readlane_b32 s53, v254, 51
	s_cbranch_scc1 .LBB0_889
	s_mul_hi_i32 s3, s2, 0x2e8ba2e9
	s_lshr_b32 s8, s3, 31
	s_ashr_i32 s3, s3, 3
	s_add_i32 s3, s3, s8
	s_mul_i32 s8, s3, 44
	s_sub_i32 s8, s2, s8
	v_lshl_or_b32 v0, s3, 6, v17
	v_lshl_add_u32 v2, s8, 6, v16
	v_ashrrev_i32_e32 v1, 31, v0
	v_ashrrev_i32_e32 v3, 31, v2
	v_lshl_add_u64 v[0:1], v[0:1], 2, s[6:7]
	v_lshlrev_b64 v[2:3], 12, v[2:3]
	v_lshl_add_u64 v[8:9], v[0:1], 0, v[2:3]
	v_add_co_u32_e32 v4, vcc, s81, v8
	s_nop 1
	v_addc_co_u32_e32 v5, vcc, 0, v9, vcc
	v_add_co_u32_e32 v10, vcc, s78, v8
	global_load_dwordx4 v[0:3], v[8:9], off
	s_nop 0
	global_load_dwordx4 v[4:7], v[4:5], off
	v_addc_co_u32_e32 v11, vcc, 0, v9, vcc
	v_add_co_u32_e32 v12, vcc, s59, v8
	s_nop 1
	v_addc_co_u32_e32 v13, vcc, 0, v9, vcc
	global_load_dwordx4 v[8:11], v[10:11], off
	s_nop 0
	global_load_dwordx4 v[12:15], v[12:13], off
.LBB0_889:
	s_andn2_b64 vcc, exec, s[20:21]
	s_cbranch_vccnz .LBB0_898
	v_lshlrev_b32_e32 v19, 4, v20
	v_and_b32_e32 v22, 48, v19
	v_mul_lo_u32 v19, v16, s58
	v_lshlrev_b32_e32 v21, 2, v17
	s_add_u32 s8, s12, 0x3400000
	v_ashrrev_i32_e32 v18, 2, v20
	v_add3_u32 v19, s60, v19, v21
	v_mul_u32_u24_e32 v21, 0x104, v22
	v_and_b32_e32 v20, -4, v20
	s_addc_u32 s9, s13, 0
	v_add3_u32 v20, s60, v21, v20
	v_lshlrev_b32_e32 v144, 1, v22
	s_mov_b32 s98, 0
	s_branch .LBB0_892

.LBB0_892:
	s_cmpk_lt_i32 s2, 0x2c0
	s_cselect_b64 s[18:19], -1, 0
	s_cmpk_gt_i32 s2, 0x2bf
	s_waitcnt lgkmcnt(0)
	s_barrier
	s_cbranch_scc1 .LBB0_894
	v_add_u32_e32 v21, 0x1040, v19
	s_cmp_eq_u32 s98, 0
	s_cbranch_scc1 .Lcvw23_f
	s_waitcnt vmcnt(2)
	s_branch .Lcvw23_d

.LBB0_894:
	s_add_i32 s3, s0, s2
	s_cmpk_gt_i32 s3, 0x2bf
	s_cbranch_scc1 .LBB0_896
	s_mul_hi_i32 s20, s3, 0x2e8ba2e9
	s_lshr_b32 s21, s20, 31
	s_ashr_i32 s20, s20, 3
	s_add_i32 s20, s20, s21
	s_mul_i32 s21, s20, 44
	s_sub_i32 s21, s3, s21
	s_waitcnt vmcnt(2)
	v_lshl_or_b32 v0, s20, 6, v17
	v_lshl_add_u32 v2, s21, 6, v16
	v_ashrrev_i32_e32 v1, 31, v0
	v_ashrrev_i32_e32 v3, 31, v2
	v_lshl_add_u64 v[0:1], v[0:1], 2, s[6:7]
	v_lshlrev_b64 v[2:3], 12, v[2:3]
	v_lshl_add_u64 v[8:9], v[0:1], 0, v[2:3]
	v_add_co_u32_e32 v4, vcc, s81, v8
	s_nop 1
	v_addc_co_u32_e32 v5, vcc, 0, v9, vcc
	v_add_co_u32_e32 v10, vcc, s78, v8
	global_load_dwordx4 v[0:3], v[8:9], off
	s_nop 0
	global_load_dwordx4 v[4:7], v[4:5], off
	v_addc_co_u32_e32 v11, vcc, 0, v9, vcc
	v_add_co_u32_e32 v12, vcc, s59, v8
	s_nop 1
	v_addc_co_u32_e32 v13, vcc, 0, v9, vcc
	global_load_dwordx4 v[8:11], v[10:11], off
	s_nop 0
	global_load_dwordx4 v[12:15], v[12:13], off
.LBB0_896:
	s_andn2_b64 vcc, exec, s[18:19]
	s_waitcnt lgkmcnt(0)
	s_barrier
	s_cbranch_vccnz .LBB0_891
	ds_read2_b32 v[22:23], v20 offset1:65
	ds_read2_b32 v[24:25], v20 offset0:130 offset1:195
	v_add_u32_e32 v21, 0x400, v20
	s_mul_hi_i32 s18, s2, 0x2e8ba2e9
	s_waitcnt lgkmcnt(0)
	v_cvt_pk_bf16_f32 v22, v22, v23
	v_cvt_pk_bf16_f32 v23, v24, v25
	ds_read2_b32 v[24:25], v21 offset0:4 offset1:69
	ds_read2_b32 v[26:27], v21 offset0:134 offset1:199
	v_add_u32_e32 v21, 0x800, v20
	s_lshr_b32 s19, s18, 31
	s_ashr_i32 s18, s18, 3
	s_waitcnt lgkmcnt(0)
	v_cvt_pk_bf16_f32 v24, v24, v25
	v_cvt_pk_bf16_f32 v25, v26, v27
	ds_read2_b32 v[26:27], v21 offset0:8 offset1:73
	ds_read2_b32 v[28:29], v21 offset0:138 offset1:203
	v_add_u32_e32 v21, 0xc00, v20
	s_add_i32 s18, s18, s19
	s_waitcnt lgkmcnt(0)
	v_cvt_pk_bf16_f32 v26, v26, v27
	v_cvt_pk_bf16_f32 v27, v28, v29
	ds_read2_b32 v[28:29], v21 offset0:12 offset1:77
	ds_read2_b32 v[30:31], v21 offset0:142 offset1:207
	s_mul_i32 s19, s18, 44
	s_waitcnt lgkmcnt(0)
	v_cvt_pk_bf16_f32 v28, v28, v29
	v_cvt_pk_bf16_f32 v29, v30, v31
	v_lshl_add_u32 v21, s18, 6, v18
	v_mov_b64_e32 v[30:31], s[8:9]
	s_sub_i32 s2, s2, s19
	v_mad_i64_i32 v[30:31], s[18:19], v21, s33, v[30:31]
	s_lshl_b32 s18, s2, 6
	s_ashr_i32 s19, s18, 31
	v_lshl_add_u64 v[30:31], s[18:19], 1, v[30:31]
	v_lshl_add_u64 v[30:31], v[30:31], 0, v[144:145]
	global_store_dwordx4 v[30:31], v[22:25], off
	global_store_dwordx4 v[30:31], v[26:29], off offset:16
	s_branch .LBB0_891
